# GEMM K-loops: per-segment s_setprio toggling removed, one static priority raise for the wave half that trails by a barrier (set at each GEMM instance's prologue)
# speedup vs baseline: 1.0010x; 1.0010x over previous
.LBB0_257:
	v_readlane_b32 s4, v254, 10
	s_cmp_lt_i32 s4, 3
	s_cselect_b64 s[0:1], -1, 0
	s_and_b64 s[72:73], s[0:1], s[2:3]
	s_mov_b32 s0, s62
	v_readlane_b32 s5, v254, 11
	v_readlane_b32 s6, v254, 12
	v_readlane_b32 s7, v254, 13
	v_writelane_b32 v254, s0, 61
	s_andn2_b64 vcc, exec, s[72:73]
	s_nop 0
	v_writelane_b32 v254, s1, 62
	s_cbranch_vccnz .LBB0_1015
	s_add_u32 s70, s76, 0x600000
	s_addc_u32 s71, s77, 0
	s_add_u32 s26, s76, 0x26200000
	v_bfe_u32 v173, v0, 4, 2
	v_lshlrev_b32_e32 v2, 6, v0
	v_lshlrev_b32_e32 v3, 2, v0
	s_addc_u32 s27, s77, 0
	v_lshlrev_b32_e32 v175, 4, v173
	v_and_b32_e32 v2, 0x3c0, v2
	v_and_b32_e32 v3, 32, v3
	s_ashr_i32 s61, s97, 3
	v_readfirstlane_b32 s0, v0
	v_and_b32_e32 v172, 15, v0
	s_cmpk_gt_i32 s97, 0xff
	v_bitop3_b32 v174, v175, v3, v2 bitop3:0x36
	s_cbranch_scc1 .LBB0_352
	v_lshrrev_b32_e32 v2, 5, v0
	v_lshrrev_b32_e32 v4, 1, v0
	s_lshl_b32 s3, s97, 5
	v_and_b32_e32 v2, 4, v2
	v_bfe_u32 v3, v0, 2, 2
	v_and_b32_e32 v4, 24, v4
	s_and_b32 s3, s3, 0xe0
	v_or3_b32 v2, v2, v3, v4
	v_lshlrev_b32_e32 v3, 4, v0
	s_add_i32 s3, s3, s61
	v_or_b32_e32 v6, 0x2000, v3
	s_ashr_i32 s4, s3, 3
	v_lshrrev_b32_e32 v4, 7, v6
	s_movk_i32 s3, 0x60
	s_lshr_b32 s2, s0, 6
	s_and_b32 s25, s61, 7
	v_and_or_b32 v5, v4, s3, v2
	v_bfe_u32 v9, v0, 2, 4
	s_movk_i32 s3, 0x70
	s_ashr_i32 s5, s4, 31
	s_lshr_b32 s1, s0, 8
	s_lshl_b32 s24, s2, 10
	v_and_b32_e32 v7, 32, v0
	v_and_or_b32 v4, v4, s3, v9
	s_lshl_b64 s[8:9], s[4:5], 21
	s_lshl_b32 s3, s25, 21
	v_bitop3_b32 v7, v3, v7, 48 bitop3:0x6c
	v_and_b32_e32 v8, 64, v0
	s_add_u32 s3, s70, s3
	v_or_b32_e32 v3, v7, v8
	s_addc_u32 s14, s71, 0
	v_lshl_or_b32 v132, v4, 13, v3
	v_lshrrev_b32_e32 v4, 3, v0
	s_add_u32 s6, s3, 0x3000000
	v_and_or_b32 v2, v4, 32, v2
	s_addc_u32 s7, s14, 0
	s_add_i32 s5, s24, 0
	v_lshl_or_b32 v134, v2, 13, v3
	s_add_i32 m0, s5, 0x10000
	v_lshl_or_b32 v130, v5, 13, v3
	global_load_lds_dwordx4 v134, s[6:7]
	s_add_i32 m0, s5, 0x12000
	s_add_u32 s10, s3, 0x3100000
	global_load_lds_dwordx4 v130, s[6:7]
	s_addc_u32 s11, s14, 0
	s_add_i32 m0, s5, 0x14000
	v_and_or_b32 v2, v4, 48, v9
	global_load_lds_dwordx4 v134, s[10:11]
	s_add_i32 m0, s5, 0x16000
	s_add_u32 s8, s22, s8
	s_addc_u32 s9, s23, s9
	s_add_i32 s34, s5, 0x2000
	v_lshl_or_b32 v136, v2, 13, v3
	global_load_lds_dwordx4 v130, s[10:11]
	s_mov_b32 m0, s5
	s_add_u32 s10, s8, 0x100000
	global_load_lds_dwordx4 v136, s[8:9]
	s_mov_b32 m0, s34
	s_addc_u32 s11, s9, 0
	s_add_i32 s35, s5, 0x4000
	global_load_lds_dwordx4 v132, s[8:9]
	s_mov_b32 m0, s35
	s_add_i32 s37, s5, 0x6000
	global_load_lds_dwordx4 v136, s[10:11]
	s_mov_b32 m0, s37
	v_mov_b32_e32 v135, 0
	global_load_lds_dwordx4 v132, s[10:11]
	v_mov_b32_e32 v137, v135
	v_mov_b32_e32 v133, v135
	s_cmp_eq_u32 s1, 1
	s_mov_b32 s38, 0
	v_mov_b32_e32 v131, v135
	v_lshl_add_u64 v[2:3], s[8:9], 0, v[136:137]
	s_cselect_b64 s[10:11], -1, 0
	s_cmp_lg_u32 s1, 1
	v_lshl_add_u64 v[4:5], s[8:9], 0, v[132:133]
	s_cbranch_scc1 .LBB0_261
	s_setprio 1
	s_barrier

.LBB0_265:
	ds_read_b128 v[142:145], v151
	ds_read_b128 v[146:149], v151 offset:1024
	ds_read_b128 v[154:157], v151 offset:2048
	ds_read_b128 v[158:161], v151 offset:3072
	ds_read_b128 v[162:165], v152
	ds_read_b128 v[166:169], v152 offset:1024
	ds_read_b128 v[176:179], v152 offset:2048
	ds_read_b128 v[180:183], v152 offset:3072
	s_add_u32 s28, s0, 0xfff00080
	s_addc_u32 s29, s1, -1
	s_cmp_eq_u32 s52, 60
	s_cselect_b32 s31, s33, s29
	s_cselect_b32 s30, s47, s28
	s_cselect_b32 s29, s48, s51
	s_cselect_b32 s28, s49, s50
	v_lshl_add_u64 v[170:171], s[0:1], 0, v[138:139]
	s_add_i32 m0, s5, 0xc000
	ds_read_b128 v[184:187], v153
	ds_read_b128 v[188:191], v153 offset:1024
	ds_read_b128 v[192:195], v153 offset:2048
	ds_read_b128 v[196:199], v153 offset:3072
	ds_read_b128 v[200:203], v153 offset:4096
	ds_read_b128 v[204:207], v153 offset:5120
	ds_read_b128 v[208:211], v153 offset:6144
	ds_read_b128 v[212:215], v153 offset:7168
	global_load_lds_dwordx4 v[170:171], off
	v_lshl_add_u64 v[170:171], s[0:1], 0, v[140:141]
	s_add_i32 m0, s5, 0xe000
	s_nop 0
	global_load_lds_dwordx4 v[170:171], off
	s_waitcnt vmcnt(8)
	s_waitcnt lgkmcnt(0)
	s_barrier
	s_waitcnt lgkmcnt(0)
	v_mfma_f32_16x16x32_bf16 v[126:129], v[142:145], v[184:187], v[126:129]
	v_mfma_f32_16x16x32_bf16 v[122:125], v[154:157], v[184:187], v[122:125]
	v_mfma_f32_16x16x32_bf16 v[110:113], v[142:145], v[192:195], v[110:113]
	v_mfma_f32_16x16x32_bf16 v[106:109], v[154:157], v[192:195], v[106:109]
	v_mfma_f32_16x16x32_bf16 v[94:97], v[142:145], v[200:203], v[94:97]
	v_mfma_f32_16x16x32_bf16 v[90:93], v[154:157], v[200:203], v[90:93]
	v_mfma_f32_16x16x32_bf16 v[78:81], v[142:145], v[208:211], v[78:81]
	v_mfma_f32_16x16x32_bf16 v[74:77], v[154:157], v[208:211], v[74:77]
	v_mfma_f32_16x16x32_bf16 v[126:129], v[146:149], v[188:191], v[126:129]
	v_mfma_f32_16x16x32_bf16 v[122:125], v[158:161], v[188:191], v[122:125]
	v_mfma_f32_16x16x32_bf16 v[110:113], v[146:149], v[196:199], v[110:113]
	v_mfma_f32_16x16x32_bf16 v[106:109], v[158:161], v[196:199], v[106:109]
	v_mfma_f32_16x16x32_bf16 v[94:97], v[146:149], v[204:207], v[94:97]
	v_mfma_f32_16x16x32_bf16 v[90:93], v[158:161], v[204:207], v[90:93]
	v_mfma_f32_16x16x32_bf16 v[78:81], v[146:149], v[212:215], v[78:81]
	v_mfma_f32_16x16x32_bf16 v[74:77], v[158:161], v[212:215], v[74:77]
	v_mfma_f32_16x16x32_bf16 v[118:121], v[162:165], v[184:187], v[118:121]
	v_mfma_f32_16x16x32_bf16 v[114:117], v[176:179], v[184:187], v[114:117]
	v_mfma_f32_16x16x32_bf16 v[102:105], v[162:165], v[192:195], v[102:105]
	v_mfma_f32_16x16x32_bf16 v[98:101], v[176:179], v[192:195], v[98:101]
	v_mfma_f32_16x16x32_bf16 v[86:89], v[162:165], v[200:203], v[86:89]
	v_mfma_f32_16x16x32_bf16 v[82:85], v[176:179], v[200:203], v[82:85]
	v_mfma_f32_16x16x32_bf16 v[70:73], v[162:165], v[208:211], v[70:73]
	v_mfma_f32_16x16x32_bf16 v[66:69], v[176:179], v[208:211], v[66:69]
	v_mfma_f32_16x16x32_bf16 v[118:121], v[166:169], v[188:191], v[118:121]
	v_mfma_f32_16x16x32_bf16 v[114:117], v[180:183], v[188:191], v[114:117]
	v_mfma_f32_16x16x32_bf16 v[102:105], v[166:169], v[196:199], v[102:105]
	v_mfma_f32_16x16x32_bf16 v[98:101], v[180:183], v[196:199], v[98:101]
	v_mfma_f32_16x16x32_bf16 v[86:89], v[166:169], v[204:207], v[86:89]
	v_mfma_f32_16x16x32_bf16 v[82:85], v[180:183], v[204:207], v[82:85]
	v_mfma_f32_16x16x32_bf16 v[70:73], v[166:169], v[212:215], v[70:73]
	v_mfma_f32_16x16x32_bf16 v[66:69], v[180:183], v[212:215], v[66:69]
	s_barrier
	s_add_i32 s53, s43, s24
	v_lshl_add_u64 v[170:171], s[28:29], 0, v[134:135]
	s_mov_b32 m0, s53
	ds_read_b128 v[184:187], v153 offset:16384
	ds_read_b128 v[188:191], v153 offset:17408
	ds_read_b128 v[192:195], v153 offset:18432
	ds_read_b128 v[196:199], v153 offset:19456
	ds_read_b128 v[200:203], v153 offset:20480
	ds_read_b128 v[204:207], v153 offset:21504
	ds_read_b128 v[208:211], v153 offset:22528
	ds_read_b128 v[212:215], v153 offset:23552
	global_load_lds_dwordx4 v[170:171], off
	s_add_i32 m0, s53, 0x2000
	s_add_u32 s54, s28, 0x100000
	v_lshl_add_u64 v[216:217], s[28:29], 0, v[130:131]
	s_addc_u32 s55, s29, 0
	s_add_i32 s53, s44, s24
	global_load_lds_dwordx4 v[216:217], off
	v_lshl_add_u64 v[218:219], s[54:55], 0, v[134:135]
	s_mov_b32 m0, s53
	v_lshl_add_u64 v[220:221], s[30:31], 0, v[132:133]
	global_load_lds_dwordx4 v[218:219], off
	v_lshl_add_u64 v[218:219], s[54:55], 0, v[130:131]
	s_add_i32 m0, s53, 0x2000
	s_nop 0
	global_load_lds_dwordx4 v[218:219], off
	v_lshl_add_u64 v[218:219], s[30:31], 0, v[136:137]
	s_mov_b32 m0, s5
	s_nop 0
	global_load_lds_dwordx4 v[218:219], off
	s_mov_b32 m0, s34
	s_nop 0
	global_load_lds_dwordx4 v[220:221], off
	s_waitcnt vmcnt(8)
	s_waitcnt lgkmcnt(0)
	s_barrier
	s_waitcnt lgkmcnt(0)
	v_mfma_f32_16x16x32_bf16 v[62:65], v[142:145], v[184:187], v[62:65]
	v_mfma_f32_16x16x32_bf16 v[58:61], v[154:157], v[184:187], v[58:61]
	v_mfma_f32_16x16x32_bf16 v[46:49], v[142:145], v[192:195], v[46:49]
	v_mfma_f32_16x16x32_bf16 v[42:45], v[154:157], v[192:195], v[42:45]
	v_mfma_f32_16x16x32_bf16 v[30:33], v[142:145], v[200:203], v[30:33]
	v_mfma_f32_16x16x32_bf16 v[26:29], v[154:157], v[200:203], v[26:29]
	v_mfma_f32_16x16x32_bf16 v[14:17], v[142:145], v[208:211], v[14:17]
	v_mfma_f32_16x16x32_bf16 v[10:13], v[154:157], v[208:211], v[10:13]
	v_mfma_f32_16x16x32_bf16 v[62:65], v[146:149], v[188:191], v[62:65]
	v_mfma_f32_16x16x32_bf16 v[58:61], v[158:161], v[188:191], v[58:61]
	v_mfma_f32_16x16x32_bf16 v[46:49], v[146:149], v[196:199], v[46:49]
	v_mfma_f32_16x16x32_bf16 v[42:45], v[158:161], v[196:199], v[42:45]
	v_mfma_f32_16x16x32_bf16 v[30:33], v[146:149], v[204:207], v[30:33]
	v_mfma_f32_16x16x32_bf16 v[26:29], v[158:161], v[204:207], v[26:29]
	v_mfma_f32_16x16x32_bf16 v[14:17], v[146:149], v[212:215], v[14:17]
	v_mfma_f32_16x16x32_bf16 v[10:13], v[158:161], v[212:215], v[10:13]
	v_mfma_f32_16x16x32_bf16 v[54:57], v[162:165], v[184:187], v[54:57]
	v_mfma_f32_16x16x32_bf16 v[50:53], v[176:179], v[184:187], v[50:53]
	v_mfma_f32_16x16x32_bf16 v[38:41], v[162:165], v[192:195], v[38:41]
	v_mfma_f32_16x16x32_bf16 v[34:37], v[176:179], v[192:195], v[34:37]
	v_mfma_f32_16x16x32_bf16 v[22:25], v[162:165], v[200:203], v[22:25]
	v_mfma_f32_16x16x32_bf16 v[18:21], v[176:179], v[200:203], v[18:21]
	v_mfma_f32_16x16x32_bf16 v[6:9], v[162:165], v[208:211], v[6:9]
	v_mfma_f32_16x16x32_bf16 v[2:5], v[176:179], v[208:211], v[2:5]
	v_mfma_f32_16x16x32_bf16 v[54:57], v[166:169], v[188:191], v[54:57]
	v_mfma_f32_16x16x32_bf16 v[50:53], v[180:183], v[188:191], v[50:53]
	v_mfma_f32_16x16x32_bf16 v[38:41], v[166:169], v[196:199], v[38:41]
	v_mfma_f32_16x16x32_bf16 v[34:37], v[180:183], v[196:199], v[34:37]
	v_mfma_f32_16x16x32_bf16 v[22:25], v[166:169], v[204:207], v[22:25]
	v_mfma_f32_16x16x32_bf16 v[18:21], v[180:183], v[204:207], v[18:21]
	v_mfma_f32_16x16x32_bf16 v[6:9], v[166:169], v[212:215], v[6:9]
	v_mfma_f32_16x16x32_bf16 v[2:5], v[180:183], v[212:215], v[2:5]
	s_barrier
	s_add_i32 s53, 0, 0x18000
	s_add_i32 s54, 0, 0x1c000
	v_add_u32_e32 v158, s53, v150
	v_add_u32_e32 v180, s54, v150
	ds_read_b128 v[142:145], v158
	ds_read_b128 v[146:149], v158 offset:1024
	ds_read_b128 v[154:157], v158 offset:2048
	ds_read_b128 v[158:161], v158 offset:3072
	ds_read_b128 v[162:165], v180
	ds_read_b128 v[166:169], v180 offset:1024
	ds_read_b128 v[176:179], v180 offset:2048
	ds_read_b128 v[180:183], v180 offset:3072
	s_add_u32 s30, s30, 0x100000
	s_addc_u32 s31, s31, 0
	s_mov_b32 m0, s35
	v_lshl_add_u64 v[222:223], s[30:31], 0, v[136:137]
	ds_read_b128 v[184:187], v153 offset:32768
	ds_read_b128 v[188:191], v153 offset:33792
	ds_read_b128 v[192:195], v153 offset:34816
	ds_read_b128 v[196:199], v153 offset:35840
	ds_read_b128 v[200:203], v153 offset:36864
	ds_read_b128 v[204:207], v153 offset:37888
	ds_read_b128 v[208:211], v153 offset:38912
	ds_read_b128 v[212:215], v153 offset:39936
	global_load_lds_dwordx4 v[222:223], off
	v_lshl_add_u64 v[222:223], s[30:31], 0, v[132:133]
	s_mov_b32 m0, s37
	s_nop 0
	global_load_lds_dwordx4 v[222:223], off
	s_waitcnt vmcnt(8)
	s_waitcnt lgkmcnt(0)
	s_barrier
	s_waitcnt lgkmcnt(0)
	v_mfma_f32_16x16x32_bf16 v[126:129], v[142:145], v[184:187], v[126:129]
	v_mfma_f32_16x16x32_bf16 v[122:125], v[154:157], v[184:187], v[122:125]
	v_mfma_f32_16x16x32_bf16 v[110:113], v[142:145], v[192:195], v[110:113]
	v_mfma_f32_16x16x32_bf16 v[106:109], v[154:157], v[192:195], v[106:109]
	v_mfma_f32_16x16x32_bf16 v[94:97], v[142:145], v[200:203], v[94:97]
	v_mfma_f32_16x16x32_bf16 v[90:93], v[154:157], v[200:203], v[90:93]
	v_mfma_f32_16x16x32_bf16 v[78:81], v[142:145], v[208:211], v[78:81]
	v_mfma_f32_16x16x32_bf16 v[74:77], v[154:157], v[208:211], v[74:77]
	v_mfma_f32_16x16x32_bf16 v[126:129], v[146:149], v[188:191], v[126:129]
	v_mfma_f32_16x16x32_bf16 v[122:125], v[158:161], v[188:191], v[122:125]
	v_mfma_f32_16x16x32_bf16 v[110:113], v[146:149], v[196:199], v[110:113]
	v_mfma_f32_16x16x32_bf16 v[106:109], v[158:161], v[196:199], v[106:109]
	v_mfma_f32_16x16x32_bf16 v[94:97], v[146:149], v[204:207], v[94:97]
	v_mfma_f32_16x16x32_bf16 v[90:93], v[158:161], v[204:207], v[90:93]
	v_mfma_f32_16x16x32_bf16 v[78:81], v[146:149], v[212:215], v[78:81]
	v_mfma_f32_16x16x32_bf16 v[74:77], v[158:161], v[212:215], v[74:77]
	v_mfma_f32_16x16x32_bf16 v[118:121], v[162:165], v[184:187], v[118:121]
	v_mfma_f32_16x16x32_bf16 v[114:117], v[176:179], v[184:187], v[114:117]
	v_mfma_f32_16x16x32_bf16 v[102:105], v[162:165], v[192:195], v[102:105]
	v_mfma_f32_16x16x32_bf16 v[98:101], v[176:179], v[192:195], v[98:101]
	v_mfma_f32_16x16x32_bf16 v[86:89], v[162:165], v[200:203], v[86:89]
	v_mfma_f32_16x16x32_bf16 v[82:85], v[176:179], v[200:203], v[82:85]
	v_mfma_f32_16x16x32_bf16 v[70:73], v[162:165], v[208:211], v[70:73]
	v_mfma_f32_16x16x32_bf16 v[66:69], v[176:179], v[208:211], v[66:69]
	v_mfma_f32_16x16x32_bf16 v[118:121], v[166:169], v[188:191], v[118:121]
	v_mfma_f32_16x16x32_bf16 v[114:117], v[180:183], v[188:191], v[114:117]
	v_mfma_f32_16x16x32_bf16 v[102:105], v[166:169], v[196:199], v[102:105]
	v_mfma_f32_16x16x32_bf16 v[98:101], v[180:183], v[196:199], v[98:101]
	v_mfma_f32_16x16x32_bf16 v[86:89], v[166:169], v[204:207], v[86:89]
	v_mfma_f32_16x16x32_bf16 v[82:85], v[180:183], v[204:207], v[82:85]
	v_mfma_f32_16x16x32_bf16 v[70:73], v[166:169], v[212:215], v[70:73]
	v_mfma_f32_16x16x32_bf16 v[66:69], v[180:183], v[212:215], v[66:69]
	s_barrier
	s_add_i32 s30, s53, s24
	v_lshl_add_u64 v[170:171], v[170:171], 0, s[12:13]
	s_mov_b32 m0, s30
	ds_read_b128 v[184:187], v153 offset:49152
	ds_read_b128 v[188:191], v153 offset:50176
	ds_read_b128 v[192:195], v153 offset:51200
	ds_read_b128 v[196:199], v153 offset:52224
	ds_read_b128 v[200:203], v153 offset:53248
	ds_read_b128 v[204:207], v153 offset:54272
	ds_read_b128 v[208:211], v153 offset:55296
	ds_read_b128 v[212:215], v153 offset:56320
	global_load_lds_dwordx4 v[170:171], off
	s_add_i32 m0, s30, 0x2000
	s_add_u32 s28, s28, 0x100080
	v_lshl_add_u64 v[170:171], v[216:217], 0, s[12:13]
	s_addc_u32 s29, s29, 0
	s_add_i32 s30, s54, s24
	global_load_lds_dwordx4 v[170:171], off
	v_lshl_add_u64 v[170:171], s[28:29], 0, v[134:135]
	s_mov_b32 m0, s30
	s_nop 0
	global_load_lds_dwordx4 v[170:171], off
	v_lshl_add_u64 v[170:171], s[28:29], 0, v[130:131]
	s_add_i32 m0, s30, 0x2000
	s_nop 0
	global_load_lds_dwordx4 v[170:171], off
	v_lshl_add_u64 v[170:171], v[218:219], 0, s[12:13]
	s_mov_b32 m0, s41
	s_nop 0
	global_load_lds_dwordx4 v[170:171], off
	v_lshl_add_u64 v[170:171], v[220:221], 0, s[12:13]
	s_mov_b32 m0, s42
	s_nop 0
	global_load_lds_dwordx4 v[170:171], off
	s_waitcnt vmcnt(8)
	s_waitcnt lgkmcnt(0)
	s_barrier
	s_waitcnt lgkmcnt(0)
	v_mfma_f32_16x16x32_bf16 v[62:65], v[142:145], v[184:187], v[62:65]
	v_mfma_f32_16x16x32_bf16 v[58:61], v[154:157], v[184:187], v[58:61]
	v_mfma_f32_16x16x32_bf16 v[46:49], v[142:145], v[192:195], v[46:49]
	v_mfma_f32_16x16x32_bf16 v[42:45], v[154:157], v[192:195], v[42:45]
	v_mfma_f32_16x16x32_bf16 v[30:33], v[142:145], v[200:203], v[30:33]
	v_mfma_f32_16x16x32_bf16 v[26:29], v[154:157], v[200:203], v[26:29]
	v_mfma_f32_16x16x32_bf16 v[14:17], v[142:145], v[208:211], v[14:17]
	v_mfma_f32_16x16x32_bf16 v[10:13], v[154:157], v[208:211], v[10:13]
	v_mfma_f32_16x16x32_bf16 v[62:65], v[146:149], v[188:191], v[62:65]
	v_mfma_f32_16x16x32_bf16 v[58:61], v[158:161], v[188:191], v[58:61]
	v_mfma_f32_16x16x32_bf16 v[46:49], v[146:149], v[196:199], v[46:49]
	v_mfma_f32_16x16x32_bf16 v[42:45], v[158:161], v[196:199], v[42:45]
	v_mfma_f32_16x16x32_bf16 v[30:33], v[146:149], v[204:207], v[30:33]
	v_mfma_f32_16x16x32_bf16 v[26:29], v[158:161], v[204:207], v[26:29]
	v_mfma_f32_16x16x32_bf16 v[14:17], v[146:149], v[212:215], v[14:17]
	v_mfma_f32_16x16x32_bf16 v[10:13], v[158:161], v[212:215], v[10:13]
	v_mfma_f32_16x16x32_bf16 v[54:57], v[162:165], v[184:187], v[54:57]
	v_mfma_f32_16x16x32_bf16 v[50:53], v[176:179], v[184:187], v[50:53]
	v_mfma_f32_16x16x32_bf16 v[38:41], v[162:165], v[192:195], v[38:41]
	v_mfma_f32_16x16x32_bf16 v[34:37], v[176:179], v[192:195], v[34:37]
	v_mfma_f32_16x16x32_bf16 v[22:25], v[162:165], v[200:203], v[22:25]
	v_mfma_f32_16x16x32_bf16 v[18:21], v[176:179], v[200:203], v[18:21]
	v_mfma_f32_16x16x32_bf16 v[6:9], v[162:165], v[208:211], v[6:9]
	v_mfma_f32_16x16x32_bf16 v[2:5], v[176:179], v[208:211], v[2:5]
	v_mfma_f32_16x16x32_bf16 v[54:57], v[166:169], v[188:191], v[54:57]
	v_mfma_f32_16x16x32_bf16 v[50:53], v[180:183], v[188:191], v[50:53]
	v_mfma_f32_16x16x32_bf16 v[38:41], v[166:169], v[196:199], v[38:41]
	v_mfma_f32_16x16x32_bf16 v[34:37], v[180:183], v[196:199], v[34:37]
	v_mfma_f32_16x16x32_bf16 v[22:25], v[166:169], v[204:207], v[22:25]
	v_mfma_f32_16x16x32_bf16 v[18:21], v[180:183], v[204:207], v[18:21]
	v_mfma_f32_16x16x32_bf16 v[6:9], v[166:169], v[212:215], v[6:9]
	v_mfma_f32_16x16x32_bf16 v[2:5], v[180:183], v[212:215], v[2:5]
	s_barrier
	s_add_i32 s52, s52, 2
	s_add_u32 s0, s0, 0x100
	s_addc_u32 s1, s1, 0
	s_add_u32 s50, s50, 0x100
	s_addc_u32 s51, s51, 0
	s_cmp_gt_u32 s52, 61
	s_cbranch_scc0 .LBB0_265
	s_and_b64 vcc, exec, s[14:15]
	s_cbranch_vccz .LBB0_268
	s_barrier

.Lstream_call:
	s_setprio 0
	s_cmp_eq_u32 s32, 0x100
	s_cbranch_scc1 .LBB0_361
	v_writelane_b32 v2, s0, 0
	v_writelane_b32 v2, s1, 1
	v_writelane_b32 v2, s2, 2
	v_writelane_b32 v2, s3, 3
	v_writelane_b32 v2, s4, 4
	v_writelane_b32 v2, s5, 5
	v_writelane_b32 v2, s6, 6
	v_writelane_b32 v2, s7, 7
	v_writelane_b32 v2, s8, 8
	v_writelane_b32 v2, s9, 9
	v_writelane_b32 v2, s10, 10
	v_writelane_b32 v2, s11, 11
	v_writelane_b32 v2, s12, 12
	v_writelane_b32 v2, s13, 13
	v_writelane_b32 v2, s14, 14
	v_writelane_b32 v2, s15, 15
	v_writelane_b32 v2, s16, 16
	v_writelane_b32 v2, s17, 17
	v_writelane_b32 v2, s18, 18
	v_writelane_b32 v2, s19, 19
	v_writelane_b32 v2, s20, 20
	v_writelane_b32 v2, s21, 21
	v_writelane_b32 v2, s22, 22
	v_writelane_b32 v2, s23, 23
	v_writelane_b32 v2, s24, 24
	v_writelane_b32 v2, s25, 25
	v_writelane_b32 v2, s26, 26
	v_writelane_b32 v2, s27, 27
	v_writelane_b32 v2, s28, 28
	v_writelane_b32 v2, s29, 29
	v_writelane_b32 v2, s30, 30
	v_writelane_b32 v2, s31, 31
	v_writelane_b32 v2, s32, 32
	v_writelane_b32 v2, s33, 33
	v_writelane_b32 v2, s34, 34
	v_writelane_b32 v2, s35, 35
	v_writelane_b32 v2, s36, 36
	v_writelane_b32 v2, s37, 37
	v_writelane_b32 v2, s38, 38
	v_writelane_b32 v2, s39, 39
	v_writelane_b32 v2, s40, 40
	v_writelane_b32 v2, s41, 41
	v_writelane_b32 v2, s42, 42
	v_writelane_b32 v2, s43, 43
	v_writelane_b32 v2, s44, 44
	v_writelane_b32 v2, s45, 45
	v_writelane_b32 v2, s46, 46
	v_writelane_b32 v2, s47, 47
	v_writelane_b32 v2, s48, 48
	v_writelane_b32 v2, s49, 49
	v_writelane_b32 v2, s50, 50
	v_writelane_b32 v2, s51, 51
	v_writelane_b32 v2, s52, 52
	v_writelane_b32 v2, s53, 53
	v_writelane_b32 v2, s54, 54
	v_writelane_b32 v2, s55, 55
	v_writelane_b32 v2, s56, 56
	v_writelane_b32 v2, s57, 57
	v_writelane_b32 v2, s58, 58
	v_writelane_b32 v2, s59, 59
	v_writelane_b32 v2, s60, 60
	v_writelane_b32 v2, s61, 61
	v_writelane_b32 v2, s62, 62
	v_writelane_b32 v2, s63, 63
	v_writelane_b32 v3, s64, 0
	v_writelane_b32 v3, s65, 1
	v_writelane_b32 v3, s66, 2
	v_writelane_b32 v3, s67, 3
	v_writelane_b32 v3, s68, 4
	v_writelane_b32 v3, s69, 5
	v_writelane_b32 v3, s70, 6
	v_writelane_b32 v3, s71, 7
	v_writelane_b32 v3, s72, 8
	v_writelane_b32 v3, s73, 9
	v_writelane_b32 v3, s74, 10
	v_writelane_b32 v3, s75, 11
	v_writelane_b32 v3, s76, 12
	v_writelane_b32 v3, s77, 13
	v_writelane_b32 v3, s78, 14
	v_writelane_b32 v3, s79, 15
	v_writelane_b32 v3, s80, 16
	v_writelane_b32 v3, s81, 17
	v_writelane_b32 v3, s82, 18
	v_writelane_b32 v3, s83, 19
	v_writelane_b32 v3, s84, 20
	v_writelane_b32 v3, s85, 21
	v_writelane_b32 v3, s86, 22
	v_writelane_b32 v3, s87, 23
	v_writelane_b32 v3, s88, 24
	v_writelane_b32 v3, s89, 25
	v_writelane_b32 v3, s90, 26
	v_writelane_b32 v3, s91, 27
	v_writelane_b32 v3, s92, 28
	v_writelane_b32 v3, s93, 29
	v_writelane_b32 v3, s94, 30
	v_writelane_b32 v3, s95, 31
	v_writelane_b32 v3, s96, 32
	v_writelane_b32 v3, s97, 33
	s_lshl_b32 s2, s97, 11
	v_lshl_add_u32 v4, v0, 2, s2
	s_add_u32 s2, s76, 0x30c00000
	s_addc_u32 s3, s77, 0
	global_store_dword v4, v2, s[2:3]
	s_add_u32 s2, s2, 0x80000
	s_addc_u32 s3, s3, 0
	global_store_dword v4, v3, s[2:3]
	s_add_u32 s2, s2, 0x80000
	s_addc_u32 s3, s3, 0
	global_store_dword v4, v0, s[2:3]
	s_add_u32 s2, s2, 0x80000
	s_addc_u32 s3, s3, 0
	global_store_dword v4, v1, s[2:3]
	s_add_u32 s2, s2, 0x80000
	s_addc_u32 s3, s3, 0
	global_store_dword v4, v5, s[2:3]
	s_add_u32 s2, s2, 0x80000
	s_addc_u32 s3, s3, 0
	global_store_dword v4, v6, s[2:3]
	s_add_u32 s2, s2, 0x80000
	s_addc_u32 s3, s3, 0
	global_store_dword v4, v8, s[2:3]
	s_add_u32 s2, s2, 0x80000
	s_addc_u32 s3, s3, 0
	global_store_dword v4, v36, s[2:3]
	s_add_u32 s2, s2, 0x80000
	s_addc_u32 s3, s3, 0
	global_store_dword v4, v37, s[2:3]
	s_add_u32 s2, s2, 0x80000
	s_addc_u32 s3, s3, 0
	global_store_dword v4, v38, s[2:3]
	s_add_u32 s2, s2, 0x80000
	s_addc_u32 s3, s3, 0
	global_store_dword v4, v39, s[2:3]
	s_add_u32 s2, s2, 0x80000
	s_addc_u32 s3, s3, 0
	global_store_dword v4, v40, s[2:3]
	s_add_u32 s2, s2, 0x80000
	s_addc_u32 s3, s3, 0
	global_store_dword v4, v41, s[2:3]
	s_add_u32 s2, s2, 0x80000
	s_addc_u32 s3, s3, 0
	global_store_dword v4, v42, s[2:3]
	s_add_u32 s2, s2, 0x80000
	s_addc_u32 s3, s3, 0
	global_store_dword v4, v43, s[2:3]
	s_add_u32 s2, s2, 0x80000
	s_addc_u32 s3, s3, 0
	global_store_dword v4, v44, s[2:3]
	s_add_u32 s2, s2, 0x80000
	s_addc_u32 s3, s3, 0
	global_store_dword v4, v45, s[2:3]
	s_add_u32 s2, s2, 0x80000
	s_addc_u32 s3, s3, 0
	global_store_dword v4, v50, s[2:3]
	s_add_u32 s2, s2, 0x80000
	s_addc_u32 s3, s3, 0
	global_store_dword v4, v51, s[2:3]
	s_add_u32 s2, s2, 0x80000
	s_addc_u32 s3, s3, 0
	global_store_dword v4, v52, s[2:3]
	s_add_u32 s2, s2, 0x80000
	s_addc_u32 s3, s3, 0
	global_store_dword v4, v53, s[2:3]
	s_add_u32 s2, s2, 0x80000
	s_addc_u32 s3, s3, 0
	global_store_dword v4, v54, s[2:3]
	s_add_u32 s2, s2, 0x80000
	s_addc_u32 s3, s3, 0
	global_store_dword v4, v55, s[2:3]
	s_add_u32 s2, s2, 0x80000
	s_addc_u32 s3, s3, 0
	global_store_dword v4, v56, s[2:3]
	s_add_u32 s2, s2, 0x80000
	s_addc_u32 s3, s3, 0
	global_store_dword v4, v57, s[2:3]
	s_add_u32 s2, s2, 0x80000
	s_addc_u32 s3, s3, 0
	global_store_dword v4, v62, s[2:3]
	s_add_u32 s2, s2, 0x80000
	s_addc_u32 s3, s3, 0
	global_store_dword v4, v63, s[2:3]
	s_add_u32 s2, s2, 0x80000
	s_addc_u32 s3, s3, 0
	global_store_dword v4, v64, s[2:3]
	s_add_u32 s2, s2, 0x80000
	s_addc_u32 s3, s3, 0
	global_store_dword v4, v65, s[2:3]
	s_add_u32 s2, s2, 0x80000
	s_addc_u32 s3, s3, 0
	global_store_dword v4, v70, s[2:3]
	s_add_u32 s2, s2, 0x80000
	s_addc_u32 s3, s3, 0
	global_store_dword v4, v71, s[2:3]
	s_add_u32 s2, s2, 0x80000
	s_addc_u32 s3, s3, 0
	global_store_dword v4, v72, s[2:3]
	s_add_u32 s2, s2, 0x80000
	s_addc_u32 s3, s3, 0
	global_store_dword v4, v73, s[2:3]
	s_add_u32 s2, s2, 0x80000
	s_addc_u32 s3, s3, 0
	global_store_dword v4, v82, s[2:3]
	s_add_u32 s2, s2, 0x80000
	s_addc_u32 s3, s3, 0
	global_store_dword v4, v83, s[2:3]
	s_add_u32 s2, s2, 0x80000
	s_addc_u32 s3, s3, 0
	global_store_dword v4, v84, s[2:3]
	s_add_u32 s2, s2, 0x80000
	s_addc_u32 s3, s3, 0
	global_store_dword v4, v85, s[2:3]
	s_add_u32 s2, s2, 0x80000
	s_addc_u32 s3, s3, 0
	global_store_dword v4, v88, s[2:3]
	s_add_u32 s2, s2, 0x80000
	s_addc_u32 s3, s3, 0
	global_store_dword v4, v89, s[2:3]
	s_add_u32 s2, s2, 0x80000
	s_addc_u32 s3, s3, 0
	global_store_dword v4, v94, s[2:3]
	s_add_u32 s2, s2, 0x80000
	s_addc_u32 s3, s3, 0
	global_store_dword v4, v95, s[2:3]
	s_add_u32 s2, s2, 0x80000
	s_addc_u32 s3, s3, 0
	global_store_dword v4, v96, s[2:3]
	s_add_u32 s2, s2, 0x80000
	s_addc_u32 s3, s3, 0
	global_store_dword v4, v97, s[2:3]
	s_add_u32 s2, s2, 0x80000
	s_addc_u32 s3, s3, 0
	global_store_dword v4, v102, s[2:3]
	s_add_u32 s2, s2, 0x80000
	s_addc_u32 s3, s3, 0
	global_store_dword v4, v103, s[2:3]
	s_add_u32 s2, s2, 0x80000
	s_addc_u32 s3, s3, 0
	global_store_dword v4, v104, s[2:3]
	s_add_u32 s2, s2, 0x80000
	s_addc_u32 s3, s3, 0
	global_store_dword v4, v105, s[2:3]
	s_add_u32 s2, s2, 0x80000
	s_addc_u32 s3, s3, 0
	global_store_dword v4, v122, s[2:3]
	s_add_u32 s2, s2, 0x80000
	s_addc_u32 s3, s3, 0
	global_store_dword v4, v123, s[2:3]
	s_add_u32 s2, s2, 0x80000
	s_addc_u32 s3, s3, 0
	global_store_dword v4, v124, s[2:3]
	s_add_u32 s2, s2, 0x80000
	s_addc_u32 s3, s3, 0
	global_store_dword v4, v125, s[2:3]
	s_add_u32 s2, s2, 0x80000
	s_addc_u32 s3, s3, 0
	global_store_dword v4, v170, s[2:3]
	s_add_u32 s2, s2, 0x80000
	s_addc_u32 s3, s3, 0
	global_store_dword v4, v171, s[2:3]
	s_add_u32 s2, s2, 0x80000
	s_addc_u32 s3, s3, 0
	global_store_dword v4, v172, s[2:3]
	s_add_u32 s2, s2, 0x80000
	s_addc_u32 s3, s3, 0
	global_store_dword v4, v173, s[2:3]
	s_add_u32 s2, s2, 0x80000
	s_addc_u32 s3, s3, 0
	global_store_dword v4, v174, s[2:3]
	s_add_u32 s2, s2, 0x80000
	s_addc_u32 s3, s3, 0
	global_store_dword v4, v175, s[2:3]
	s_add_u32 s2, s2, 0x80000
	s_addc_u32 s3, s3, 0
	global_store_dword v4, v195, s[2:3]
	s_add_u32 s2, s2, 0x80000
	s_addc_u32 s3, s3, 0
	global_store_dword v4, v197, s[2:3]
	s_add_u32 s2, s2, 0x80000
	s_addc_u32 s3, s3, 0
	global_store_dword v4, v254, s[2:3]
	s_add_u32 s2, s2, 0x80000
	s_addc_u32 s3, s3, 0
	global_store_dword v4, v255, s[2:3]
	s_waitcnt vmcnt(0)
	v_lshlrev_b32_e32 v4, 2, v0
	v_add_u32_e32 v4, 0x22080, v4
	ds_read_b32 v7, v4 offset:4096
	ds_read_b32 v254, v4 offset:2048
	s_waitcnt lgkmcnt(0)
	s_sub_i32 s2, s97, 0x70
	v_readlane_b32 s0, v7, 0
	v_readlane_b32 s1, v7, 1
	v_readlane_b32 s20, v7, 2
	v_readlane_b32 s76, v7, 3
	v_readlane_b32 s77, v7, 4
	s_movk_i32 s96, 0x90
	s_mov_b32 s97, s2
	s_mov_b32 s32, 1
	s_nop 4
	s_branch .Lmode_reentry

.Lsnap_done:
	s_add_u32 s94, s76, 0x1bc00000
	v_writelane_b32 v255, s61, 7
	s_addc_u32 s3, s77, 0
	v_writelane_b32 v255, s3, 33
	s_add_u32 s3, s76, 0x1de00000
	v_writelane_b32 v255, s3, 1
	s_addc_u32 s3, s77, 0
	s_add_u32 s8, s76, 0x22000000
	s_addc_u32 s9, s77, 0
	s_add_u32 s30, s76, 0x24000000
	v_lshlrev_b32_e32 v186, 4, v0
	v_and_b32_e32 v2, 32, v0
	v_writelane_b32 v255, s3, 3
	s_addc_u32 s31, s77, 0
	v_bitop3_b32 v176, v186, v2, 48 bitop3:0x6c
	v_lshrrev_b32_e32 v2, 1, v0
	v_lshrrev_b32_e32 v3, 5, v0
	v_writelane_b32 v254, s8, 63
	s_add_u32 s3, s76, 0x2a600000
	v_and_b32_e32 v2, 24, v2
	v_writelane_b32 v255, s9, 0
	v_and_b32_e32 v3, 4, v3
	v_bfe_u32 v4, v0, 2, 2
	v_or_b32_e32 v179, 0x2000, v186
	v_writelane_b32 v255, s3, 19
	s_addc_u32 s3, s77, 0
	v_bfe_u32 v178, v0, 2, 4
	v_or3_b32 v2, v3, v4, v2
	v_lshrrev_b32_e32 v3, 7, v179
	s_movk_i32 s2, 0x70
	v_writelane_b32 v255, s3, 21
	v_and_b32_e32 v177, 64, v0
	v_lshrrev_b32_e32 v185, 3, v0
	v_and_or_b32 v183, v3, s2, v178
	s_movk_i32 s2, 0x60
	v_writelane_b32 v255, s72, 25
	v_or_b32_e32 v180, v176, v177
	v_and_or_b32 v181, v185, 48, v178
	v_and_or_b32 v182, v185, 32, v2
	s_andn2_b64 vcc, exec, s[0:1]
	v_and_or_b32 v184, v3, s2, v2
	v_writelane_b32 v255, s73, 26
	s_cbranch_vccnz .LBB0_636
	s_lshr_b32 s11, s6, 6
	s_ashr_i32 s81, s80, 31
	s_ashr_i32 s5, s4, 31
	s_lshr_b32 s10, s6, 8
	s_lshl_b32 s24, s11, 10
	s_lshl_b64 s[0:1], s[80:81], 21
	s_lshl_b64 s[2:3], s[4:5], 21
	s_add_u32 s2, s70, s2
	s_addc_u32 s3, s71, s3
	s_add_i32 s25, s24, 0
	v_lshl_or_b32 v136, v182, 13, v180
	s_add_i32 m0, s25, 0x10000
	v_lshl_or_b32 v140, v184, 13, v180
	global_load_lds_dwordx4 v136, s[2:3]
	s_add_i32 m0, s25, 0x12000
	s_add_u32 s8, s2, 0x100000
	global_load_lds_dwordx4 v140, s[2:3]
	s_addc_u32 s9, s3, 0
	s_add_i32 m0, s25, 0x14000
	v_lshl_or_b32 v134, v181, 13, v180
	global_load_lds_dwordx4 v136, s[8:9]
	s_add_i32 m0, s25, 0x16000
	s_add_u32 s0, s22, s0
	s_addc_u32 s1, s23, s1
	s_add_i32 s53, s25, 0x2000
	global_load_lds_dwordx4 v140, s[8:9]
	s_mov_b32 m0, s25
	s_add_u32 s8, s0, 0x100000
	v_lshl_or_b32 v138, v183, 13, v180
	global_load_lds_dwordx4 v134, s[0:1]
	s_mov_b32 m0, s53
	s_addc_u32 s9, s1, 0
	s_add_i32 s68, s25, 0x4000
	global_load_lds_dwordx4 v138, s[0:1]
	s_mov_b32 m0, s68
	s_add_i32 s72, s25, 0x6000
	global_load_lds_dwordx4 v134, s[8:9]
	s_mov_b32 m0, s72
	s_mov_b32 s88, s60
	global_load_lds_dwordx4 v138, s[8:9]
	v_mov_b32_e32 v143, 0
	v_writelane_b32 v255, s88, 37
	v_mov_b32_e32 v137, v143
	v_mov_b32_e32 v141, v143
	v_mov_b32_e32 v135, v143
	v_mov_b32_e32 v139, v143
	s_cmp_eq_u32 s10, 1
	v_writelane_b32 v255, s89, 38
	s_mov_b32 s7, 0
	v_lshl_add_u64 v[8:9], s[2:3], 0, v[136:137]
	v_lshl_add_u64 v[6:7], s[2:3], 0, v[140:141]
	v_lshl_add_u64 v[4:5], s[0:1], 0, v[134:135]
	s_cselect_b64 s[28:29], -1, 0
	s_cmp_lg_u32 s10, 1
	v_lshl_add_u64 v[2:3], s[0:1], 0, v[138:139]
	s_cbranch_scc1 .LBB0_364
	s_setprio 1
	s_barrier

.LBB0_374:
	ds_read_b128 v[130:133], v188
	ds_read_b128 v[148:151], v188 offset:1024
	ds_read_b128 v[152:155], v188 offset:2048
	ds_read_b128 v[156:159], v188 offset:3072
	ds_read_b128 v[160:163], v189
	ds_read_b128 v[164:167], v189 offset:1024
	ds_read_b128 v[168:171], v189 offset:2048
	ds_read_b128 v[194:197], v189 offset:3072
	s_add_u32 s2, s0, 0xfff00080
	s_addc_u32 s3, s1, -1
	s_cmp_eq_u32 s43, 60
	s_cselect_b32 s39, s5, s3
	s_cselect_b32 s38, s6, s2
	s_cselect_b32 s3, s19, s42
	s_cselect_b32 s2, s21, s33
	v_lshl_add_u64 v[230:231], s[0:1], 0, v[144:145]
	s_add_i32 m0, s25, 0xc000
	ds_read_b128 v[198:201], v190
	ds_read_b128 v[202:205], v190 offset:1024
	ds_read_b128 v[206:209], v190 offset:2048
	ds_read_b128 v[210:213], v190 offset:3072
	ds_read_b128 v[214:217], v190 offset:4096
	ds_read_b128 v[218:221], v190 offset:5120
	ds_read_b128 v[222:225], v190 offset:6144
	ds_read_b128 v[226:229], v190 offset:7168
	global_load_lds_dwordx4 v[230:231], off
	v_lshl_add_u64 v[230:231], s[0:1], 0, v[146:147]
	s_add_i32 m0, s25, 0xe000
	s_nop 0
	global_load_lds_dwordx4 v[230:231], off
	s_waitcnt vmcnt(8)
	s_waitcnt lgkmcnt(0)
	s_barrier
	s_waitcnt lgkmcnt(0)
	v_mfma_f32_16x16x32_bf16 v[126:129], v[130:133], v[198:201], v[126:129]
	v_mfma_f32_16x16x32_bf16 v[122:125], v[152:155], v[198:201], v[122:125]
	v_mfma_f32_16x16x32_bf16 v[110:113], v[130:133], v[206:209], v[110:113]
	v_mfma_f32_16x16x32_bf16 v[106:109], v[152:155], v[206:209], v[106:109]
	v_mfma_f32_16x16x32_bf16 v[94:97], v[130:133], v[214:217], v[94:97]
	v_mfma_f32_16x16x32_bf16 v[90:93], v[152:155], v[214:217], v[90:93]
	v_mfma_f32_16x16x32_bf16 v[78:81], v[130:133], v[222:225], v[78:81]
	v_mfma_f32_16x16x32_bf16 v[74:77], v[152:155], v[222:225], v[74:77]
	v_mfma_f32_16x16x32_bf16 v[126:129], v[148:151], v[202:205], v[126:129]
	v_mfma_f32_16x16x32_bf16 v[122:125], v[156:159], v[202:205], v[122:125]
	v_mfma_f32_16x16x32_bf16 v[110:113], v[148:151], v[210:213], v[110:113]
	v_mfma_f32_16x16x32_bf16 v[106:109], v[156:159], v[210:213], v[106:109]
	v_mfma_f32_16x16x32_bf16 v[94:97], v[148:151], v[218:221], v[94:97]
	v_mfma_f32_16x16x32_bf16 v[90:93], v[156:159], v[218:221], v[90:93]
	v_mfma_f32_16x16x32_bf16 v[78:81], v[148:151], v[226:229], v[78:81]
	v_mfma_f32_16x16x32_bf16 v[74:77], v[156:159], v[226:229], v[74:77]
	v_mfma_f32_16x16x32_bf16 v[118:121], v[160:163], v[198:201], v[118:121]
	v_mfma_f32_16x16x32_bf16 v[114:117], v[168:171], v[198:201], v[114:117]
	v_mfma_f32_16x16x32_bf16 v[102:105], v[160:163], v[206:209], v[102:105]
	v_mfma_f32_16x16x32_bf16 v[98:101], v[168:171], v[206:209], v[98:101]
	v_mfma_f32_16x16x32_bf16 v[86:89], v[160:163], v[214:217], v[86:89]
	v_mfma_f32_16x16x32_bf16 v[82:85], v[168:171], v[214:217], v[82:85]
	v_mfma_f32_16x16x32_bf16 v[70:73], v[160:163], v[222:225], v[70:73]
	v_mfma_f32_16x16x32_bf16 v[66:69], v[168:171], v[222:225], v[66:69]
	v_mfma_f32_16x16x32_bf16 v[118:121], v[164:167], v[202:205], v[118:121]
	v_mfma_f32_16x16x32_bf16 v[114:117], v[194:197], v[202:205], v[114:117]
	v_mfma_f32_16x16x32_bf16 v[102:105], v[164:167], v[210:213], v[102:105]
	v_mfma_f32_16x16x32_bf16 v[98:101], v[194:197], v[210:213], v[98:101]
	v_mfma_f32_16x16x32_bf16 v[86:89], v[164:167], v[218:221], v[86:89]
	v_mfma_f32_16x16x32_bf16 v[82:85], v[194:197], v[218:221], v[82:85]
	v_mfma_f32_16x16x32_bf16 v[70:73], v[164:167], v[226:229], v[70:73]
	v_mfma_f32_16x16x32_bf16 v[66:69], v[194:197], v[226:229], v[66:69]
	s_barrier
	s_add_i32 s47, s87, s24
	v_lshl_add_u64 v[230:231], s[2:3], 0, v[136:137]
	s_mov_b32 m0, s47
	ds_read_b128 v[198:201], v190 offset:16384
	ds_read_b128 v[202:205], v190 offset:17408
	ds_read_b128 v[206:209], v190 offset:18432
	ds_read_b128 v[210:213], v190 offset:19456
	ds_read_b128 v[214:217], v190 offset:20480
	ds_read_b128 v[218:221], v190 offset:21504
	ds_read_b128 v[222:225], v190 offset:22528
	ds_read_b128 v[226:229], v190 offset:23552
	global_load_lds_dwordx4 v[230:231], off
	s_add_i32 m0, s47, 0x2000
	s_add_u32 s48, s2, 0x100000
	v_lshl_add_u64 v[232:233], s[2:3], 0, v[140:141]
	s_addc_u32 s49, s3, 0
	s_add_i32 s47, s88, s24
	global_load_lds_dwordx4 v[232:233], off
	v_lshl_add_u64 v[234:235], s[48:49], 0, v[136:137]
	s_mov_b32 m0, s47
	v_lshl_add_u64 v[236:237], s[38:39], 0, v[138:139]
	global_load_lds_dwordx4 v[234:235], off
	v_lshl_add_u64 v[234:235], s[48:49], 0, v[140:141]
	s_add_i32 m0, s47, 0x2000
	s_nop 0
	global_load_lds_dwordx4 v[234:235], off
	v_lshl_add_u64 v[234:235], s[38:39], 0, v[134:135]
	s_mov_b32 m0, s25
	s_nop 0
	global_load_lds_dwordx4 v[234:235], off
	s_mov_b32 m0, s53
	s_nop 0
	global_load_lds_dwordx4 v[236:237], off
	s_waitcnt vmcnt(8)
	s_waitcnt lgkmcnt(0)
	s_barrier
	s_waitcnt lgkmcnt(0)
	v_mfma_f32_16x16x32_bf16 v[62:65], v[130:133], v[198:201], v[62:65]
	v_mfma_f32_16x16x32_bf16 v[58:61], v[152:155], v[198:201], v[58:61]
	v_mfma_f32_16x16x32_bf16 v[46:49], v[130:133], v[206:209], v[46:49]
	v_mfma_f32_16x16x32_bf16 v[42:45], v[152:155], v[206:209], v[42:45]
	v_mfma_f32_16x16x32_bf16 v[30:33], v[130:133], v[214:217], v[30:33]
	v_mfma_f32_16x16x32_bf16 v[26:29], v[152:155], v[214:217], v[26:29]
	v_mfma_f32_16x16x32_bf16 v[14:17], v[130:133], v[222:225], v[14:17]
	v_mfma_f32_16x16x32_bf16 v[10:13], v[152:155], v[222:225], v[10:13]
	v_mfma_f32_16x16x32_bf16 v[62:65], v[148:151], v[202:205], v[62:65]
	v_mfma_f32_16x16x32_bf16 v[58:61], v[156:159], v[202:205], v[58:61]
	v_mfma_f32_16x16x32_bf16 v[46:49], v[148:151], v[210:213], v[46:49]
	v_mfma_f32_16x16x32_bf16 v[42:45], v[156:159], v[210:213], v[42:45]
	v_mfma_f32_16x16x32_bf16 v[30:33], v[148:151], v[218:221], v[30:33]
	v_mfma_f32_16x16x32_bf16 v[26:29], v[156:159], v[218:221], v[26:29]
	v_mfma_f32_16x16x32_bf16 v[14:17], v[148:151], v[226:229], v[14:17]
	v_mfma_f32_16x16x32_bf16 v[10:13], v[156:159], v[226:229], v[10:13]
	v_mfma_f32_16x16x32_bf16 v[54:57], v[160:163], v[198:201], v[54:57]
	v_mfma_f32_16x16x32_bf16 v[50:53], v[168:171], v[198:201], v[50:53]
	v_mfma_f32_16x16x32_bf16 v[38:41], v[160:163], v[206:209], v[38:41]
	v_mfma_f32_16x16x32_bf16 v[34:37], v[168:171], v[206:209], v[34:37]
	v_mfma_f32_16x16x32_bf16 v[22:25], v[160:163], v[214:217], v[22:25]
	v_mfma_f32_16x16x32_bf16 v[18:21], v[168:171], v[214:217], v[18:21]
	v_mfma_f32_16x16x32_bf16 v[6:9], v[160:163], v[222:225], v[6:9]
	v_mfma_f32_16x16x32_bf16 v[2:5], v[168:171], v[222:225], v[2:5]
	v_mfma_f32_16x16x32_bf16 v[54:57], v[164:167], v[202:205], v[54:57]
	v_mfma_f32_16x16x32_bf16 v[50:53], v[194:197], v[202:205], v[50:53]
	v_mfma_f32_16x16x32_bf16 v[38:41], v[164:167], v[210:213], v[38:41]
	v_mfma_f32_16x16x32_bf16 v[34:37], v[194:197], v[210:213], v[34:37]
	v_mfma_f32_16x16x32_bf16 v[22:25], v[164:167], v[218:221], v[22:25]
	v_mfma_f32_16x16x32_bf16 v[18:21], v[194:197], v[218:221], v[18:21]
	v_mfma_f32_16x16x32_bf16 v[6:9], v[164:167], v[226:229], v[6:9]
	v_mfma_f32_16x16x32_bf16 v[2:5], v[194:197], v[226:229], v[2:5]
	s_barrier
	s_add_i32 s47, 0, 0x18000
	v_add_u32_e32 v142, s47, v187
	s_add_i32 s48, 0, 0x1c000
	ds_read_b128 v[130:133], v142
	ds_read_b128 v[148:151], v142 offset:1024
	ds_read_b128 v[152:155], v142 offset:2048
	ds_read_b128 v[156:159], v142 offset:3072
	v_add_u32_e32 v142, s48, v187
	ds_read_b128 v[160:163], v142
	ds_read_b128 v[164:167], v142 offset:1024
	ds_read_b128 v[168:171], v142 offset:2048
	ds_read_b128 v[194:197], v142 offset:3072
	s_add_u32 s38, s38, 0x100000
	s_addc_u32 s39, s39, 0
	s_mov_b32 m0, s68
	v_lshl_add_u64 v[238:239], s[38:39], 0, v[134:135]
	ds_read_b128 v[198:201], v190 offset:32768
	ds_read_b128 v[202:205], v190 offset:33792
	ds_read_b128 v[206:209], v190 offset:34816
	ds_read_b128 v[210:213], v190 offset:35840
	ds_read_b128 v[214:217], v190 offset:36864
	ds_read_b128 v[218:221], v190 offset:37888
	ds_read_b128 v[222:225], v190 offset:38912
	ds_read_b128 v[226:229], v190 offset:39936
	global_load_lds_dwordx4 v[238:239], off
	v_lshl_add_u64 v[238:239], s[38:39], 0, v[138:139]
	s_mov_b32 m0, s72
	s_nop 0
	global_load_lds_dwordx4 v[238:239], off
	s_waitcnt vmcnt(8)
	s_waitcnt lgkmcnt(0)
	s_barrier
	s_waitcnt lgkmcnt(0)
	v_mfma_f32_16x16x32_bf16 v[126:129], v[130:133], v[198:201], v[126:129]
	v_mfma_f32_16x16x32_bf16 v[122:125], v[152:155], v[198:201], v[122:125]
	v_mfma_f32_16x16x32_bf16 v[110:113], v[130:133], v[206:209], v[110:113]
	v_mfma_f32_16x16x32_bf16 v[106:109], v[152:155], v[206:209], v[106:109]
	v_mfma_f32_16x16x32_bf16 v[94:97], v[130:133], v[214:217], v[94:97]
	v_mfma_f32_16x16x32_bf16 v[90:93], v[152:155], v[214:217], v[90:93]
	v_mfma_f32_16x16x32_bf16 v[78:81], v[130:133], v[222:225], v[78:81]
	v_mfma_f32_16x16x32_bf16 v[74:77], v[152:155], v[222:225], v[74:77]
	v_mfma_f32_16x16x32_bf16 v[126:129], v[148:151], v[202:205], v[126:129]
	v_mfma_f32_16x16x32_bf16 v[122:125], v[156:159], v[202:205], v[122:125]
	v_mfma_f32_16x16x32_bf16 v[110:113], v[148:151], v[210:213], v[110:113]
	v_mfma_f32_16x16x32_bf16 v[106:109], v[156:159], v[210:213], v[106:109]
	v_mfma_f32_16x16x32_bf16 v[94:97], v[148:151], v[218:221], v[94:97]
	v_mfma_f32_16x16x32_bf16 v[90:93], v[156:159], v[218:221], v[90:93]
	v_mfma_f32_16x16x32_bf16 v[78:81], v[148:151], v[226:229], v[78:81]
	v_mfma_f32_16x16x32_bf16 v[74:77], v[156:159], v[226:229], v[74:77]
	v_mfma_f32_16x16x32_bf16 v[118:121], v[160:163], v[198:201], v[118:121]
	v_mfma_f32_16x16x32_bf16 v[114:117], v[168:171], v[198:201], v[114:117]
	v_mfma_f32_16x16x32_bf16 v[102:105], v[160:163], v[206:209], v[102:105]
	v_mfma_f32_16x16x32_bf16 v[98:101], v[168:171], v[206:209], v[98:101]
	v_mfma_f32_16x16x32_bf16 v[86:89], v[160:163], v[214:217], v[86:89]
	v_mfma_f32_16x16x32_bf16 v[82:85], v[168:171], v[214:217], v[82:85]
	v_mfma_f32_16x16x32_bf16 v[70:73], v[160:163], v[222:225], v[70:73]
	v_mfma_f32_16x16x32_bf16 v[66:69], v[168:171], v[222:225], v[66:69]
	v_mfma_f32_16x16x32_bf16 v[118:121], v[164:167], v[202:205], v[118:121]
	v_mfma_f32_16x16x32_bf16 v[114:117], v[194:197], v[202:205], v[114:117]
	v_mfma_f32_16x16x32_bf16 v[102:105], v[164:167], v[210:213], v[102:105]
	v_mfma_f32_16x16x32_bf16 v[98:101], v[194:197], v[210:213], v[98:101]
	v_mfma_f32_16x16x32_bf16 v[86:89], v[164:167], v[218:221], v[86:89]
	v_mfma_f32_16x16x32_bf16 v[82:85], v[194:197], v[218:221], v[82:85]
	v_mfma_f32_16x16x32_bf16 v[70:73], v[164:167], v[226:229], v[70:73]
	v_mfma_f32_16x16x32_bf16 v[66:69], v[194:197], v[226:229], v[66:69]
	s_barrier
	s_add_i32 s38, s47, s24
	v_lshl_add_u64 v[230:231], v[230:231], 0, s[10:11]
	s_mov_b32 m0, s38
	ds_read_b128 v[198:201], v190 offset:49152
	ds_read_b128 v[202:205], v190 offset:50176
	ds_read_b128 v[206:209], v190 offset:51200
	ds_read_b128 v[210:213], v190 offset:52224
	ds_read_b128 v[214:217], v190 offset:53248
	ds_read_b128 v[218:221], v190 offset:54272
	ds_read_b128 v[222:225], v190 offset:55296
	ds_read_b128 v[226:229], v190 offset:56320
	global_load_lds_dwordx4 v[230:231], off
	s_add_i32 m0, s38, 0x2000
	s_add_u32 s2, s2, 0x100080
	v_lshl_add_u64 v[230:231], v[232:233], 0, s[10:11]
	s_addc_u32 s3, s3, 0
	s_add_i32 s38, s48, s24
	global_load_lds_dwordx4 v[230:231], off
	v_lshl_add_u64 v[230:231], s[2:3], 0, v[136:137]
	s_mov_b32 m0, s38
	s_nop 0
	global_load_lds_dwordx4 v[230:231], off
	v_lshl_add_u64 v[230:231], s[2:3], 0, v[140:141]
	s_add_i32 m0, s38, 0x2000
	s_nop 0
	global_load_lds_dwordx4 v[230:231], off
	v_lshl_add_u64 v[230:231], v[234:235], 0, s[10:11]
	s_mov_b32 m0, s77
	s_nop 0
	global_load_lds_dwordx4 v[230:231], off
	v_lshl_add_u64 v[230:231], v[236:237], 0, s[10:11]
	s_mov_b32 m0, s78
	s_nop 0
	global_load_lds_dwordx4 v[230:231], off
	s_waitcnt vmcnt(8)
	s_waitcnt lgkmcnt(0)
	s_barrier
	s_waitcnt lgkmcnt(0)
	v_mfma_f32_16x16x32_bf16 v[62:65], v[130:133], v[198:201], v[62:65]
	v_mfma_f32_16x16x32_bf16 v[58:61], v[152:155], v[198:201], v[58:61]
	v_mfma_f32_16x16x32_bf16 v[46:49], v[130:133], v[206:209], v[46:49]
	v_mfma_f32_16x16x32_bf16 v[42:45], v[152:155], v[206:209], v[42:45]
	v_mfma_f32_16x16x32_bf16 v[30:33], v[130:133], v[214:217], v[30:33]
	v_mfma_f32_16x16x32_bf16 v[26:29], v[152:155], v[214:217], v[26:29]
	v_mfma_f32_16x16x32_bf16 v[14:17], v[130:133], v[222:225], v[14:17]
	v_mfma_f32_16x16x32_bf16 v[10:13], v[152:155], v[222:225], v[10:13]
	v_mfma_f32_16x16x32_bf16 v[62:65], v[148:151], v[202:205], v[62:65]
	v_mfma_f32_16x16x32_bf16 v[58:61], v[156:159], v[202:205], v[58:61]
	v_mfma_f32_16x16x32_bf16 v[46:49], v[148:151], v[210:213], v[46:49]
	v_mfma_f32_16x16x32_bf16 v[42:45], v[156:159], v[210:213], v[42:45]
	v_mfma_f32_16x16x32_bf16 v[30:33], v[148:151], v[218:221], v[30:33]
	v_mfma_f32_16x16x32_bf16 v[26:29], v[156:159], v[218:221], v[26:29]
	v_mfma_f32_16x16x32_bf16 v[14:17], v[148:151], v[226:229], v[14:17]
	v_mfma_f32_16x16x32_bf16 v[10:13], v[156:159], v[226:229], v[10:13]
	v_mfma_f32_16x16x32_bf16 v[54:57], v[160:163], v[198:201], v[54:57]
	v_mfma_f32_16x16x32_bf16 v[50:53], v[168:171], v[198:201], v[50:53]
	v_mfma_f32_16x16x32_bf16 v[38:41], v[160:163], v[206:209], v[38:41]
	v_mfma_f32_16x16x32_bf16 v[34:37], v[168:171], v[206:209], v[34:37]
	v_mfma_f32_16x16x32_bf16 v[22:25], v[160:163], v[214:217], v[22:25]
	v_mfma_f32_16x16x32_bf16 v[18:21], v[168:171], v[214:217], v[18:21]
	v_mfma_f32_16x16x32_bf16 v[6:9], v[160:163], v[222:225], v[6:9]
	v_mfma_f32_16x16x32_bf16 v[2:5], v[168:171], v[222:225], v[2:5]
	v_mfma_f32_16x16x32_bf16 v[54:57], v[164:167], v[202:205], v[54:57]
	v_mfma_f32_16x16x32_bf16 v[50:53], v[194:197], v[202:205], v[50:53]
	v_mfma_f32_16x16x32_bf16 v[38:41], v[164:167], v[210:213], v[38:41]
	v_mfma_f32_16x16x32_bf16 v[34:37], v[194:197], v[210:213], v[34:37]
	v_mfma_f32_16x16x32_bf16 v[22:25], v[164:167], v[218:221], v[22:25]
	v_mfma_f32_16x16x32_bf16 v[18:21], v[194:197], v[218:221], v[18:21]
	v_mfma_f32_16x16x32_bf16 v[6:9], v[164:167], v[226:229], v[6:9]
	v_mfma_f32_16x16x32_bf16 v[2:5], v[194:197], v[226:229], v[2:5]
	s_barrier
	s_add_i32 s43, s43, 2
	s_add_u32 s0, s0, 0x100
	s_addc_u32 s1, s1, 0
	s_add_u32 s33, s33, 0x100
	s_addc_u32 s42, s42, 0
	s_cmp_gt_u32 s43, 61
	s_cbranch_scc0 .LBB0_374
	s_and_b64 vcc, exec, s[12:13]
	s_cbranch_vccz .LBB0_377
	s_barrier

.LBB0_657:
	s_setprio 0
	s_mov_b64 s[14:15], exec
	v_readlane_b32 s16, v254, 17
	v_readlane_b32 s17, v254, 18
	s_and_b64 s[16:17], s[14:15], s[16:17]
	s_mov_b64 exec, s[16:17]
	v_readfirstlane_b32 s18, v252
	s_nop 1
	v_add_u32_e32 v161, s18, v253
	v_mov_b32_e32 v2, s42
	ds_write_b32 v2, v161
	s_or_b64 exec, exec, s[14:15]
	s_waitcnt lgkmcnt(0)
	s_barrier
	ds_read_b32 v2, v169
	s_movk_i32 s14, 0x7ff
	s_waitcnt lgkmcnt(0)
	v_cmp_lt_i32_e64 s[14:15], s14, v2
	v_readfirstlane_b32 s34, v2
	s_and_b64 vcc, exec, s[14:15]
	s_cbranch_vccnz .LBB0_656
	s_mov_b64 s[16:17], exec
	v_readlane_b32 s18, v254, 17
	v_readlane_b32 s19, v254, 18
	s_and_b64 s[18:19], s[16:17], s[18:19]
	s_mov_b64 exec, s[18:19]
	s_cbranch_execz .LBB0_664
	s_mov_b64 s[20:21], exec
	v_mbcnt_lo_u32_b32 v253, s20, 0
	v_mbcnt_hi_u32_b32 v253, s21, v253
	v_cmp_eq_u32_e32 vcc, 0, v253
	s_and_saveexec_b64 s[18:19], vcc
	s_cbranch_execz .LBB0_663
	s_bcnt1_i32_b64 s20, s[20:21]
	v_mov_b32_e32 v252, s20
	global_atomic_add v252, v147, v252, s[76:77] offset:512 sc0

.LBB0_743:
	s_andn2_b64 vcc, exec, s[0:1]
	s_cbranch_vccnz .LBB0_1015
	s_add_u32 s19, s76, 0x42000000
	s_addc_u32 s69, s77, 0
	s_add_u32 s70, s76, 0x3f400000
	s_addc_u32 s71, s77, 0
	s_lshr_b32 s10, s6, 6
	s_ashr_i32 s15, s14, 31
	s_ashr_i32 s5, s4, 31
	s_lshr_b32 s16, s6, 8
	s_lshl_b32 s72, s10, 10
	s_lshl_b64 s[0:1], s[14:15], 20
	s_lshl_b64 s[2:3], s[4:5], 20
	s_add_u32 s2, s70, s2
	s_addc_u32 s3, s71, s3
	s_add_i32 s73, s72, 0
	v_lshl_or_b32 v148, v182, 12, v180
	s_add_i32 m0, s73, 0x10000
	v_lshl_or_b32 v152, v184, 12, v180
	global_load_lds_dwordx4 v148, s[2:3]
	s_add_i32 m0, s73, 0x12000
	s_add_u32 s8, s2, 0x80000
	global_load_lds_dwordx4 v152, s[2:3]
	s_addc_u32 s9, s3, 0
	s_add_i32 m0, s73, 0x14000
	v_lshl_or_b32 v146, v181, 12, v180
	global_load_lds_dwordx4 v148, s[8:9]
	s_add_i32 m0, s73, 0x16000
	s_add_u32 s0, s19, s0
	s_addc_u32 s1, s69, s1
	s_add_i32 s74, s73, 0x2000
	global_load_lds_dwordx4 v152, s[8:9]
	s_mov_b32 m0, s73
	s_add_u32 s8, s0, 0x80000
	v_lshl_or_b32 v150, v183, 12, v180
	global_load_lds_dwordx4 v146, s[0:1]
	s_mov_b32 m0, s74
	s_addc_u32 s9, s1, 0
	s_add_i32 s75, s73, 0x4000
	global_load_lds_dwordx4 v150, s[0:1]
	s_mov_b32 m0, s75
	s_add_i32 s76, s73, 0x6000
	global_load_lds_dwordx4 v146, s[8:9]
	s_mov_b32 m0, s76
	s_mov_b32 s88, s60
	global_load_lds_dwordx4 v150, s[8:9]
	v_writelane_b32 v255, s88, 37
	s_cmp_eq_u32 s16, 1
	v_mov_b32_e32 v155, 0
	v_writelane_b32 v255, s89, 38
	s_cselect_b64 s[8:9], -1, 0
	v_mov_b32_e32 v149, v155
	v_mov_b32_e32 v153, v155
	v_mov_b32_e32 v147, v155
	v_mov_b32_e32 v151, v155
	v_writelane_b32 v255, s8, 7
	s_mov_b32 s7, 0
	v_lshl_add_u64 v[8:9], s[2:3], 0, v[148:149]
	v_lshl_add_u64 v[6:7], s[2:3], 0, v[152:153]
	v_lshl_add_u64 v[4:5], s[0:1], 0, v[146:147]
	v_lshl_add_u64 v[2:3], s[0:1], 0, v[150:151]
	v_writelane_b32 v255, s9, 8
	s_cmp_lg_u32 s16, 1
	s_cbranch_scc1 .LBB0_746
	s_setprio 1
	s_barrier

.LBB0_755:
	ds_read_b128 v[122:125], v175
	ds_read_b128 v[126:129], v175 offset:1024
	ds_read_b128 v[138:141], v175 offset:2048
	ds_read_b128 v[142:145], v175 offset:3072
	ds_read_b128 v[160:163], v176
	ds_read_b128 v[164:167], v176 offset:1024
	ds_read_b128 v[168:171], v176 offset:2048
	ds_read_b128 v[180:183], v176 offset:3072
	s_add_u32 s2, s0, 0xfff80080
	s_addc_u32 s3, s1, -1
	s_cmp_eq_u32 s35, 28
	s_cselect_b32 s39, s5, s3
	s_cselect_b32 s38, s6, s2
	s_cselect_b32 s3, s16, s33
	s_cselect_b32 s2, s17, s21
	v_lshl_add_u64 v[216:217], s[0:1], 0, v[156:157]
	s_add_i32 m0, s73, 0xc000
	ds_read_b128 v[184:187], v177
	ds_read_b128 v[188:191], v177 offset:1024
	ds_read_b128 v[192:195], v177 offset:2048
	ds_read_b128 v[196:199], v177 offset:3072
	ds_read_b128 v[200:203], v177 offset:4096
	ds_read_b128 v[204:207], v177 offset:5120
	ds_read_b128 v[208:211], v177 offset:6144
	ds_read_b128 v[212:215], v177 offset:7168
	global_load_lds_dwordx4 v[216:217], off
	v_lshl_add_u64 v[216:217], s[0:1], 0, v[158:159]
	s_add_i32 m0, s73, 0xe000
	s_nop 0
	global_load_lds_dwordx4 v[216:217], off
	s_waitcnt vmcnt(8)
	s_waitcnt lgkmcnt(0)
	s_barrier
	s_waitcnt lgkmcnt(0)
	v_mfma_i32_16x16x64_i8 v[118:121], v[122:125], v[184:187], v[118:121]
	v_mfma_i32_16x16x64_i8 v[114:117], v[138:141], v[184:187], v[114:117]
	v_mfma_i32_16x16x64_i8 v[102:105], v[122:125], v[192:195], v[102:105]
	v_mfma_i32_16x16x64_i8 v[98:101], v[138:141], v[192:195], v[98:101]
	v_mfma_i32_16x16x64_i8 v[94:97], v[122:125], v[200:203], v[94:97]
	v_mfma_i32_16x16x64_i8 v[86:89], v[138:141], v[200:203], v[86:89]
	v_mfma_i32_16x16x64_i8 v[78:81], v[122:125], v[208:211], v[78:81]
	v_mfma_i32_16x16x64_i8 v[70:73], v[138:141], v[208:211], v[70:73]
	v_mfma_i32_16x16x64_i8 v[118:121], v[126:129], v[188:191], v[118:121]
	v_mfma_i32_16x16x64_i8 v[114:117], v[142:145], v[188:191], v[114:117]
	v_mfma_i32_16x16x64_i8 v[102:105], v[126:129], v[196:199], v[102:105]
	v_mfma_i32_16x16x64_i8 v[98:101], v[142:145], v[196:199], v[98:101]
	v_mfma_i32_16x16x64_i8 v[94:97], v[126:129], v[204:207], v[94:97]
	v_mfma_i32_16x16x64_i8 v[86:89], v[142:145], v[204:207], v[86:89]
	v_mfma_i32_16x16x64_i8 v[78:81], v[126:129], v[212:215], v[78:81]
	v_mfma_i32_16x16x64_i8 v[70:73], v[142:145], v[212:215], v[70:73]
	v_mfma_i32_16x16x64_i8 v[110:113], v[160:163], v[184:187], v[110:113]
	v_mfma_i32_16x16x64_i8 v[106:109], v[168:171], v[184:187], v[106:109]
	v_mfma_i32_16x16x64_i8 v[90:93], v[160:163], v[192:195], v[90:93]
	v_mfma_i32_16x16x64_i8 v[82:85], v[168:171], v[192:195], v[82:85]
	v_mfma_i32_16x16x64_i8 v[74:77], v[160:163], v[200:203], v[74:77]
	v_mfma_i32_16x16x64_i8 v[66:69], v[168:171], v[200:203], v[66:69]
	v_mfma_i32_16x16x64_i8 v[62:65], v[160:163], v[208:211], v[62:65]
	v_mfma_i32_16x16x64_i8 v[58:61], v[168:171], v[208:211], v[58:61]
	v_mfma_i32_16x16x64_i8 v[110:113], v[164:167], v[188:191], v[110:113]
	v_mfma_i32_16x16x64_i8 v[106:109], v[180:183], v[188:191], v[106:109]
	v_mfma_i32_16x16x64_i8 v[90:93], v[164:167], v[196:199], v[90:93]
	v_mfma_i32_16x16x64_i8 v[82:85], v[180:183], v[196:199], v[82:85]
	v_mfma_i32_16x16x64_i8 v[74:77], v[164:167], v[204:207], v[74:77]
	v_mfma_i32_16x16x64_i8 v[66:69], v[180:183], v[204:207], v[66:69]
	v_mfma_i32_16x16x64_i8 v[62:65], v[164:167], v[212:215], v[62:65]
	v_mfma_i32_16x16x64_i8 v[58:61], v[180:183], v[212:215], v[58:61]
	s_barrier
	s_add_i32 s42, s24, s72
	v_lshl_add_u64 v[216:217], s[2:3], 0, v[148:149]
	s_mov_b32 m0, s42
	ds_read_b128 v[184:187], v177 offset:16384
	ds_read_b128 v[188:191], v177 offset:17408
	ds_read_b128 v[192:195], v177 offset:18432
	ds_read_b128 v[196:199], v177 offset:19456
	ds_read_b128 v[200:203], v177 offset:20480
	ds_read_b128 v[204:207], v177 offset:21504
	ds_read_b128 v[208:211], v177 offset:22528
	ds_read_b128 v[212:215], v177 offset:23552
	global_load_lds_dwordx4 v[216:217], off
	s_add_i32 m0, s42, 0x2000
	s_add_u32 s42, s2, 0x80000
	v_lshl_add_u64 v[218:219], s[2:3], 0, v[152:153]
	s_addc_u32 s43, s3, 0
	s_add_i32 s49, s25, s72
	global_load_lds_dwordx4 v[218:219], off
	v_lshl_add_u64 v[220:221], s[42:43], 0, v[148:149]
	s_mov_b32 m0, s49
	v_lshl_add_u64 v[222:223], s[38:39], 0, v[150:151]
	global_load_lds_dwordx4 v[220:221], off
	v_lshl_add_u64 v[220:221], s[42:43], 0, v[152:153]
	s_add_i32 m0, s49, 0x2000
	s_nop 0
	global_load_lds_dwordx4 v[220:221], off
	v_lshl_add_u64 v[220:221], s[38:39], 0, v[146:147]
	s_mov_b32 m0, s73
	s_nop 0
	global_load_lds_dwordx4 v[220:221], off
	s_mov_b32 m0, s74
	s_nop 0
	global_load_lds_dwordx4 v[222:223], off
	s_waitcnt vmcnt(8)
	s_waitcnt lgkmcnt(0)
	s_barrier
	s_waitcnt lgkmcnt(0)
	v_mfma_i32_16x16x64_i8 v[54:57], v[122:125], v[184:187], v[54:57]
	v_mfma_i32_16x16x64_i8 v[50:53], v[138:141], v[184:187], v[50:53]
	v_mfma_i32_16x16x64_i8 v[46:49], v[122:125], v[192:195], v[46:49]
	v_mfma_i32_16x16x64_i8 v[38:41], v[138:141], v[192:195], v[38:41]
	v_mfma_i32_16x16x64_i8 v[134:137], v[122:125], v[200:203], v[134:137]
	v_mfma_i32_16x16x64_i8 v[26:29], v[138:141], v[200:203], v[26:29]
	v_mfma_i32_16x16x64_i8 v[14:17], v[138:141], v[208:211], v[14:17]
	v_mfma_i32_16x16x64_i8 v[122:125], v[122:125], v[208:211], v[130:133]
	v_mfma_i32_16x16x64_i8 v[54:57], v[126:129], v[188:191], v[54:57]
	v_mfma_i32_16x16x64_i8 v[50:53], v[142:145], v[188:191], v[50:53]
	v_mfma_i32_16x16x64_i8 v[46:49], v[126:129], v[196:199], v[46:49]
	v_mfma_i32_16x16x64_i8 v[38:41], v[142:145], v[196:199], v[38:41]
	v_mfma_i32_16x16x64_i8 v[130:133], v[126:129], v[204:207], v[134:137]
	v_mfma_i32_16x16x64_i8 v[26:29], v[142:145], v[204:207], v[26:29]
	v_mfma_i32_16x16x64_i8 v[14:17], v[142:145], v[212:215], v[14:17]
	v_mfma_i32_16x16x64_i8 v[122:125], v[126:129], v[212:215], v[122:125]
	v_mfma_i32_16x16x64_i8 v[42:45], v[160:163], v[184:187], v[42:45]
	v_mfma_i32_16x16x64_i8 v[34:37], v[168:171], v[184:187], v[34:37]
	v_mfma_i32_16x16x64_i8 v[30:33], v[160:163], v[192:195], v[30:33]
	v_mfma_i32_16x16x64_i8 v[22:25], v[168:171], v[192:195], v[22:25]
	v_mfma_i32_16x16x64_i8 v[18:21], v[160:163], v[200:203], v[18:21]
	v_mfma_i32_16x16x64_i8 v[10:13], v[168:171], v[200:203], v[10:13]
	v_mfma_i32_16x16x64_i8 v[2:5], v[160:163], v[208:211], v[2:5]
	v_mfma_i32_16x16x64_i8 v[6:9], v[168:171], v[208:211], v[6:9]
	v_mfma_i32_16x16x64_i8 v[42:45], v[164:167], v[188:191], v[42:45]
	v_mfma_i32_16x16x64_i8 v[34:37], v[180:183], v[188:191], v[34:37]
	v_mfma_i32_16x16x64_i8 v[30:33], v[164:167], v[196:199], v[30:33]
	v_mfma_i32_16x16x64_i8 v[22:25], v[180:183], v[196:199], v[22:25]
	v_mfma_i32_16x16x64_i8 v[18:21], v[164:167], v[204:207], v[18:21]
	v_mfma_i32_16x16x64_i8 v[10:13], v[180:183], v[204:207], v[10:13]
	v_mfma_i32_16x16x64_i8 v[2:5], v[164:167], v[212:215], v[2:5]
	v_mfma_i32_16x16x64_i8 v[6:9], v[180:183], v[212:215], v[6:9]
	s_barrier
	s_add_i32 s42, 0, 0x18000
	s_add_i32 s43, 0, 0x1c000
	v_add_u32_e32 v142, s42, v174
	v_add_u32_e32 v154, s43, v174
	ds_read_b128 v[126:129], v142
	ds_read_b128 v[138:141], v142 offset:1024
	ds_read_b128 v[134:137], v142 offset:2048
	ds_read_b128 v[142:145], v142 offset:3072
	ds_read_b128 v[160:163], v154
	ds_read_b128 v[164:167], v154 offset:1024
	ds_read_b128 v[168:171], v154 offset:2048
	ds_read_b128 v[180:183], v154 offset:3072
	s_add_u32 s38, s38, 0x80000
	s_addc_u32 s39, s39, 0
	s_mov_b32 m0, s75
	v_lshl_add_u64 v[224:225], s[38:39], 0, v[146:147]
	ds_read_b128 v[184:187], v177 offset:32768
	ds_read_b128 v[188:191], v177 offset:33792
	ds_read_b128 v[192:195], v177 offset:34816
	ds_read_b128 v[196:199], v177 offset:35840
	ds_read_b128 v[200:203], v177 offset:36864
	ds_read_b128 v[204:207], v177 offset:37888
	ds_read_b128 v[208:211], v177 offset:38912
	ds_read_b128 v[212:215], v177 offset:39936
	global_load_lds_dwordx4 v[224:225], off
	v_lshl_add_u64 v[224:225], s[38:39], 0, v[150:151]
	s_mov_b32 m0, s76
	s_nop 0
	global_load_lds_dwordx4 v[224:225], off
	s_waitcnt vmcnt(8)
	s_waitcnt lgkmcnt(0)
	s_barrier
	s_waitcnt lgkmcnt(0)
	v_mfma_i32_16x16x64_i8 v[118:121], v[126:129], v[184:187], v[118:121]
	v_mfma_i32_16x16x64_i8 v[114:117], v[134:137], v[184:187], v[114:117]
	v_mfma_i32_16x16x64_i8 v[102:105], v[126:129], v[192:195], v[102:105]
	v_mfma_i32_16x16x64_i8 v[98:101], v[134:137], v[192:195], v[98:101]
	v_mfma_i32_16x16x64_i8 v[94:97], v[126:129], v[200:203], v[94:97]
	v_mfma_i32_16x16x64_i8 v[86:89], v[134:137], v[200:203], v[86:89]
	v_mfma_i32_16x16x64_i8 v[78:81], v[126:129], v[208:211], v[78:81]
	v_mfma_i32_16x16x64_i8 v[70:73], v[134:137], v[208:211], v[70:73]
	v_mfma_i32_16x16x64_i8 v[118:121], v[138:141], v[188:191], v[118:121]
	v_mfma_i32_16x16x64_i8 v[114:117], v[142:145], v[188:191], v[114:117]
	v_mfma_i32_16x16x64_i8 v[102:105], v[138:141], v[196:199], v[102:105]
	v_mfma_i32_16x16x64_i8 v[98:101], v[142:145], v[196:199], v[98:101]
	v_mfma_i32_16x16x64_i8 v[94:97], v[138:141], v[204:207], v[94:97]
	v_mfma_i32_16x16x64_i8 v[86:89], v[142:145], v[204:207], v[86:89]
	v_mfma_i32_16x16x64_i8 v[78:81], v[138:141], v[212:215], v[78:81]
	v_mfma_i32_16x16x64_i8 v[70:73], v[142:145], v[212:215], v[70:73]
	v_mfma_i32_16x16x64_i8 v[110:113], v[160:163], v[184:187], v[110:113]
	v_mfma_i32_16x16x64_i8 v[106:109], v[168:171], v[184:187], v[106:109]
	v_mfma_i32_16x16x64_i8 v[90:93], v[160:163], v[192:195], v[90:93]
	v_mfma_i32_16x16x64_i8 v[82:85], v[168:171], v[192:195], v[82:85]
	v_mfma_i32_16x16x64_i8 v[74:77], v[160:163], v[200:203], v[74:77]
	v_mfma_i32_16x16x64_i8 v[66:69], v[168:171], v[200:203], v[66:69]
	v_mfma_i32_16x16x64_i8 v[62:65], v[160:163], v[208:211], v[62:65]
	v_mfma_i32_16x16x64_i8 v[58:61], v[168:171], v[208:211], v[58:61]
	v_mfma_i32_16x16x64_i8 v[110:113], v[164:167], v[188:191], v[110:113]
	v_mfma_i32_16x16x64_i8 v[106:109], v[180:183], v[188:191], v[106:109]
	v_mfma_i32_16x16x64_i8 v[90:93], v[164:167], v[196:199], v[90:93]
	v_mfma_i32_16x16x64_i8 v[82:85], v[180:183], v[196:199], v[82:85]
	v_mfma_i32_16x16x64_i8 v[74:77], v[164:167], v[204:207], v[74:77]
	v_mfma_i32_16x16x64_i8 v[66:69], v[180:183], v[204:207], v[66:69]
	v_mfma_i32_16x16x64_i8 v[62:65], v[164:167], v[212:215], v[62:65]
	v_mfma_i32_16x16x64_i8 v[58:61], v[180:183], v[212:215], v[58:61]
	s_barrier
	s_add_i32 s38, s42, s72
	v_lshl_add_u64 v[216:217], v[216:217], 0, s[10:11]
	s_mov_b32 m0, s38
	ds_read_b128 v[184:187], v177 offset:49152
	ds_read_b128 v[188:191], v177 offset:50176
	ds_read_b128 v[192:195], v177 offset:51200
	ds_read_b128 v[196:199], v177 offset:52224
	ds_read_b128 v[200:203], v177 offset:53248
	ds_read_b128 v[204:207], v177 offset:54272
	ds_read_b128 v[208:211], v177 offset:55296
	ds_read_b128 v[212:215], v177 offset:56320
	global_load_lds_dwordx4 v[216:217], off
	s_add_i32 m0, s38, 0x2000
	s_add_u32 s2, s2, 0x80080
	v_lshl_add_u64 v[216:217], v[218:219], 0, s[10:11]
	s_addc_u32 s3, s3, 0
	s_add_i32 s38, s43, s72
	global_load_lds_dwordx4 v[216:217], off
	v_lshl_add_u64 v[216:217], s[2:3], 0, v[148:149]
	s_mov_b32 m0, s38
	s_nop 0
	global_load_lds_dwordx4 v[216:217], off
	v_lshl_add_u64 v[216:217], s[2:3], 0, v[152:153]
	s_add_i32 m0, s38, 0x2000
	s_nop 0
	global_load_lds_dwordx4 v[216:217], off
	v_lshl_add_u64 v[216:217], v[220:221], 0, s[10:11]
	s_mov_b32 m0, s82
	s_nop 0
	global_load_lds_dwordx4 v[216:217], off
	v_lshl_add_u64 v[216:217], v[222:223], 0, s[10:11]
	s_mov_b32 m0, s83
	s_nop 0
	global_load_lds_dwordx4 v[216:217], off
	s_waitcnt vmcnt(8)
	s_waitcnt lgkmcnt(0)
	s_barrier
	s_waitcnt lgkmcnt(0)
	v_mfma_i32_16x16x64_i8 v[54:57], v[126:129], v[184:187], v[54:57]
	v_mfma_i32_16x16x64_i8 v[50:53], v[134:137], v[184:187], v[50:53]
	v_mfma_i32_16x16x64_i8 v[46:49], v[126:129], v[192:195], v[46:49]
	v_mfma_i32_16x16x64_i8 v[38:41], v[134:137], v[192:195], v[38:41]
	v_mfma_i32_16x16x64_i8 v[130:133], v[126:129], v[200:203], v[130:133]
	v_mfma_i32_16x16x64_i8 v[26:29], v[134:137], v[200:203], v[26:29]
	v_mfma_i32_16x16x64_i8 v[122:125], v[126:129], v[208:211], v[122:125]
	v_mfma_i32_16x16x64_i8 v[14:17], v[134:137], v[208:211], v[14:17]
	v_mfma_i32_16x16x64_i8 v[54:57], v[138:141], v[188:191], v[54:57]
	v_mfma_i32_16x16x64_i8 v[50:53], v[142:145], v[188:191], v[50:53]
	v_mfma_i32_16x16x64_i8 v[46:49], v[138:141], v[196:199], v[46:49]
	v_mfma_i32_16x16x64_i8 v[38:41], v[142:145], v[196:199], v[38:41]
	v_mfma_i32_16x16x64_i8 v[134:137], v[138:141], v[204:207], v[130:133]
	v_mfma_i32_16x16x64_i8 v[26:29], v[142:145], v[204:207], v[26:29]
	v_mfma_i32_16x16x64_i8 v[130:133], v[138:141], v[212:215], v[122:125]
	v_mfma_i32_16x16x64_i8 v[14:17], v[142:145], v[212:215], v[14:17]
	v_mfma_i32_16x16x64_i8 v[42:45], v[160:163], v[184:187], v[42:45]
	v_mfma_i32_16x16x64_i8 v[34:37], v[168:171], v[184:187], v[34:37]
	v_mfma_i32_16x16x64_i8 v[30:33], v[160:163], v[192:195], v[30:33]
	v_mfma_i32_16x16x64_i8 v[22:25], v[168:171], v[192:195], v[22:25]
	v_mfma_i32_16x16x64_i8 v[18:21], v[160:163], v[200:203], v[18:21]
	v_mfma_i32_16x16x64_i8 v[10:13], v[168:171], v[200:203], v[10:13]
	v_mfma_i32_16x16x64_i8 v[2:5], v[160:163], v[208:211], v[2:5]
	v_mfma_i32_16x16x64_i8 v[6:9], v[168:171], v[208:211], v[6:9]
	v_mfma_i32_16x16x64_i8 v[42:45], v[164:167], v[188:191], v[42:45]
	v_mfma_i32_16x16x64_i8 v[34:37], v[180:183], v[188:191], v[34:37]
	v_mfma_i32_16x16x64_i8 v[30:33], v[164:167], v[196:199], v[30:33]
	v_mfma_i32_16x16x64_i8 v[22:25], v[180:183], v[196:199], v[22:25]
	v_mfma_i32_16x16x64_i8 v[18:21], v[164:167], v[204:207], v[18:21]
	v_mfma_i32_16x16x64_i8 v[10:13], v[180:183], v[204:207], v[10:13]
	v_mfma_i32_16x16x64_i8 v[2:5], v[164:167], v[212:215], v[2:5]
	v_mfma_i32_16x16x64_i8 v[6:9], v[180:183], v[212:215], v[6:9]
	s_barrier
	s_add_i32 s35, s35, 2
	s_add_u32 s0, s0, 0x100
	s_addc_u32 s1, s1, 0
	s_add_u32 s21, s21, 0x100
	s_addc_u32 s33, s33, 0
	s_cmp_gt_u32 s35, 29
	s_cbranch_scc0 .LBB0_755
	s_and_b64 vcc, exec, s[12:13]
	s_cbranch_vccz .LBB0_758
	s_barrier

.LBB0_1069:
	s_setprio 0
	v_readlane_b32 s52, v254, 10
	s_cmp_lt_i32 s52, 4
	s_cselect_b64 s[2:3], -1, 0
	s_and_b64 s[20:21], s[2:3], s[0:1]
	v_readlane_b32 s53, v254, 11
	v_readlane_b32 s54, v254, 12
	s_andn2_b64 vcc, exec, s[20:21]
	v_readlane_b32 s55, v254, 13
	s_cbranch_vccnz .LBB0_1396
	s_bitcmp0_b32 s54, 0
	s_cselect_b64 s[0:1], -1, 0
	s_cmpk_gt_i32 s97, -1
	s_cselect_b64 s[2:3], -1, 0
	s_or_b64 s[0:1], s[0:1], s[2:3]
	s_mov_b32 s61, 0
	s_and_b64 vcc, exec, s[0:1]
	s_cbranch_vccnz .LBB0_1147
	s_add_i32 s0, s97, 0x800
	v_and_b32_e32 v146, 48, v1
	v_mov_b32_e32 v147, 0
	s_add_u32 s24, s76, 0x26200000
	v_lshl_add_u64 v[2:3], s[76:77], 0, v[146:147]
	s_mov_b64 s[2:3], 0x500000
	s_addc_u32 s25, s77, 0
	s_movk_i32 s1, 0x200
	v_lshl_add_u64 v[148:149], v[2:3], 0, s[2:3]
	v_lshrrev_b32_e32 v2, 3, v0
	v_lshlrev_b32_e32 v3, 4, v0
	v_cmp_gt_u32_e64 s[8:9], s1, v0
	s_movk_i32 s1, 0x210
	s_add_u32 s37, s76, 0x300000
	v_and_b32_e32 v161, 0x70, v3
	v_mad_u32_u24 v3, v2, s1, 0
	s_addc_u32 s44, s77, 0
	s_ashr_i32 s1, s0, 31
	s_lshl_b64 s[14:15], s[60:61], 12
	s_lshl_b64 s[16:17], s[0:1], 15
	v_add_u32_e32 v162, -3, v2
	v_add_u32_e32 v163, -2, v2
	v_add_u32_e32 v164, -1, v2
	v_cndmask_b32_e64 v165, 0, v2, s[8:9]
	v_lshlrev_b32_e32 v2, 8, v2
	s_add_u32 s1, s16, s14
	v_sub_u32_e32 v2, v3, v2
	s_addc_u32 s15, s17, s15
	v_lshl_add_u32 v167, v161, 1, v2
	v_or_b32_e32 v2, 48, v1
	s_add_u32 s14, s76, s1
	v_add_u32_e32 v6, 0, v146
	v_mul_u32_u24_e32 v7, 0x110, v2
	v_and_b32_e32 v2, 16, v0
	v_lshlrev_b32_e32 v146, 4, v1
	s_addc_u32 s15, s77, s15
	v_and_b32_e32 v4, 15, v0
	v_lshl_add_u32 v166, v161, 2, v3
	v_cmp_eq_u32_e64 s[10:11], 0, v2
	v_lshl_add_u64 v[2:3], s[14:15], 0, v[146:147]
	s_mov_b64 s[14:15], 0x44b00800
	v_lshrrev_b32_e32 v5, 4, v1
	v_lshl_or_b32 v160, s60, 4, v4
	v_lshl_add_u64 v[154:155], v[2:3], 0, s[14:15]
	v_cndmask_b32_e64 v150, 0, 1.0, s[8:9]
	v_mul_u32_u24_e32 v4, 0x110, v4
	v_lshl_add_u32 v8, v160, 2, 0
	v_mul_u32_u24_e32 v5, 0x840, v5
	s_ashr_i32 s97, s96, 31
	s_mov_b32 s38, 0x3e2aaaab
	v_mbcnt_lo_u32_b32 v2, -1, 0
	v_cmp_lt_u32_e64 s[2:3], 23, v0
	v_cmp_lt_u32_e64 s[4:5], 15, v0
	v_cmp_lt_u32_e64 s[6:7], 7, v0
	v_mov_b32_e32 v151, v150
	v_mov_b32_e32 v152, v150
	v_mov_b32_e32 v153, v150
	v_cmp_gt_u32_e64 s[12:13], 16, v1
	s_lshl_b64 s[26:27], s[96:97], 15
	v_readlane_b32 s97, v254, 60
	s_mov_b64 s[28:29], 0x2000
	s_movk_i32 s1, 0x2000
	s_mov_b64 s[30:31], 0x4000
	s_movk_i32 s45, 0x4000
	s_mov_b64 s[34:35], 0x6000
	v_add_u32_e32 v168, v6, v4
	v_add_u32_e32 v169, v6, v7
	s_mov_b32 s46, 0x3f2aaaab
	v_mov_b32_e32 v170, 0x3ecc95a3
	s_mov_b32 s47, 0x3f317218
	s_mov_b32 s48, 0x7f800000
	s_mov_b32 s49, 0x33800000
	s_mov_b32 s50, 0xbe800000
	s_mov_b32 s39, 0x3e124925
	v_mov_b32_e32 v156, 0x3f317218
	v_mov_b32_e32 v171, 0x7f800000
	v_mov_b32_e32 v172, 0x7fc00000
	v_mov_b32_e32 v173, 0xff800000
	v_add_u32_e32 v174, v8, v5
	v_mbcnt_hi_u32_b32 v175, -1, v2
	s_branch .LBB0_1073

.LBB0_1464:
	s_andn2_b64 vcc, exec, s[8:9]
	s_cbranch_vccnz .LBB0_1505
	s_add_u32 s21, s76, 0x2c800000
	s_addc_u32 s37, s77, 0
	s_add_u32 s54, s76, 0x5600000
	v_lshlrev_b32_e32 v2, 4, v0
	s_addc_u32 s60, s77, 0
	v_and_b32_e32 v3, 32, v0
	v_or_b32_e32 v14, 0x2000, v2
	s_lshr_b32 s13, s14, 6
	s_ashr_i32 s39, s38, 31
	s_lshr_b32 s12, s14, 8
	v_bfe_u32 v13, v0, 2, 4
	v_bitop3_b32 v11, v2, v3, 48 bitop3:0x6c
	v_lshrrev_b32_e32 v2, 7, v14
	s_movk_i32 s5, 0x70
	s_lshl_b32 s61, s13, 10
	s_lshl_b64 s[8:9], s[38:39], 20
	v_and_or_b32 v2, v2, s5, v13
	s_add_u32 s5, s21, s8
	s_addc_u32 s10, s37, s9
	s_ashr_i32 s47, s46, 31
	s_lshl_b64 s[8:9], s[46:47], 20
	s_add_u32 s8, s54, s8
	s_addc_u32 s9, s60, s9
	v_and_b32_e32 v12, 64, v0
	v_lshrrev_b32_e32 v4, 3, v0
	s_add_u32 s50, s8, s6
	v_or_b32_e32 v3, v11, v12
	v_and_or_b32 v4, v4, 48, v13
	s_addc_u32 s51, s9, s7
	s_add_i32 s62, s61, 0
	v_lshl_or_b32 v162, v4, 12, v3
	s_add_i32 m0, s62, 0x10000
	v_lshl_or_b32 v164, v2, 12, v3
	global_load_lds_dwordx4 v162, s[50:51]
	s_add_i32 m0, s62, 0x12000
	s_add_u32 s8, s50, 0x80000
	global_load_lds_dwordx4 v164, s[50:51]
	s_addc_u32 s9, s51, 0
	s_add_i32 m0, s62, 0x14000
	v_mov_b32_e32 v163, 0
	global_load_lds_dwordx4 v162, s[8:9]
	s_add_i32 m0, s62, 0x16000
	s_add_u32 s48, s5, s6
	s_addc_u32 s49, s10, s7
	s_add_i32 s63, s62, 0x2000
	global_load_lds_dwordx4 v164, s[8:9]
	s_mov_b32 m0, s62
	s_add_u32 s6, s48, 0x80000
	global_load_lds_dwordx4 v162, s[48:49]
	s_mov_b32 m0, s63
	s_addc_u32 s7, s49, 0
	s_add_i32 s64, s62, 0x4000
	global_load_lds_dwordx4 v164, s[48:49]
	s_mov_b32 m0, s64
	s_add_i32 s65, s62, 0x6000
	global_load_lds_dwordx4 v162, s[6:7]
	s_mov_b32 m0, s65
	v_mov_b32_e32 v165, v163
	global_load_lds_dwordx4 v164, s[6:7]
	s_cmp_eq_u32 s12, 1
	s_mov_b32 s5, 0
	v_lshl_add_u64 v[8:9], s[50:51], 0, v[162:163]
	v_lshl_add_u64 v[6:7], s[50:51], 0, v[164:165]
	v_lshl_add_u64 v[2:3], s[48:49], 0, v[162:163]
	s_cselect_b64 s[6:7], -1, 0
	s_cmp_lg_u32 s12, 1
	v_lshl_add_u64 v[4:5], s[48:49], 0, v[164:165]
	s_cbranch_scc1 .LBB0_1467
	s_setprio 1
	s_barrier

.LBB0_1493:
	ds_read_b128 v[26:29], v183
	ds_read_b128 v[30:33], v183 offset:1024
	ds_read_b128 v[18:21], v183 offset:2048
	ds_read_b128 v[22:25], v183 offset:3072
	ds_read_b128 v[10:13], v184
	ds_read_b128 v[14:17], v184 offset:1024
	ds_read_b128 v[2:5], v184 offset:2048
	ds_read_b128 v[6:9], v184 offset:3072
	s_add_i32 s55, s50, 2
	s_add_u32 s51, s48, 0xfff80080
	s_addc_u32 s52, s49, -1
	s_cmp_eq_u32 s39, s50
	s_cselect_b32 s50, s33, s43
	s_cselect_b32 s53, s27, s52
	s_cselect_b32 s52, s31, s51
	s_cselect_b32 s51, s29, s47
	v_lshl_add_u64 v[210:211], s[48:49], 0, v[166:167]
	s_add_i32 m0, s62, 0xc000
	ds_read_b128 v[172:175], v185
	ds_read_b128 v[176:179], v185 offset:1024
	ds_read_b128 v[186:189], v185 offset:2048
	ds_read_b128 v[190:193], v185 offset:3072
	ds_read_b128 v[194:197], v185 offset:4096
	ds_read_b128 v[198:201], v185 offset:5120
	ds_read_b128 v[202:205], v185 offset:6144
	ds_read_b128 v[206:209], v185 offset:7168
	global_load_lds_dwordx4 v[210:211], off
	v_lshl_add_u64 v[210:211], s[48:49], 0, v[168:169]
	s_add_i32 m0, s62, 0xe000
	s_nop 0
	global_load_lds_dwordx4 v[210:211], off
	s_waitcnt vmcnt(8)
	s_waitcnt lgkmcnt(0)
	s_barrier
	s_waitcnt lgkmcnt(0)
	v_mfma_f32_16x16x128_f8f6f4 v[158:161], v[26:33], v[172:179], v[158:161]
	v_mfma_f32_16x16x128_f8f6f4 v[154:157], v[18:25], v[172:179], v[154:157]
	v_mfma_f32_16x16x128_f8f6f4 v[150:153], v[26:33], v[186:193], v[150:153]
	v_mfma_f32_16x16x128_f8f6f4 v[146:149], v[18:25], v[186:193], v[146:149]
	v_mfma_f32_16x16x128_f8f6f4 v[126:129], v[26:33], v[194:201], v[126:129]
	v_mfma_f32_16x16x128_f8f6f4 v[122:125], v[18:25], v[194:201], v[122:125]
	v_mfma_f32_16x16x128_f8f6f4 v[114:117], v[26:33], v[202:209], v[114:117]
	v_mfma_f32_16x16x128_f8f6f4 v[106:109], v[18:25], v[202:209], v[106:109]
	v_mfma_f32_16x16x128_f8f6f4 v[142:145], v[10:17], v[172:179], v[142:145]
	v_mfma_f32_16x16x128_f8f6f4 v[138:141], v[2:9], v[172:179], v[138:141]
	v_mfma_f32_16x16x128_f8f6f4 v[134:137], v[10:17], v[186:193], v[134:137]
	v_mfma_f32_16x16x128_f8f6f4 v[130:133], v[2:9], v[186:193], v[130:133]
	v_mfma_f32_16x16x128_f8f6f4 v[118:121], v[10:17], v[194:201], v[118:121]
	v_mfma_f32_16x16x128_f8f6f4 v[110:113], v[2:9], v[194:201], v[110:113]
	v_mfma_f32_16x16x128_f8f6f4 v[102:105], v[10:17], v[202:209], v[102:105]
	v_mfma_f32_16x16x128_f8f6f4 v[98:101], v[2:9], v[202:209], v[98:101]
	s_barrier
	s_add_i32 s79, s75, s61
	v_lshl_add_u64 v[172:173], s[50:51], 0, v[162:163]
	s_mov_b32 m0, s79
	ds_read_b128 v[186:189], v185 offset:16384
	ds_read_b128 v[190:193], v185 offset:17408
	ds_read_b128 v[194:197], v185 offset:18432
	ds_read_b128 v[198:201], v185 offset:19456
	ds_read_b128 v[202:205], v185 offset:20480
	ds_read_b128 v[206:209], v185 offset:21504
	ds_read_b128 v[210:213], v185 offset:22528
	ds_read_b128 v[214:217], v185 offset:23552
	global_load_lds_dwordx4 v[172:173], off
	s_add_i32 m0, s79, 0x2000
	s_add_u32 s82, s50, 0x80000
	v_lshl_add_u64 v[174:175], s[50:51], 0, v[164:165]
	s_addc_u32 s83, s51, 0
	s_add_i32 s79, s76, s61
	global_load_lds_dwordx4 v[174:175], off
	v_lshl_add_u64 v[176:177], s[82:83], 0, v[162:163]
	s_mov_b32 m0, s79
	v_lshl_add_u64 v[178:179], s[52:53], 0, v[164:165]
	global_load_lds_dwordx4 v[176:177], off
	v_lshl_add_u64 v[176:177], s[82:83], 0, v[164:165]
	s_add_i32 m0, s79, 0x2000
	s_nop 0
	global_load_lds_dwordx4 v[176:177], off
	v_lshl_add_u64 v[176:177], s[52:53], 0, v[162:163]
	s_mov_b32 m0, s62
	s_nop 0
	global_load_lds_dwordx4 v[176:177], off
	s_mov_b32 m0, s63
	s_nop 0
	global_load_lds_dwordx4 v[178:179], off
	s_waitcnt vmcnt(8)
	s_waitcnt lgkmcnt(0)
	s_barrier
	s_waitcnt lgkmcnt(0)
	v_mfma_f32_16x16x128_f8f6f4 v[94:97], v[26:33], v[186:193], v[94:97]
	v_mfma_f32_16x16x128_f8f6f4 v[90:93], v[18:25], v[186:193], v[90:93]
	v_mfma_f32_16x16x128_f8f6f4 v[82:85], v[26:33], v[194:201], v[82:85]
	v_mfma_f32_16x16x128_f8f6f4 v[74:77], v[18:25], v[194:201], v[74:77]
	v_mfma_f32_16x16x128_f8f6f4 v[66:69], v[26:33], v[202:209], v[66:69]
	v_mfma_f32_16x16x128_f8f6f4 v[58:61], v[18:25], v[202:209], v[58:61]
	v_mfma_f32_16x16x128_f8f6f4 v[50:53], v[26:33], v[210:217], v[50:53]
	v_mfma_f32_16x16x128_f8f6f4 v[42:45], v[18:25], v[210:217], v[42:45]
	v_mfma_f32_16x16x128_f8f6f4 v[86:89], v[10:17], v[186:193], v[86:89]
	v_mfma_f32_16x16x128_f8f6f4 v[78:81], v[2:9], v[186:193], v[78:81]
	v_mfma_f32_16x16x128_f8f6f4 v[70:73], v[10:17], v[194:201], v[70:73]
	v_mfma_f32_16x16x128_f8f6f4 v[62:65], v[2:9], v[194:201], v[62:65]
	v_mfma_f32_16x16x128_f8f6f4 v[54:57], v[10:17], v[202:209], v[54:57]
	v_mfma_f32_16x16x128_f8f6f4 v[46:49], v[2:9], v[202:209], v[46:49]
	v_mfma_f32_16x16x128_f8f6f4 v[38:41], v[10:17], v[210:217], v[38:41]
	v_mfma_f32_16x16x128_f8f6f4 v[34:37], v[2:9], v[210:217], v[34:37]
	s_barrier
	s_add_i32 s79, 0, 0x18000
	s_add_i32 s82, 0, 0x1c000
	v_add_u32_e32 v14, s79, v182
	v_add_u32_e32 v30, s82, v182
	ds_read_b128 v[2:5], v14
	ds_read_b128 v[6:9], v14 offset:1024
	ds_read_b128 v[10:13], v14 offset:2048
	ds_read_b128 v[14:17], v14 offset:3072
	ds_read_b128 v[18:21], v30
	ds_read_b128 v[22:25], v30 offset:1024
	ds_read_b128 v[26:29], v30 offset:2048
	ds_read_b128 v[30:33], v30 offset:3072
	s_add_u32 s52, s52, 0x80000
	s_addc_u32 s53, s53, 0
	s_mov_b32 m0, s64
	v_lshl_add_u64 v[218:219], s[52:53], 0, v[162:163]
	ds_read_b128 v[186:189], v185 offset:32768
	ds_read_b128 v[190:193], v185 offset:33792
	ds_read_b128 v[194:197], v185 offset:34816
	ds_read_b128 v[198:201], v185 offset:35840
	ds_read_b128 v[202:205], v185 offset:36864
	ds_read_b128 v[206:209], v185 offset:37888
	ds_read_b128 v[210:213], v185 offset:38912
	ds_read_b128 v[214:217], v185 offset:39936
	global_load_lds_dwordx4 v[218:219], off
	v_lshl_add_u64 v[218:219], s[52:53], 0, v[164:165]
	s_mov_b32 m0, s65
	s_nop 0
	global_load_lds_dwordx4 v[218:219], off
	s_waitcnt vmcnt(8)
	s_waitcnt lgkmcnt(0)
	s_barrier
	s_waitcnt lgkmcnt(0)
	v_mfma_f32_16x16x128_f8f6f4 v[158:161], v[2:9], v[186:193], v[158:161]
	v_mfma_f32_16x16x128_f8f6f4 v[154:157], v[10:17], v[186:193], v[154:157]
	v_mfma_f32_16x16x128_f8f6f4 v[150:153], v[2:9], v[194:201], v[150:153]
	v_mfma_f32_16x16x128_f8f6f4 v[146:149], v[10:17], v[194:201], v[146:149]
	v_mfma_f32_16x16x128_f8f6f4 v[126:129], v[2:9], v[202:209], v[126:129]
	v_mfma_f32_16x16x128_f8f6f4 v[122:125], v[10:17], v[202:209], v[122:125]
	v_mfma_f32_16x16x128_f8f6f4 v[114:117], v[2:9], v[210:217], v[114:117]
	v_mfma_f32_16x16x128_f8f6f4 v[106:109], v[10:17], v[210:217], v[106:109]
	v_mfma_f32_16x16x128_f8f6f4 v[142:145], v[18:25], v[186:193], v[142:145]
	v_mfma_f32_16x16x128_f8f6f4 v[138:141], v[26:33], v[186:193], v[138:141]
	v_mfma_f32_16x16x128_f8f6f4 v[134:137], v[18:25], v[194:201], v[134:137]
	v_mfma_f32_16x16x128_f8f6f4 v[130:133], v[26:33], v[194:201], v[130:133]
	v_mfma_f32_16x16x128_f8f6f4 v[118:121], v[18:25], v[202:209], v[118:121]
	v_mfma_f32_16x16x128_f8f6f4 v[110:113], v[26:33], v[202:209], v[110:113]
	v_mfma_f32_16x16x128_f8f6f4 v[102:105], v[18:25], v[210:217], v[102:105]
	v_mfma_f32_16x16x128_f8f6f4 v[98:101], v[26:33], v[210:217], v[98:101]
	s_barrier
	s_add_i32 s52, s79, s61
	v_lshl_add_u64 v[172:173], v[172:173], 0, s[12:13]
	s_mov_b32 m0, s52
	ds_read_b128 v[186:189], v185 offset:49152
	ds_read_b128 v[190:193], v185 offset:50176
	ds_read_b128 v[194:197], v185 offset:51200
	ds_read_b128 v[198:201], v185 offset:52224
	ds_read_b128 v[202:205], v185 offset:53248
	ds_read_b128 v[206:209], v185 offset:54272
	ds_read_b128 v[210:213], v185 offset:55296
	ds_read_b128 v[214:217], v185 offset:56320
	global_load_lds_dwordx4 v[172:173], off
	s_add_i32 m0, s52, 0x2000
	s_add_u32 s50, s50, 0x80080
	v_lshl_add_u64 v[172:173], v[174:175], 0, s[12:13]
	s_addc_u32 s51, s51, 0
	s_add_i32 s52, s82, s61
	global_load_lds_dwordx4 v[172:173], off
	v_lshl_add_u64 v[172:173], s[50:51], 0, v[162:163]
	s_mov_b32 m0, s52
	s_nop 0
	global_load_lds_dwordx4 v[172:173], off
	v_lshl_add_u64 v[172:173], s[50:51], 0, v[164:165]
	s_add_i32 m0, s52, 0x2000
	s_nop 0
	global_load_lds_dwordx4 v[172:173], off
	v_lshl_add_u64 v[172:173], v[176:177], 0, s[12:13]
	s_mov_b32 m0, s70
	s_nop 0
	global_load_lds_dwordx4 v[172:173], off
	v_lshl_add_u64 v[172:173], v[178:179], 0, s[12:13]
	s_mov_b32 m0, s71
	s_nop 0
	global_load_lds_dwordx4 v[172:173], off
	s_waitcnt vmcnt(8)
	s_waitcnt lgkmcnt(0)
	s_barrier
	s_waitcnt lgkmcnt(0)
	v_mfma_f32_16x16x128_f8f6f4 v[94:97], v[2:9], v[186:193], v[94:97]
	v_mfma_f32_16x16x128_f8f6f4 v[90:93], v[10:17], v[186:193], v[90:93]
	v_mfma_f32_16x16x128_f8f6f4 v[82:85], v[2:9], v[194:201], v[82:85]
	v_mfma_f32_16x16x128_f8f6f4 v[74:77], v[10:17], v[194:201], v[74:77]
	v_mfma_f32_16x16x128_f8f6f4 v[66:69], v[2:9], v[202:209], v[66:69]
	v_mfma_f32_16x16x128_f8f6f4 v[58:61], v[10:17], v[202:209], v[58:61]
	v_mfma_f32_16x16x128_f8f6f4 v[50:53], v[2:9], v[210:217], v[50:53]
	v_mfma_f32_16x16x128_f8f6f4 v[42:45], v[10:17], v[210:217], v[42:45]
	v_mfma_f32_16x16x128_f8f6f4 v[86:89], v[18:25], v[186:193], v[86:89]
	v_mfma_f32_16x16x128_f8f6f4 v[78:81], v[26:33], v[186:193], v[78:81]
	v_mfma_f32_16x16x128_f8f6f4 v[70:73], v[18:25], v[194:201], v[70:73]
	v_mfma_f32_16x16x128_f8f6f4 v[62:65], v[26:33], v[194:201], v[62:65]
	v_mfma_f32_16x16x128_f8f6f4 v[54:57], v[18:25], v[202:209], v[54:57]
	v_mfma_f32_16x16x128_f8f6f4 v[46:49], v[26:33], v[202:209], v[46:49]
	v_mfma_f32_16x16x128_f8f6f4 v[38:41], v[18:25], v[210:217], v[38:41]
	v_mfma_f32_16x16x128_f8f6f4 v[34:37], v[26:33], v[210:217], v[34:37]
	s_barrier
	s_add_u32 s48, s48, 0x100
	s_addc_u32 s49, s49, 0
	s_add_u32 s43, s43, 0x100
	s_addc_u32 s47, s47, 0
	s_cmp_ge_i32 s55, s42
	s_mov_b32 s50, s55
	s_cbranch_scc0 .LBB0_1493
	s_and_b64 vcc, exec, s[14:15]
	s_cbranch_vccz .LBB0_1496
	s_barrier

.LBB0_1559:
	s_setprio 0
	s_cmp_lt_i32 s52, 6
	s_cselect_b64 s[0:1], -1, 0
	s_and_b64 s[0:1], s[0:1], s[2:3]
	s_andn2_b64 vcc, exec, s[0:1]
	s_cbranch_vccnz .LBB0_1574
	s_cmpk_gt_i32 s97, 0xff
	v_mbcnt_lo_u32_b32 v44, -1, 0
	v_cmp_eq_u32_e64 s[2:3], 0, v1
	v_lshlrev_b32_e32 v34, 4, v1
	s_cbranch_scc1 .LBB0_1569
	s_add_u32 s12, s76, 0x28000
	v_readlane_b32 s5, v254, 51
	s_addc_u32 s13, s77, 0
	s_bfe_u32 s4, s5, 0x20006
	s_lshl_b32 s10, s4, 10
	v_lshlrev_b32_e32 v36, 2, v1
	s_mov_b32 s8, s62
	v_readlane_b32 s60, v254, 19
	v_or_b32_e32 v18, s10, v36
	v_readlane_b32 s62, v254, 21
	v_readlane_b32 s63, v254, 22
	v_lshlrev_b32_e32 v19, 2, v18
	s_mov_b64 s[6:7], s[62:63]
	global_load_dwordx4 v[2:5], v19, s[6:7]
	global_load_dwordx4 v[6:9], v19, s[6:7] offset:1024
	global_load_dwordx4 v[10:13], v19, s[6:7] offset:2048
	global_load_dwordx4 v[14:17], v19, s[6:7] offset:3072
	v_mbcnt_hi_u32_b32 v19, -1, v44
	v_and_b32_e32 v20, 64, v19
	v_add_u32_e32 v20, 64, v20
	v_xor_b32_e32 v21, 1, v19
	v_cmp_lt_i32_e32 vcc, v21, v20
	s_lshr_b32 s18, s5, 8
	s_lshl_b32 s5, s4, 12
	v_cndmask_b32_e32 v21, v19, v21, vcc
	v_lshlrev_b32_e32 v45, 2, v21
	v_xor_b32_e32 v21, 2, v19
	v_cmp_lt_i32_e32 vcc, v21, v20
	s_add_u32 s6, s58, s5
	s_mov_b32 s62, s8
	v_cndmask_b32_e32 v21, v19, v21, vcc
	v_lshlrev_b32_e32 v46, 2, v21
	v_xor_b32_e32 v21, 4, v19
	s_addc_u32 s7, s59, 0
	s_lshl_b32 s8, s4, 11
	v_cmp_lt_i32_e32 vcc, v21, v20
	s_add_u32 s8, s76, s8
	s_addc_u32 s9, s77, 0
	v_cndmask_b32_e32 v21, v19, v21, vcc
	v_lshlrev_b32_e32 v47, 2, v21
	v_xor_b32_e32 v21, 8, v19
	s_add_u32 s14, s8, 0x1bc00000
	v_cmp_lt_i32_e32 vcc, v21, v20
	s_addc_u32 s15, s9, 0
	s_add_u32 s8, s76, s5
	v_cndmask_b32_e32 v21, v19, v21, vcc
	v_lshlrev_b32_e32 v48, 2, v21
	v_xor_b32_e32 v21, 16, v19
	s_addc_u32 s9, s77, 0
	v_cmp_lt_i32_e32 vcc, v21, v20
	s_lshl_b32 s5, s84, 2
	s_add_i32 s16, s5, 0
	v_cndmask_b32_e32 v21, v19, v21, vcc
	s_and_b32 s5, s84, 4
	v_lshlrev_b32_e32 v49, 2, v21
	v_xor_b32_e32 v21, 32, v19
	s_lshl_b32 s5, s5, 2
	v_mov_b32_e32 v37, 0
	v_cmp_lt_i32_e32 vcc, v21, v20
	s_add_i32 s17, s5, 0
	v_mov_b32_e32 v35, v37
	v_cndmask_b32_e32 v19, v19, v21, vcc
	s_add_u32 s10, s22, s10
	v_lshl_add_u64 v[38:39], s[6:7], 0, v[34:35]
	v_lshl_add_u64 v[32:33], s[8:9], 0, v[34:35]
	s_mov_b64 s[6:7], 0x38c00000
	v_readlane_b32 s69, v254, 28
	v_lshlrev_b32_e32 v50, 2, v19
	v_or_b32_e32 v19, s4, v1
	s_addc_u32 s11, s23, 0
	v_or_b32_e32 v20, 0x100, v36
	v_or_b32_e32 v22, 0x200, v36
	v_or_b32_e32 v24, 0x300, v36
	v_or_b32_e32 v26, 0x100, v18
	v_or_b32_e32 v28, 0x200, v18
	v_or_b32_e32 v30, 0x300, v18
	v_lshl_add_u64 v[40:41], v[32:33], 0, s[6:7]
	s_lshl_b32 s6, s97, 1
	v_readlane_b32 s69, v254, 55
	s_mov_b32 s60, s84
	v_cmp_eq_u32_e64 s[4:5], 0, v19
	v_lshl_add_u64 v[42:43], s[10:11], 0, v[36:37]
	s_add_i32 s6, s18, s6
	s_lshl_b32 s18, s96, 1
	v_lshlrev_b32_e32 v35, 1, v36
	v_lshlrev_b32_e32 v36, 1, v20
	v_lshlrev_b32_e32 v51, 1, v22
	v_lshlrev_b32_e32 v52, 1, v24
	v_mov_b32_e32 v53, 0x358637bd
	v_lshlrev_b32_e32 v54, 2, v18
	v_lshlrev_b32_e32 v55, 2, v26
	v_lshlrev_b32_e32 v56, 2, v28
	v_lshlrev_b32_e32 v57, 2, v30
	s_mov_b32 s19, 0x42fe0000
	s_mov_b32 s20, 0x40c0c00
	s_mov_b32 s21, s97
	v_readlane_b32 s61, v254, 20
	v_readlane_b32 s64, v254, 23
	v_readlane_b32 s65, v254, 24
	v_readlane_b32 s66, v254, 25
	v_readlane_b32 s67, v254, 26
	v_readlane_b32 s68, v254, 27
	v_readlane_b32 s70, v254, 29
	v_readlane_b32 s71, v254, 30
	v_readlane_b32 s72, v254, 31
	v_readlane_b32 s73, v254, 32
	v_readlane_b32 s74, v254, 33
	v_readlane_b32 s75, v254, 34
	s_branch .LBB0_1563

.LBB0_1628:
	s_cmp_lt_i32 s52, 7
	s_cselect_b64 s[0:1], -1, 0
	s_and_b64 s[0:1], s[0:1], s[2:3]
	s_andn2_b64 vcc, exec, s[0:1]
	s_cbranch_vccnz .LBB0_1701
	s_add_u32 s37, s76, 0x7600000
	s_addc_u32 s40, s77, 0
	s_add_u32 s4, s76, 0x39400000
	s_addc_u32 s5, s77, 0
	v_lshlrev_b32_e32 v2, 4, v0
	v_and_b32_e32 v3, 32, v0
	s_add_u32 s41, s76, 0x28000
	v_bitop3_b32 v153, v2, v3, 48 bitop3:0x6c
	v_lshrrev_b32_e32 v3, 1, v0
	v_lshrrev_b32_e32 v4, 5, v0
	v_or_b32_e32 v151, 0x2000, v2
	s_addc_u32 s42, s77, 0
	v_bfe_u32 v149, v0, 2, 4
	v_and_b32_e32 v3, 24, v3
	v_and_b32_e32 v4, 4, v4
	v_bfe_u32 v5, v0, 2, 2
	v_lshrrev_b32_e32 v2, 7, v151
	s_movk_i32 s2, 0x70
	s_add_u32 s43, s76, 0x8000
	v_or3_b32 v3, v4, v5, v3
	v_and_or_b32 v162, v2, s2, v149
	s_movk_i32 s2, 0x60
	s_addc_u32 s44, s77, 0
	v_and_or_b32 v2, v2, s2, v3
	s_add_i32 s2, s97, 0xac
	s_and_b32 s8, s2, 0xff
	v_and_b32_e32 v155, 64, v0
	s_cmpk_eq_i32 s96, 0x100
	v_or_b32_e32 v163, v153, v155
	v_lshrrev_b32_e32 v4, 3, v0
	s_cselect_b64 s[6:7], -1, 0
	v_and_or_b32 v164, v4, 48, v149
	v_and_or_b32 v4, v4, 32, v3
	v_lshl_or_b32 v136, v2, 12, v163
	v_bfe_u32 v179, v0, 4, 2
	v_lshlrev_b32_e32 v2, 6, v0
	v_lshlrev_b32_e32 v3, 2, v0
	s_and_b64 s[2:3], s[6:7], exec
	v_lshlrev_b32_e32 v159, 4, v179
	v_and_b32_e32 v2, 0x3c0, v2
	v_and_b32_e32 v3, 32, v3
	s_cselect_b32 s13, s8, s97
	v_readfirstlane_b32 s10, v0
	v_lshl_or_b32 v130, v164, 12, v163
	v_lshl_or_b32 v132, v4, 12, v163
	v_lshl_or_b32 v134, v162, 12, v163
	v_and_b32_e32 v178, 15, v0
	s_cmpk_gt_i32 s13, 0xab
	v_bitop3_b32 v166, v159, v3, v2 bitop3:0x36
	s_mov_b32 s36, s62
	s_cbranch_scc1 .LBB0_1645
	s_mul_hi_i32 s2, s13, 0x2fa0be83
	s_lshr_b32 s3, s2, 31
	s_ashr_i32 s2, s2, 4
	s_add_i32 s2, s2, s3
	s_add_i32 s26, s2, 32
	s_mulk_i32 s2, 0x56
	s_sub_i32 s28, s13, s2
	s_lshr_b32 s8, s10, 6
	s_ashr_i32 s27, s26, 31
	s_ashr_i32 s29, s28, 31
	s_lshr_b32 s12, s10, 8
	s_lshl_b32 s45, s8, 10
	s_lshl_b64 s[2:3], s[26:27], 20
	s_lshl_b64 s[14:15], s[28:29], 20
	s_add_u32 s34, s37, s14
	s_addc_u32 s35, s40, s15
	s_add_i32 s29, s45, 0
	s_add_i32 m0, s29, 0x10000
	v_mov_b32_e32 v133, 0
	global_load_lds_dwordx4 v132, s[34:35]
	s_add_i32 m0, s29, 0x12000
	s_add_u32 s14, s34, 0x80000
	global_load_lds_dwordx4 v136, s[34:35]
	s_addc_u32 s15, s35, 0
	s_add_i32 m0, s29, 0x14000
	v_mov_b32_e32 v137, v133
	global_load_lds_dwordx4 v132, s[14:15]
	s_add_i32 m0, s29, 0x16000
	s_add_u32 s30, s22, s2
	s_addc_u32 s31, s23, s3
	s_add_i32 s46, s29, 0x2000
	global_load_lds_dwordx4 v136, s[14:15]
	s_mov_b32 m0, s29
	s_add_u32 s2, s30, 0x80000
	global_load_lds_dwordx4 v130, s[30:31]
	s_mov_b32 m0, s46
	s_addc_u32 s3, s31, 0
	s_add_i32 s47, s29, 0x4000
	global_load_lds_dwordx4 v134, s[30:31]
	s_mov_b32 m0, s47
	s_add_i32 s48, s29, 0x6000
	global_load_lds_dwordx4 v130, s[2:3]
	s_mov_b32 m0, s48
	v_mov_b32_e32 v131, v133
	global_load_lds_dwordx4 v134, s[2:3]
	v_mov_b32_e32 v135, v133
	s_cmp_eq_u32 s12, 1
	s_mov_b32 s49, 0
	v_lshl_add_u64 v[8:9], s[34:35], 0, v[132:133]
	v_lshl_add_u64 v[6:7], s[34:35], 0, v[136:137]
	v_lshl_add_u64 v[2:3], s[30:31], 0, v[130:131]
	s_cselect_b64 s[2:3], -1, 0
	s_cmp_lg_u32 s12, 1
	v_lshl_add_u64 v[4:5], s[30:31], 0, v[134:135]
	s_cbranch_scc1 .LBB0_1632
	s_setprio 1
	s_barrier

.LBB0_1638:
	ds_read_b128 v[142:145], v160
	ds_read_b128 v[168:171], v160 offset:1024
	ds_read_b128 v[172:175], v160 offset:2048
	ds_read_b128 v[180:183], v160 offset:3072
	ds_read_b128 v[184:187], v161
	ds_read_b128 v[188:191], v161 offset:1024
	ds_read_b128 v[192:195], v161 offset:2048
	ds_read_b128 v[196:199], v161 offset:3072
	s_add_u32 s34, s30, 0xfff80080
	s_addc_u32 s35, s31, -1
	s_cmp_eq_u32 s70, 28
	s_cselect_b32 s39, s15, s35
	s_cselect_b32 s38, s27, s34
	s_cselect_b32 s35, s17, s69
	s_cselect_b32 s34, s33, s68
	v_lshl_add_u64 v[146:147], s[30:31], 0, v[138:139]
	s_add_i32 m0, s29, 0xc000
	ds_read_b128 v[200:203], v165
	ds_read_b128 v[204:207], v165 offset:1024
	ds_read_b128 v[208:211], v165 offset:2048
	ds_read_b128 v[212:215], v165 offset:3072
	ds_read_b128 v[216:219], v165 offset:4096
	ds_read_b128 v[220:223], v165 offset:5120
	ds_read_b128 v[224:227], v165 offset:6144
	ds_read_b128 v[228:231], v165 offset:7168
	global_load_lds_dwordx4 v[146:147], off
	v_lshl_add_u64 v[146:147], s[30:31], 0, v[140:141]
	s_add_i32 m0, s29, 0xe000
	s_nop 0
	global_load_lds_dwordx4 v[146:147], off
	s_waitcnt vmcnt(8)
	s_waitcnt lgkmcnt(0)
	s_barrier
	s_waitcnt lgkmcnt(0)
	v_mfma_i32_16x16x64_i8 v[126:129], v[142:145], v[200:203], v[126:129]
	v_mfma_i32_16x16x64_i8 v[118:121], v[172:175], v[200:203], v[118:121]
	v_mfma_i32_16x16x64_i8 v[110:113], v[142:145], v[208:211], v[110:113]
	v_mfma_i32_16x16x64_i8 v[102:105], v[172:175], v[208:211], v[102:105]
	v_mfma_i32_16x16x64_i8 v[94:97], v[142:145], v[216:219], v[94:97]
	v_mfma_i32_16x16x64_i8 v[86:89], v[172:175], v[216:219], v[86:89]
	v_mfma_i32_16x16x64_i8 v[78:81], v[142:145], v[224:227], v[78:81]
	v_mfma_i32_16x16x64_i8 v[70:73], v[172:175], v[224:227], v[70:73]
	v_mfma_i32_16x16x64_i8 v[126:129], v[168:171], v[204:207], v[126:129]
	v_mfma_i32_16x16x64_i8 v[118:121], v[180:183], v[204:207], v[118:121]
	v_mfma_i32_16x16x64_i8 v[110:113], v[168:171], v[212:215], v[110:113]
	v_mfma_i32_16x16x64_i8 v[102:105], v[180:183], v[212:215], v[102:105]
	v_mfma_i32_16x16x64_i8 v[94:97], v[168:171], v[220:223], v[94:97]
	v_mfma_i32_16x16x64_i8 v[86:89], v[180:183], v[220:223], v[86:89]
	v_mfma_i32_16x16x64_i8 v[78:81], v[168:171], v[228:231], v[78:81]
	v_mfma_i32_16x16x64_i8 v[70:73], v[180:183], v[228:231], v[70:73]
	v_mfma_i32_16x16x64_i8 v[122:125], v[184:187], v[200:203], v[122:125]
	v_mfma_i32_16x16x64_i8 v[114:117], v[192:195], v[200:203], v[114:117]
	v_mfma_i32_16x16x64_i8 v[106:109], v[184:187], v[208:211], v[106:109]
	v_mfma_i32_16x16x64_i8 v[98:101], v[192:195], v[208:211], v[98:101]
	v_mfma_i32_16x16x64_i8 v[90:93], v[184:187], v[216:219], v[90:93]
	v_mfma_i32_16x16x64_i8 v[82:85], v[192:195], v[216:219], v[82:85]
	v_mfma_i32_16x16x64_i8 v[74:77], v[184:187], v[224:227], v[74:77]
	v_mfma_i32_16x16x64_i8 v[66:69], v[192:195], v[224:227], v[66:69]
	v_mfma_i32_16x16x64_i8 v[122:125], v[188:191], v[204:207], v[122:125]
	v_mfma_i32_16x16x64_i8 v[114:117], v[196:199], v[204:207], v[114:117]
	v_mfma_i32_16x16x64_i8 v[106:109], v[188:191], v[212:215], v[106:109]
	v_mfma_i32_16x16x64_i8 v[98:101], v[196:199], v[212:215], v[98:101]
	v_mfma_i32_16x16x64_i8 v[90:93], v[188:191], v[220:223], v[90:93]
	v_mfma_i32_16x16x64_i8 v[82:85], v[196:199], v[220:223], v[82:85]
	v_mfma_i32_16x16x64_i8 v[74:77], v[188:191], v[228:231], v[74:77]
	v_mfma_i32_16x16x64_i8 v[66:69], v[196:199], v[228:231], v[66:69]
	s_barrier
	s_add_i32 s71, s58, s45
	v_lshl_add_u64 v[146:147], s[34:35], 0, v[132:133]
	s_mov_b32 m0, s71
	ds_read_b128 v[200:203], v165 offset:16384
	ds_read_b128 v[204:207], v165 offset:17408
	ds_read_b128 v[208:211], v165 offset:18432
	ds_read_b128 v[212:215], v165 offset:19456
	ds_read_b128 v[216:219], v165 offset:20480
	ds_read_b128 v[220:223], v165 offset:21504
	ds_read_b128 v[224:227], v165 offset:22528
	ds_read_b128 v[228:231], v165 offset:23552
	global_load_lds_dwordx4 v[146:147], off
	s_add_i32 m0, s71, 0x2000
	s_add_u32 s72, s34, 0x80000
	v_lshl_add_u64 v[156:157], s[34:35], 0, v[136:137]
	s_addc_u32 s73, s35, 0
	s_add_i32 s71, s59, s45
	global_load_lds_dwordx4 v[156:157], off
	v_lshl_add_u64 v[176:177], s[72:73], 0, v[132:133]
	s_mov_b32 m0, s71
	v_lshl_add_u64 v[232:233], s[38:39], 0, v[134:135]
	global_load_lds_dwordx4 v[176:177], off
	v_lshl_add_u64 v[176:177], s[72:73], 0, v[136:137]
	s_add_i32 m0, s71, 0x2000
	s_nop 0
	global_load_lds_dwordx4 v[176:177], off
	v_lshl_add_u64 v[176:177], s[38:39], 0, v[130:131]
	s_mov_b32 m0, s29
	s_nop 0
	global_load_lds_dwordx4 v[176:177], off
	s_mov_b32 m0, s46
	s_nop 0
	global_load_lds_dwordx4 v[232:233], off
	s_waitcnt vmcnt(8)
	s_waitcnt lgkmcnt(0)
	s_barrier
	s_waitcnt lgkmcnt(0)
	v_mfma_i32_16x16x64_i8 v[62:65], v[142:145], v[200:203], v[62:65]
	v_mfma_i32_16x16x64_i8 v[54:57], v[172:175], v[200:203], v[54:57]
	v_mfma_i32_16x16x64_i8 v[46:49], v[142:145], v[208:211], v[46:49]
	v_mfma_i32_16x16x64_i8 v[38:41], v[172:175], v[208:211], v[38:41]
	v_mfma_i32_16x16x64_i8 v[30:33], v[142:145], v[216:219], v[30:33]
	v_mfma_i32_16x16x64_i8 v[22:25], v[172:175], v[216:219], v[22:25]
	v_mfma_i32_16x16x64_i8 v[14:17], v[142:145], v[224:227], v[14:17]
	v_mfma_i32_16x16x64_i8 v[6:9], v[172:175], v[224:227], v[6:9]
	v_mfma_i32_16x16x64_i8 v[62:65], v[168:171], v[204:207], v[62:65]
	v_mfma_i32_16x16x64_i8 v[54:57], v[180:183], v[204:207], v[54:57]
	v_mfma_i32_16x16x64_i8 v[46:49], v[168:171], v[212:215], v[46:49]
	v_mfma_i32_16x16x64_i8 v[38:41], v[180:183], v[212:215], v[38:41]
	v_mfma_i32_16x16x64_i8 v[30:33], v[168:171], v[220:223], v[30:33]
	v_mfma_i32_16x16x64_i8 v[22:25], v[180:183], v[220:223], v[22:25]
	v_mfma_i32_16x16x64_i8 v[14:17], v[168:171], v[228:231], v[14:17]
	v_mfma_i32_16x16x64_i8 v[6:9], v[180:183], v[228:231], v[6:9]
	v_mfma_i32_16x16x64_i8 v[58:61], v[184:187], v[200:203], v[58:61]
	v_mfma_i32_16x16x64_i8 v[50:53], v[192:195], v[200:203], v[50:53]
	v_mfma_i32_16x16x64_i8 v[42:45], v[184:187], v[208:211], v[42:45]
	v_mfma_i32_16x16x64_i8 v[34:37], v[192:195], v[208:211], v[34:37]
	v_mfma_i32_16x16x64_i8 v[26:29], v[184:187], v[216:219], v[26:29]
	v_mfma_i32_16x16x64_i8 v[18:21], v[192:195], v[216:219], v[18:21]
	v_mfma_i32_16x16x64_i8 v[10:13], v[184:187], v[224:227], v[10:13]
	v_mfma_i32_16x16x64_i8 v[2:5], v[192:195], v[224:227], v[2:5]
	v_mfma_i32_16x16x64_i8 v[58:61], v[188:191], v[204:207], v[58:61]
	v_mfma_i32_16x16x64_i8 v[50:53], v[196:199], v[204:207], v[50:53]
	v_mfma_i32_16x16x64_i8 v[42:45], v[188:191], v[212:215], v[42:45]
	v_mfma_i32_16x16x64_i8 v[34:37], v[196:199], v[212:215], v[34:37]
	v_mfma_i32_16x16x64_i8 v[26:29], v[188:191], v[220:223], v[26:29]
	v_mfma_i32_16x16x64_i8 v[18:21], v[196:199], v[220:223], v[18:21]
	v_mfma_i32_16x16x64_i8 v[10:13], v[188:191], v[228:231], v[10:13]
	v_mfma_i32_16x16x64_i8 v[2:5], v[196:199], v[228:231], v[2:5]
	s_barrier
	s_add_i32 s71, 0, 0x18000
	v_add_u32_e32 v148, s71, v158
	s_add_i32 s72, 0, 0x1c000
	ds_read_b128 v[142:145], v148
	ds_read_b128 v[168:171], v148 offset:1024
	ds_read_b128 v[172:175], v148 offset:2048
	ds_read_b128 v[180:183], v148 offset:3072
	v_add_u32_e32 v148, s72, v158
	ds_read_b128 v[184:187], v148
	ds_read_b128 v[188:191], v148 offset:1024
	ds_read_b128 v[192:195], v148 offset:2048
	ds_read_b128 v[196:199], v148 offset:3072
	s_add_u32 s38, s38, 0x80000
	s_addc_u32 s39, s39, 0
	s_mov_b32 m0, s47
	v_lshl_add_u64 v[234:235], s[38:39], 0, v[130:131]
	ds_read_b128 v[200:203], v165 offset:32768
	ds_read_b128 v[204:207], v165 offset:33792
	ds_read_b128 v[208:211], v165 offset:34816
	ds_read_b128 v[212:215], v165 offset:35840
	ds_read_b128 v[216:219], v165 offset:36864
	ds_read_b128 v[220:223], v165 offset:37888
	ds_read_b128 v[224:227], v165 offset:38912
	ds_read_b128 v[228:231], v165 offset:39936
	global_load_lds_dwordx4 v[234:235], off
	v_lshl_add_u64 v[234:235], s[38:39], 0, v[134:135]
	s_mov_b32 m0, s48
	s_nop 0
	global_load_lds_dwordx4 v[234:235], off
	s_waitcnt vmcnt(8)
	s_waitcnt lgkmcnt(0)
	s_barrier
	s_waitcnt lgkmcnt(0)
	v_mfma_i32_16x16x64_i8 v[126:129], v[142:145], v[200:203], v[126:129]
	v_mfma_i32_16x16x64_i8 v[118:121], v[172:175], v[200:203], v[118:121]
	v_mfma_i32_16x16x64_i8 v[110:113], v[142:145], v[208:211], v[110:113]
	v_mfma_i32_16x16x64_i8 v[102:105], v[172:175], v[208:211], v[102:105]
	v_mfma_i32_16x16x64_i8 v[94:97], v[142:145], v[216:219], v[94:97]
	v_mfma_i32_16x16x64_i8 v[86:89], v[172:175], v[216:219], v[86:89]
	v_mfma_i32_16x16x64_i8 v[78:81], v[142:145], v[224:227], v[78:81]
	v_mfma_i32_16x16x64_i8 v[70:73], v[172:175], v[224:227], v[70:73]
	v_mfma_i32_16x16x64_i8 v[126:129], v[168:171], v[204:207], v[126:129]
	v_mfma_i32_16x16x64_i8 v[118:121], v[180:183], v[204:207], v[118:121]
	v_mfma_i32_16x16x64_i8 v[110:113], v[168:171], v[212:215], v[110:113]
	v_mfma_i32_16x16x64_i8 v[102:105], v[180:183], v[212:215], v[102:105]
	v_mfma_i32_16x16x64_i8 v[94:97], v[168:171], v[220:223], v[94:97]
	v_mfma_i32_16x16x64_i8 v[86:89], v[180:183], v[220:223], v[86:89]
	v_mfma_i32_16x16x64_i8 v[78:81], v[168:171], v[228:231], v[78:81]
	v_mfma_i32_16x16x64_i8 v[70:73], v[180:183], v[228:231], v[70:73]
	v_mfma_i32_16x16x64_i8 v[122:125], v[184:187], v[200:203], v[122:125]
	v_mfma_i32_16x16x64_i8 v[114:117], v[192:195], v[200:203], v[114:117]
	v_mfma_i32_16x16x64_i8 v[106:109], v[184:187], v[208:211], v[106:109]
	v_mfma_i32_16x16x64_i8 v[98:101], v[192:195], v[208:211], v[98:101]
	v_mfma_i32_16x16x64_i8 v[90:93], v[184:187], v[216:219], v[90:93]
	v_mfma_i32_16x16x64_i8 v[82:85], v[192:195], v[216:219], v[82:85]
	v_mfma_i32_16x16x64_i8 v[74:77], v[184:187], v[224:227], v[74:77]
	v_mfma_i32_16x16x64_i8 v[66:69], v[192:195], v[224:227], v[66:69]
	v_mfma_i32_16x16x64_i8 v[122:125], v[188:191], v[204:207], v[122:125]
	v_mfma_i32_16x16x64_i8 v[114:117], v[196:199], v[204:207], v[114:117]
	v_mfma_i32_16x16x64_i8 v[106:109], v[188:191], v[212:215], v[106:109]
	v_mfma_i32_16x16x64_i8 v[98:101], v[196:199], v[212:215], v[98:101]
	v_mfma_i32_16x16x64_i8 v[90:93], v[188:191], v[220:223], v[90:93]
	v_mfma_i32_16x16x64_i8 v[82:85], v[196:199], v[220:223], v[82:85]
	v_mfma_i32_16x16x64_i8 v[74:77], v[188:191], v[228:231], v[74:77]
	v_mfma_i32_16x16x64_i8 v[66:69], v[196:199], v[228:231], v[66:69]
	s_barrier
	s_add_i32 s38, s71, s45
	v_lshl_add_u64 v[146:147], v[146:147], 0, s[8:9]
	s_mov_b32 m0, s38
	ds_read_b128 v[200:203], v165 offset:49152
	ds_read_b128 v[204:207], v165 offset:50176
	ds_read_b128 v[208:211], v165 offset:51200
	ds_read_b128 v[212:215], v165 offset:52224
	ds_read_b128 v[216:219], v165 offset:53248
	ds_read_b128 v[220:223], v165 offset:54272
	ds_read_b128 v[224:227], v165 offset:55296
	ds_read_b128 v[228:231], v165 offset:56320
	global_load_lds_dwordx4 v[146:147], off
	s_add_i32 m0, s38, 0x2000
	s_add_u32 s34, s34, 0x80080
	v_lshl_add_u64 v[146:147], v[156:157], 0, s[8:9]
	s_addc_u32 s35, s35, 0
	s_add_i32 s38, s72, s45
	global_load_lds_dwordx4 v[146:147], off
	v_lshl_add_u64 v[146:147], s[34:35], 0, v[132:133]
	s_mov_b32 m0, s38
	s_nop 0
	global_load_lds_dwordx4 v[146:147], off
	v_lshl_add_u64 v[146:147], s[34:35], 0, v[136:137]
	s_add_i32 m0, s38, 0x2000
	s_nop 0
	global_load_lds_dwordx4 v[146:147], off
	v_lshl_add_u64 v[146:147], v[176:177], 0, s[8:9]
	s_mov_b32 m0, s52
	s_nop 0
	global_load_lds_dwordx4 v[146:147], off
	v_lshl_add_u64 v[146:147], v[232:233], 0, s[8:9]
	s_mov_b32 m0, s53
	s_nop 0
	global_load_lds_dwordx4 v[146:147], off
	s_waitcnt vmcnt(8)
	s_waitcnt lgkmcnt(0)
	s_barrier
	s_waitcnt lgkmcnt(0)
	v_mfma_i32_16x16x64_i8 v[62:65], v[142:145], v[200:203], v[62:65]
	v_mfma_i32_16x16x64_i8 v[54:57], v[172:175], v[200:203], v[54:57]
	v_mfma_i32_16x16x64_i8 v[46:49], v[142:145], v[208:211], v[46:49]
	v_mfma_i32_16x16x64_i8 v[38:41], v[172:175], v[208:211], v[38:41]
	v_mfma_i32_16x16x64_i8 v[30:33], v[142:145], v[216:219], v[30:33]
	v_mfma_i32_16x16x64_i8 v[22:25], v[172:175], v[216:219], v[22:25]
	v_mfma_i32_16x16x64_i8 v[14:17], v[142:145], v[224:227], v[14:17]
	v_mfma_i32_16x16x64_i8 v[6:9], v[172:175], v[224:227], v[6:9]
	v_mfma_i32_16x16x64_i8 v[62:65], v[168:171], v[204:207], v[62:65]
	v_mfma_i32_16x16x64_i8 v[54:57], v[180:183], v[204:207], v[54:57]
	v_mfma_i32_16x16x64_i8 v[46:49], v[168:171], v[212:215], v[46:49]
	v_mfma_i32_16x16x64_i8 v[38:41], v[180:183], v[212:215], v[38:41]
	v_mfma_i32_16x16x64_i8 v[30:33], v[168:171], v[220:223], v[30:33]
	v_mfma_i32_16x16x64_i8 v[22:25], v[180:183], v[220:223], v[22:25]
	v_mfma_i32_16x16x64_i8 v[14:17], v[168:171], v[228:231], v[14:17]
	v_mfma_i32_16x16x64_i8 v[6:9], v[180:183], v[228:231], v[6:9]
	v_mfma_i32_16x16x64_i8 v[58:61], v[184:187], v[200:203], v[58:61]
	v_mfma_i32_16x16x64_i8 v[50:53], v[192:195], v[200:203], v[50:53]
	v_mfma_i32_16x16x64_i8 v[42:45], v[184:187], v[208:211], v[42:45]
	v_mfma_i32_16x16x64_i8 v[34:37], v[192:195], v[208:211], v[34:37]
	v_mfma_i32_16x16x64_i8 v[26:29], v[184:187], v[216:219], v[26:29]
	v_mfma_i32_16x16x64_i8 v[18:21], v[192:195], v[216:219], v[18:21]
	v_mfma_i32_16x16x64_i8 v[10:13], v[184:187], v[224:227], v[10:13]
	v_mfma_i32_16x16x64_i8 v[2:5], v[192:195], v[224:227], v[2:5]
	v_mfma_i32_16x16x64_i8 v[58:61], v[188:191], v[204:207], v[58:61]
	v_mfma_i32_16x16x64_i8 v[50:53], v[196:199], v[204:207], v[50:53]
	v_mfma_i32_16x16x64_i8 v[42:45], v[188:191], v[212:215], v[42:45]
	v_mfma_i32_16x16x64_i8 v[34:37], v[196:199], v[212:215], v[34:37]
	v_mfma_i32_16x16x64_i8 v[26:29], v[188:191], v[220:223], v[26:29]
	v_mfma_i32_16x16x64_i8 v[18:21], v[196:199], v[220:223], v[18:21]
	v_mfma_i32_16x16x64_i8 v[10:13], v[188:191], v[228:231], v[10:13]
	v_mfma_i32_16x16x64_i8 v[2:5], v[196:199], v[228:231], v[2:5]
	s_barrier
	s_add_i32 s70, s70, 2
	s_add_u32 s30, s30, 0x100
	s_addc_u32 s31, s31, 0
	s_add_u32 s68, s68, 0x100
	s_addc_u32 s69, s69, 0
	s_cmp_gt_u32 s70, 29
	s_cbranch_scc0 .LBB0_1638
	s_and_b64 vcc, exec, s[10:11]
	s_cbranch_vccz .LBB0_1641
	s_barrier

.LBB0_1648:
	s_or_b64 exec, exec, s[2:3]
	s_cmpk_gt_i32 s97, 0xabf
	v_readfirstlane_b32 s12, v0
	s_cbranch_scc1 .LBB0_1664
	s_ashr_i32 s38, s97, 31
	s_lshr_b32 s2, s38, 29
	s_add_i32 s2, s97, s2
	s_lshr_b32 s10, s12, 6
	s_ashr_i32 s8, s2, 3
	s_and_b32 s2, s2, -8
	s_lshr_b32 s3, s12, 8
	s_lshl_b32 s15, s10, 10
	s_sub_i32 s2, s97, s2
	s_cmp_lt_i32 s2, 0
	s_movk_i32 s39, 0x159
	s_cselect_b32 s9, s39, 0x158
	s_mul_i32 s2, s2, s9
	s_add_i32 s2, s2, s8
	s_mul_hi_i32 s8, s2, 0x2fa0be83
	s_lshr_b32 s9, s8, 31
	s_ashr_i32 s8, s8, 7
	s_add_i32 s8, s8, s9
	s_lshl_b32 s9, s8, 3
	s_mulk_i32 s8, 0x2b0
	s_sub_i32 s8, s2, s8
	s_sext_i32_i16 s2, s8
	s_bfe_u32 s2, s2, 0x3001c
	s_add_i32 s11, s8, s2
	s_sext_i32_i16 s2, s11
	s_and_b32 s11, s11, 0xfff8
	s_sub_i32 s8, s8, s11
	s_sext_i32_i16 s8, s8
	s_lshr_b32 s2, s2, 3
	s_add_i32 s26, s9, s8
	s_ashr_i32 s27, s26, 31
	s_bfe_i64 s[16:17], s[2:3], 0x100000
	s_lshl_b64 s[8:9], s[26:27], 20
	s_lshl_b64 s[16:17], s[16:17], 20
	s_add_u32 s30, s37, s16
	s_addc_u32 s31, s40, s17
	s_add_i32 s45, s15, 0
	s_add_i32 m0, s45, 0x10000
	v_mov_b32_e32 v133, 0
	global_load_lds_dwordx4 v132, s[30:31]
	s_add_i32 m0, s45, 0x12000
	s_add_u32 s16, s30, 0x80000
	global_load_lds_dwordx4 v136, s[30:31]
	s_addc_u32 s17, s31, 0
	s_add_i32 m0, s45, 0x14000
	v_mov_b32_e32 v137, v133
	global_load_lds_dwordx4 v132, s[16:17]
	s_add_i32 m0, s45, 0x16000
	s_add_u32 s28, s22, s8
	s_addc_u32 s29, s23, s9
	s_add_i32 s46, s45, 0x2000
	global_load_lds_dwordx4 v136, s[16:17]
	s_mov_b32 m0, s45
	s_add_u32 s8, s28, 0x80000
	global_load_lds_dwordx4 v130, s[28:29]
	s_mov_b32 m0, s46
	s_addc_u32 s9, s29, 0
	s_add_i32 s47, s45, 0x4000
	global_load_lds_dwordx4 v134, s[28:29]
	s_mov_b32 m0, s47
	s_add_i32 s48, s45, 0x6000
	global_load_lds_dwordx4 v130, s[8:9]
	s_mov_b32 m0, s48
	v_mov_b32_e32 v131, v133
	global_load_lds_dwordx4 v134, s[8:9]
	v_mov_b32_e32 v135, v133
	s_cmp_eq_u32 s3, 1
	s_mov_b32 s49, 0
	v_lshl_add_u64 v[8:9], s[30:31], 0, v[132:133]
	v_lshl_add_u64 v[6:7], s[30:31], 0, v[136:137]
	v_lshl_add_u64 v[2:3], s[28:29], 0, v[130:131]
	s_cselect_b64 s[8:9], -1, 0
	s_cmp_lg_u32 s3, 1
	v_lshl_add_u64 v[4:5], s[28:29], 0, v[134:135]
	s_cbranch_scc1 .LBB0_1651
	s_setprio 1
	s_barrier

.LBB0_1657:
	ds_read_b128 v[146:149], v165
	ds_read_b128 v[170:173], v165 offset:1024
	ds_read_b128 v[174:177], v165 offset:2048
	ds_read_b128 v[180:183], v165 offset:3072
	ds_read_b128 v[184:187], v167
	ds_read_b128 v[188:191], v167 offset:1024
	ds_read_b128 v[192:195], v167 offset:2048
	ds_read_b128 v[196:199], v167 offset:3072
	s_add_u32 s30, s28, 0xfff80080
	s_addc_u32 s31, s29, -1
	s_cmp_eq_u32 s68, 28
	s_cselect_b32 s35, s19, s31
	s_cselect_b32 s34, s27, s30
	s_cselect_b32 s31, s17, s67
	s_cselect_b32 s30, s65, s66
	v_lshl_add_u64 v[150:151], s[28:29], 0, v[138:139]
	s_add_i32 m0, s45, 0xc000
	ds_read_b128 v[200:203], v168
	ds_read_b128 v[204:207], v168 offset:1024
	ds_read_b128 v[208:211], v168 offset:2048
	ds_read_b128 v[212:215], v168 offset:3072
	ds_read_b128 v[216:219], v168 offset:4096
	ds_read_b128 v[220:223], v168 offset:5120
	ds_read_b128 v[224:227], v168 offset:6144
	ds_read_b128 v[228:231], v168 offset:7168
	global_load_lds_dwordx4 v[150:151], off
	v_lshl_add_u64 v[150:151], s[28:29], 0, v[140:141]
	s_add_i32 m0, s45, 0xe000
	s_nop 0
	global_load_lds_dwordx4 v[150:151], off
	s_waitcnt vmcnt(8)
	s_waitcnt lgkmcnt(0)
	s_barrier
	s_waitcnt lgkmcnt(0)
	v_mfma_i32_16x16x64_i8 v[126:129], v[146:149], v[200:203], v[126:129]
	v_mfma_i32_16x16x64_i8 v[118:121], v[174:177], v[200:203], v[118:121]
	v_mfma_i32_16x16x64_i8 v[110:113], v[146:149], v[208:211], v[110:113]
	v_mfma_i32_16x16x64_i8 v[102:105], v[174:177], v[208:211], v[102:105]
	v_mfma_i32_16x16x64_i8 v[94:97], v[146:149], v[216:219], v[94:97]
	v_mfma_i32_16x16x64_i8 v[86:89], v[174:177], v[216:219], v[86:89]
	v_mfma_i32_16x16x64_i8 v[78:81], v[146:149], v[224:227], v[78:81]
	v_mfma_i32_16x16x64_i8 v[70:73], v[174:177], v[224:227], v[70:73]
	v_mfma_i32_16x16x64_i8 v[126:129], v[170:173], v[204:207], v[126:129]
	v_mfma_i32_16x16x64_i8 v[118:121], v[180:183], v[204:207], v[118:121]
	v_mfma_i32_16x16x64_i8 v[110:113], v[170:173], v[212:215], v[110:113]
	v_mfma_i32_16x16x64_i8 v[102:105], v[180:183], v[212:215], v[102:105]
	v_mfma_i32_16x16x64_i8 v[94:97], v[170:173], v[220:223], v[94:97]
	v_mfma_i32_16x16x64_i8 v[86:89], v[180:183], v[220:223], v[86:89]
	v_mfma_i32_16x16x64_i8 v[78:81], v[170:173], v[228:231], v[78:81]
	v_mfma_i32_16x16x64_i8 v[70:73], v[180:183], v[228:231], v[70:73]
	v_mfma_i32_16x16x64_i8 v[122:125], v[184:187], v[200:203], v[122:125]
	v_mfma_i32_16x16x64_i8 v[114:117], v[192:195], v[200:203], v[114:117]
	v_mfma_i32_16x16x64_i8 v[106:109], v[184:187], v[208:211], v[106:109]
	v_mfma_i32_16x16x64_i8 v[98:101], v[192:195], v[208:211], v[98:101]
	v_mfma_i32_16x16x64_i8 v[90:93], v[184:187], v[216:219], v[90:93]
	v_mfma_i32_16x16x64_i8 v[82:85], v[192:195], v[216:219], v[82:85]
	v_mfma_i32_16x16x64_i8 v[74:77], v[184:187], v[224:227], v[74:77]
	v_mfma_i32_16x16x64_i8 v[66:69], v[192:195], v[224:227], v[66:69]
	v_mfma_i32_16x16x64_i8 v[122:125], v[188:191], v[204:207], v[122:125]
	v_mfma_i32_16x16x64_i8 v[114:117], v[196:199], v[204:207], v[114:117]
	v_mfma_i32_16x16x64_i8 v[106:109], v[188:191], v[212:215], v[106:109]
	v_mfma_i32_16x16x64_i8 v[98:101], v[196:199], v[212:215], v[98:101]
	v_mfma_i32_16x16x64_i8 v[90:93], v[188:191], v[220:223], v[90:93]
	v_mfma_i32_16x16x64_i8 v[82:85], v[196:199], v[220:223], v[82:85]
	v_mfma_i32_16x16x64_i8 v[74:77], v[188:191], v[228:231], v[74:77]
	v_mfma_i32_16x16x64_i8 v[66:69], v[196:199], v[228:231], v[66:69]
	s_barrier
	s_add_i32 s69, s55, s15
	v_lshl_add_u64 v[150:151], s[30:31], 0, v[132:133]
	s_mov_b32 m0, s69
	ds_read_b128 v[200:203], v168 offset:16384
	ds_read_b128 v[204:207], v168 offset:17408
	ds_read_b128 v[208:211], v168 offset:18432
	ds_read_b128 v[212:215], v168 offset:19456
	ds_read_b128 v[216:219], v168 offset:20480
	ds_read_b128 v[220:223], v168 offset:21504
	ds_read_b128 v[224:227], v168 offset:22528
	ds_read_b128 v[228:231], v168 offset:23552
	global_load_lds_dwordx4 v[150:151], off
	s_add_i32 m0, s69, 0x2000
	s_add_u32 s70, s30, 0x80000
	v_lshl_add_u64 v[160:161], s[30:31], 0, v[136:137]
	s_addc_u32 s71, s31, 0
	s_add_i32 s69, s56, s15
	global_load_lds_dwordx4 v[160:161], off
	v_lshl_add_u64 v[232:233], s[70:71], 0, v[132:133]
	s_mov_b32 m0, s69
	v_lshl_add_u64 v[234:235], s[34:35], 0, v[134:135]
	global_load_lds_dwordx4 v[232:233], off
	v_lshl_add_u64 v[232:233], s[70:71], 0, v[136:137]
	s_add_i32 m0, s69, 0x2000
	s_nop 0
	global_load_lds_dwordx4 v[232:233], off
	v_lshl_add_u64 v[232:233], s[34:35], 0, v[130:131]
	s_mov_b32 m0, s45
	s_nop 0
	global_load_lds_dwordx4 v[232:233], off
	s_mov_b32 m0, s46
	s_nop 0
	global_load_lds_dwordx4 v[234:235], off
	s_waitcnt vmcnt(8)
	s_waitcnt lgkmcnt(0)
	s_barrier
	s_waitcnt lgkmcnt(0)
	v_mfma_i32_16x16x64_i8 v[62:65], v[146:149], v[200:203], v[62:65]
	v_mfma_i32_16x16x64_i8 v[54:57], v[174:177], v[200:203], v[54:57]
	v_mfma_i32_16x16x64_i8 v[46:49], v[146:149], v[208:211], v[46:49]
	v_mfma_i32_16x16x64_i8 v[38:41], v[174:177], v[208:211], v[38:41]
	v_mfma_i32_16x16x64_i8 v[30:33], v[146:149], v[216:219], v[30:33]
	v_mfma_i32_16x16x64_i8 v[22:25], v[174:177], v[216:219], v[22:25]
	v_mfma_i32_16x16x64_i8 v[14:17], v[146:149], v[224:227], v[14:17]
	v_mfma_i32_16x16x64_i8 v[6:9], v[174:177], v[224:227], v[6:9]
	v_mfma_i32_16x16x64_i8 v[62:65], v[170:173], v[204:207], v[62:65]
	v_mfma_i32_16x16x64_i8 v[54:57], v[180:183], v[204:207], v[54:57]
	v_mfma_i32_16x16x64_i8 v[46:49], v[170:173], v[212:215], v[46:49]
	v_mfma_i32_16x16x64_i8 v[38:41], v[180:183], v[212:215], v[38:41]
	v_mfma_i32_16x16x64_i8 v[30:33], v[170:173], v[220:223], v[30:33]
	v_mfma_i32_16x16x64_i8 v[22:25], v[180:183], v[220:223], v[22:25]
	v_mfma_i32_16x16x64_i8 v[14:17], v[170:173], v[228:231], v[14:17]
	v_mfma_i32_16x16x64_i8 v[6:9], v[180:183], v[228:231], v[6:9]
	v_mfma_i32_16x16x64_i8 v[58:61], v[184:187], v[200:203], v[58:61]
	v_mfma_i32_16x16x64_i8 v[50:53], v[192:195], v[200:203], v[50:53]
	v_mfma_i32_16x16x64_i8 v[42:45], v[184:187], v[208:211], v[42:45]
	v_mfma_i32_16x16x64_i8 v[34:37], v[192:195], v[208:211], v[34:37]
	v_mfma_i32_16x16x64_i8 v[26:29], v[184:187], v[216:219], v[26:29]
	v_mfma_i32_16x16x64_i8 v[18:21], v[192:195], v[216:219], v[18:21]
	v_mfma_i32_16x16x64_i8 v[10:13], v[184:187], v[224:227], v[10:13]
	v_mfma_i32_16x16x64_i8 v[2:5], v[192:195], v[224:227], v[2:5]
	v_mfma_i32_16x16x64_i8 v[58:61], v[188:191], v[204:207], v[58:61]
	v_mfma_i32_16x16x64_i8 v[50:53], v[196:199], v[204:207], v[50:53]
	v_mfma_i32_16x16x64_i8 v[42:45], v[188:191], v[212:215], v[42:45]
	v_mfma_i32_16x16x64_i8 v[34:37], v[196:199], v[212:215], v[34:37]
	v_mfma_i32_16x16x64_i8 v[26:29], v[188:191], v[220:223], v[26:29]
	v_mfma_i32_16x16x64_i8 v[18:21], v[196:199], v[220:223], v[18:21]
	v_mfma_i32_16x16x64_i8 v[10:13], v[188:191], v[228:231], v[10:13]
	v_mfma_i32_16x16x64_i8 v[2:5], v[196:199], v[228:231], v[2:5]
	s_barrier
	s_add_i32 s69, 0, 0x18000
	v_add_u32_e32 v152, s69, v157
	s_add_i32 s70, 0, 0x1c000
	ds_read_b128 v[146:149], v152
	ds_read_b128 v[170:173], v152 offset:1024
	ds_read_b128 v[174:177], v152 offset:2048
	ds_read_b128 v[180:183], v152 offset:3072
	v_add_u32_e32 v152, s70, v157
	ds_read_b128 v[184:187], v152
	ds_read_b128 v[188:191], v152 offset:1024
	ds_read_b128 v[192:195], v152 offset:2048
	ds_read_b128 v[196:199], v152 offset:3072
	s_add_u32 s34, s34, 0x80000
	s_addc_u32 s35, s35, 0
	s_mov_b32 m0, s47
	v_lshl_add_u64 v[236:237], s[34:35], 0, v[130:131]
	ds_read_b128 v[200:203], v168 offset:32768
	ds_read_b128 v[204:207], v168 offset:33792
	ds_read_b128 v[208:211], v168 offset:34816
	ds_read_b128 v[212:215], v168 offset:35840
	ds_read_b128 v[216:219], v168 offset:36864
	ds_read_b128 v[220:223], v168 offset:37888
	ds_read_b128 v[224:227], v168 offset:38912
	ds_read_b128 v[228:231], v168 offset:39936
	global_load_lds_dwordx4 v[236:237], off
	v_lshl_add_u64 v[236:237], s[34:35], 0, v[134:135]
	s_mov_b32 m0, s48
	s_nop 0
	global_load_lds_dwordx4 v[236:237], off
	s_waitcnt vmcnt(8)
	s_waitcnt lgkmcnt(0)
	s_barrier
	s_waitcnt lgkmcnt(0)
	v_mfma_i32_16x16x64_i8 v[126:129], v[146:149], v[200:203], v[126:129]
	v_mfma_i32_16x16x64_i8 v[118:121], v[174:177], v[200:203], v[118:121]
	v_mfma_i32_16x16x64_i8 v[110:113], v[146:149], v[208:211], v[110:113]
	v_mfma_i32_16x16x64_i8 v[102:105], v[174:177], v[208:211], v[102:105]
	v_mfma_i32_16x16x64_i8 v[94:97], v[146:149], v[216:219], v[94:97]
	v_mfma_i32_16x16x64_i8 v[86:89], v[174:177], v[216:219], v[86:89]
	v_mfma_i32_16x16x64_i8 v[78:81], v[146:149], v[224:227], v[78:81]
	v_mfma_i32_16x16x64_i8 v[70:73], v[174:177], v[224:227], v[70:73]
	v_mfma_i32_16x16x64_i8 v[126:129], v[170:173], v[204:207], v[126:129]
	v_mfma_i32_16x16x64_i8 v[118:121], v[180:183], v[204:207], v[118:121]
	v_mfma_i32_16x16x64_i8 v[110:113], v[170:173], v[212:215], v[110:113]
	v_mfma_i32_16x16x64_i8 v[102:105], v[180:183], v[212:215], v[102:105]
	v_mfma_i32_16x16x64_i8 v[94:97], v[170:173], v[220:223], v[94:97]
	v_mfma_i32_16x16x64_i8 v[86:89], v[180:183], v[220:223], v[86:89]
	v_mfma_i32_16x16x64_i8 v[78:81], v[170:173], v[228:231], v[78:81]
	v_mfma_i32_16x16x64_i8 v[70:73], v[180:183], v[228:231], v[70:73]
	v_mfma_i32_16x16x64_i8 v[122:125], v[184:187], v[200:203], v[122:125]
	v_mfma_i32_16x16x64_i8 v[114:117], v[192:195], v[200:203], v[114:117]
	v_mfma_i32_16x16x64_i8 v[106:109], v[184:187], v[208:211], v[106:109]
	v_mfma_i32_16x16x64_i8 v[98:101], v[192:195], v[208:211], v[98:101]
	v_mfma_i32_16x16x64_i8 v[90:93], v[184:187], v[216:219], v[90:93]
	v_mfma_i32_16x16x64_i8 v[82:85], v[192:195], v[216:219], v[82:85]
	v_mfma_i32_16x16x64_i8 v[74:77], v[184:187], v[224:227], v[74:77]
	v_mfma_i32_16x16x64_i8 v[66:69], v[192:195], v[224:227], v[66:69]
	v_mfma_i32_16x16x64_i8 v[122:125], v[188:191], v[204:207], v[122:125]
	v_mfma_i32_16x16x64_i8 v[114:117], v[196:199], v[204:207], v[114:117]
	v_mfma_i32_16x16x64_i8 v[106:109], v[188:191], v[212:215], v[106:109]
	v_mfma_i32_16x16x64_i8 v[98:101], v[196:199], v[212:215], v[98:101]
	v_mfma_i32_16x16x64_i8 v[90:93], v[188:191], v[220:223], v[90:93]
	v_mfma_i32_16x16x64_i8 v[82:85], v[196:199], v[220:223], v[82:85]
	v_mfma_i32_16x16x64_i8 v[74:77], v[188:191], v[228:231], v[74:77]
	v_mfma_i32_16x16x64_i8 v[66:69], v[196:199], v[228:231], v[66:69]
	s_barrier
	s_add_i32 s34, s69, s15
	v_lshl_add_u64 v[150:151], v[150:151], 0, s[10:11]
	s_mov_b32 m0, s34
	ds_read_b128 v[200:203], v168 offset:49152
	ds_read_b128 v[204:207], v168 offset:50176
	ds_read_b128 v[208:211], v168 offset:51200
	ds_read_b128 v[212:215], v168 offset:52224
	ds_read_b128 v[216:219], v168 offset:53248
	ds_read_b128 v[220:223], v168 offset:54272
	ds_read_b128 v[224:227], v168 offset:55296
	ds_read_b128 v[228:231], v168 offset:56320
	global_load_lds_dwordx4 v[150:151], off
	s_add_i32 m0, s34, 0x2000
	s_add_u32 s30, s30, 0x80080
	v_lshl_add_u64 v[150:151], v[160:161], 0, s[10:11]
	s_addc_u32 s31, s31, 0
	s_add_i32 s34, s70, s15
	global_load_lds_dwordx4 v[150:151], off
	v_lshl_add_u64 v[150:151], s[30:31], 0, v[132:133]
	s_mov_b32 m0, s34
	s_nop 0
	global_load_lds_dwordx4 v[150:151], off
	v_lshl_add_u64 v[150:151], s[30:31], 0, v[136:137]
	s_add_i32 m0, s34, 0x2000
	s_nop 0
	global_load_lds_dwordx4 v[150:151], off
	v_lshl_add_u64 v[150:151], v[232:233], 0, s[10:11]
	s_mov_b32 m0, s52
	s_nop 0
	global_load_lds_dwordx4 v[150:151], off
	v_lshl_add_u64 v[150:151], v[234:235], 0, s[10:11]
	s_mov_b32 m0, s53
	s_nop 0
	global_load_lds_dwordx4 v[150:151], off
	s_waitcnt vmcnt(8)
	s_waitcnt lgkmcnt(0)
	s_barrier
	s_waitcnt lgkmcnt(0)
	v_mfma_i32_16x16x64_i8 v[62:65], v[146:149], v[200:203], v[62:65]
	v_mfma_i32_16x16x64_i8 v[54:57], v[174:177], v[200:203], v[54:57]
	v_mfma_i32_16x16x64_i8 v[46:49], v[146:149], v[208:211], v[46:49]
	v_mfma_i32_16x16x64_i8 v[38:41], v[174:177], v[208:211], v[38:41]
	v_mfma_i32_16x16x64_i8 v[30:33], v[146:149], v[216:219], v[30:33]
	v_mfma_i32_16x16x64_i8 v[22:25], v[174:177], v[216:219], v[22:25]
	v_mfma_i32_16x16x64_i8 v[14:17], v[146:149], v[224:227], v[14:17]
	v_mfma_i32_16x16x64_i8 v[6:9], v[174:177], v[224:227], v[6:9]
	v_mfma_i32_16x16x64_i8 v[62:65], v[170:173], v[204:207], v[62:65]
	v_mfma_i32_16x16x64_i8 v[54:57], v[180:183], v[204:207], v[54:57]
	v_mfma_i32_16x16x64_i8 v[46:49], v[170:173], v[212:215], v[46:49]
	v_mfma_i32_16x16x64_i8 v[38:41], v[180:183], v[212:215], v[38:41]
	v_mfma_i32_16x16x64_i8 v[30:33], v[170:173], v[220:223], v[30:33]
	v_mfma_i32_16x16x64_i8 v[22:25], v[180:183], v[220:223], v[22:25]
	v_mfma_i32_16x16x64_i8 v[14:17], v[170:173], v[228:231], v[14:17]
	v_mfma_i32_16x16x64_i8 v[6:9], v[180:183], v[228:231], v[6:9]
	v_mfma_i32_16x16x64_i8 v[58:61], v[184:187], v[200:203], v[58:61]
	v_mfma_i32_16x16x64_i8 v[50:53], v[192:195], v[200:203], v[50:53]
	v_mfma_i32_16x16x64_i8 v[42:45], v[184:187], v[208:211], v[42:45]
	v_mfma_i32_16x16x64_i8 v[34:37], v[192:195], v[208:211], v[34:37]
	v_mfma_i32_16x16x64_i8 v[26:29], v[184:187], v[216:219], v[26:29]
	v_mfma_i32_16x16x64_i8 v[18:21], v[192:195], v[216:219], v[18:21]
	v_mfma_i32_16x16x64_i8 v[10:13], v[184:187], v[224:227], v[10:13]
	v_mfma_i32_16x16x64_i8 v[2:5], v[192:195], v[224:227], v[2:5]
	v_mfma_i32_16x16x64_i8 v[58:61], v[188:191], v[204:207], v[58:61]
	v_mfma_i32_16x16x64_i8 v[50:53], v[196:199], v[204:207], v[50:53]
	v_mfma_i32_16x16x64_i8 v[42:45], v[188:191], v[212:215], v[42:45]
	v_mfma_i32_16x16x64_i8 v[34:37], v[196:199], v[212:215], v[34:37]
	v_mfma_i32_16x16x64_i8 v[26:29], v[188:191], v[220:223], v[26:29]
	v_mfma_i32_16x16x64_i8 v[18:21], v[196:199], v[220:223], v[18:21]
	v_mfma_i32_16x16x64_i8 v[10:13], v[188:191], v[228:231], v[10:13]
	v_mfma_i32_16x16x64_i8 v[2:5], v[196:199], v[228:231], v[2:5]
	s_barrier
	s_add_i32 s68, s68, 2
	s_add_u32 s28, s28, 0x100
	s_addc_u32 s29, s29, 0
	s_add_u32 s66, s66, 0x100
	s_addc_u32 s67, s67, 0
	s_cmp_gt_u32 s68, 29
	s_cbranch_scc0 .LBB0_1657
	s_and_b64 vcc, exec, s[12:13]
	s_cbranch_vccz .LBB0_1660
	s_barrier

.LBB0_1677:
	s_or_b64 exec, exec, s[2:3]
	s_add_i32 s2, s97, 0xffffff94
	s_cmpk_gt_u32 s97, 0xbf
	s_cselect_b32 s2, s2, -1
	s_cmpk_lt_i32 s97, 0x54
	s_cselect_b32 s8, s97, s2
	s_and_b64 s[2:3], s[6:7], exec
	s_cselect_b32 s19, s8, s97
	s_cmpk_gt_u32 s19, 0x7f
	v_readfirstlane_b32 s2, v0
	s_barrier
	s_cbranch_scc1 .LBB0_1701
	s_add_u32 s37, s76, 0x12200000
	s_addc_u32 s46, s77, 0
	s_lshr_b32 s9, s19, 6
	s_lshr_b32 s3, s2, 6
	s_or_b32 s38, s9, 32
	s_lshr_b32 s14, s2, 8
	s_lshl_b32 s47, s3, 10
	s_and_b32 s8, s19, 3
	s_bfe_u32 s33, s19, 0x40002
	s_mul_i32 s10, s38, 0x2b0000
	s_add_u32 s12, s4, s10
	s_addc_u32 s13, s5, 0
	s_mul_i32 s10, s33, 0x2b0000
	s_add_u32 s10, s37, s10
	s_mul_i32 s9, s8, 0xb00
	s_addc_u32 s11, s46, 0
	s_add_u32 s42, s10, s9
	v_mul_u32_u24_e32 v11, 0x2b00, v164
	s_addc_u32 s43, s11, 0
	s_add_i32 s48, s47, 0
	v_or_b32_e32 v164, v11, v163
	s_add_i32 m0, s48, 0x10000
	v_mul_u32_u24_e32 v10, 0x2b00, v162
	global_load_lds_dwordx4 v164, s[42:43]
	s_add_i32 m0, s48, 0x12000
	v_or_b32_e32 v162, v10, v163
	s_add_u32 s10, s42, 0x158000
	global_load_lds_dwordx4 v162, s[42:43]
	s_addc_u32 s11, s43, 0
	s_add_i32 m0, s48, 0x14000
	v_mov_b32_e32 v165, 0
	global_load_lds_dwordx4 v164, s[10:11]
	s_add_i32 m0, s48, 0x16000
	s_add_u32 s40, s12, s9
	s_addc_u32 s41, s13, 0
	s_add_i32 s49, s48, 0x2000
	global_load_lds_dwordx4 v162, s[10:11]
	s_mov_b32 m0, s48
	s_add_u32 s10, s40, 0x158000
	global_load_lds_dwordx4 v164, s[40:41]
	s_mov_b32 m0, s49
	s_addc_u32 s11, s41, 0
	s_add_i32 s50, s48, 0x4000
	global_load_lds_dwordx4 v162, s[40:41]
	s_mov_b32 m0, s50
	s_add_i32 s51, s48, 0x6000
	global_load_lds_dwordx4 v164, s[10:11]
	s_mov_b32 m0, s51
	v_mov_b32_e32 v163, v165
	global_load_lds_dwordx4 v162, s[10:11]
	s_cmp_eq_u32 s14, 1
	s_mov_b32 s9, 0
	v_lshl_add_u64 v[8:9], s[42:43], 0, v[164:165]
	v_lshl_add_u64 v[6:7], s[42:43], 0, v[162:163]
	v_lshl_add_u64 v[2:3], s[40:41], 0, v[164:165]
	s_cselect_b64 s[10:11], -1, 0
	s_cmp_lg_u32 s14, 1
	v_lshl_add_u64 v[4:5], s[40:41], 0, v[162:163]
	s_cbranch_scc1 .LBB0_1680
	s_setprio 1
	s_barrier

.LBB0_1690:
	ds_read_b128 v[26:29], v181
	ds_read_b128 v[30:33], v181 offset:1024
	ds_read_b128 v[18:21], v181 offset:2048
	ds_read_b128 v[22:25], v181 offset:3072
	ds_read_b128 v[10:13], v182
	ds_read_b128 v[14:17], v182 offset:1024
	ds_read_b128 v[2:5], v182 offset:2048
	ds_read_b128 v[6:9], v182 offset:3072
	s_add_i32 s70, s42, 2
	s_add_u32 s43, s40, 0xffea8080
	s_addc_u32 s44, s41, -1
	s_cmp_eq_u32 s29, s42
	s_cselect_b32 s42, s34, s68
	s_cselect_b32 s45, s31, s44
	s_cselect_b32 s44, s30, s43
	s_cselect_b32 s43, s35, s69
	v_lshl_add_u64 v[208:209], s[40:41], 0, v[166:167]
	s_add_i32 m0, s48, 0xc000
	ds_read_b128 v[170:173], v183
	ds_read_b128 v[174:177], v183 offset:1024
	ds_read_b128 v[184:187], v183 offset:2048
	ds_read_b128 v[188:191], v183 offset:3072
	ds_read_b128 v[192:195], v183 offset:4096
	ds_read_b128 v[196:199], v183 offset:5120
	ds_read_b128 v[200:203], v183 offset:6144
	ds_read_b128 v[204:207], v183 offset:7168
	global_load_lds_dwordx4 v[208:209], off
	v_lshl_add_u64 v[208:209], s[40:41], 0, v[168:169]
	s_add_i32 m0, s48, 0xe000
	s_nop 0
	global_load_lds_dwordx4 v[208:209], off
	s_waitcnt vmcnt(8)
	s_waitcnt lgkmcnt(0)
	s_barrier
	s_waitcnt lgkmcnt(0)
	v_mfma_f32_16x16x128_f8f6f4 v[158:161], v[26:33], v[170:177], v[158:161]
	v_mfma_f32_16x16x128_f8f6f4 v[154:157], v[18:25], v[170:177], v[154:157]
	v_mfma_f32_16x16x128_f8f6f4 v[150:153], v[26:33], v[184:191], v[150:153]
	v_mfma_f32_16x16x128_f8f6f4 v[138:141], v[18:25], v[184:191], v[138:141]
	v_mfma_f32_16x16x128_f8f6f4 v[130:133], v[26:33], v[192:199], v[130:133]
	v_mfma_f32_16x16x128_f8f6f4 v[122:125], v[18:25], v[192:199], v[122:125]
	v_mfma_f32_16x16x128_f8f6f4 v[114:117], v[26:33], v[200:207], v[114:117]
	v_mfma_f32_16x16x128_f8f6f4 v[106:109], v[18:25], v[200:207], v[106:109]
	v_mfma_f32_16x16x128_f8f6f4 v[146:149], v[10:17], v[170:177], v[146:149]
	v_mfma_f32_16x16x128_f8f6f4 v[142:145], v[2:9], v[170:177], v[142:145]
	v_mfma_f32_16x16x128_f8f6f4 v[134:137], v[10:17], v[184:191], v[134:137]
	v_mfma_f32_16x16x128_f8f6f4 v[126:129], v[2:9], v[184:191], v[126:129]
	v_mfma_f32_16x16x128_f8f6f4 v[118:121], v[10:17], v[192:199], v[118:121]
	v_mfma_f32_16x16x128_f8f6f4 v[110:113], v[2:9], v[192:199], v[110:113]
	v_mfma_f32_16x16x128_f8f6f4 v[102:105], v[10:17], v[200:207], v[102:105]
	v_mfma_f32_16x16x128_f8f6f4 v[98:101], v[2:9], v[200:207], v[98:101]
	s_barrier
	s_add_i32 s71, s60, s47
	v_lshl_add_u64 v[170:171], s[42:43], 0, v[164:165]
	s_mov_b32 m0, s71
	ds_read_b128 v[184:187], v183 offset:16384
	ds_read_b128 v[188:191], v183 offset:17408
	ds_read_b128 v[192:195], v183 offset:18432
	ds_read_b128 v[196:199], v183 offset:19456
	ds_read_b128 v[200:203], v183 offset:20480
	ds_read_b128 v[204:207], v183 offset:21504
	ds_read_b128 v[208:211], v183 offset:22528
	ds_read_b128 v[212:215], v183 offset:23552
	global_load_lds_dwordx4 v[170:171], off
	s_add_i32 m0, s71, 0x2000
	s_add_u32 s72, s42, 0x158000
	v_lshl_add_u64 v[172:173], s[42:43], 0, v[162:163]
	s_addc_u32 s73, s43, 0
	s_add_i32 s71, s61, s47
	global_load_lds_dwordx4 v[172:173], off
	v_lshl_add_u64 v[174:175], s[72:73], 0, v[164:165]
	s_mov_b32 m0, s71
	v_lshl_add_u64 v[176:177], s[44:45], 0, v[162:163]
	global_load_lds_dwordx4 v[174:175], off
	v_lshl_add_u64 v[174:175], s[72:73], 0, v[162:163]
	s_add_i32 m0, s71, 0x2000
	s_nop 0
	global_load_lds_dwordx4 v[174:175], off
	v_lshl_add_u64 v[174:175], s[44:45], 0, v[164:165]
	s_mov_b32 m0, s48
	s_nop 0
	global_load_lds_dwordx4 v[174:175], off
	s_mov_b32 m0, s49
	s_nop 0
	global_load_lds_dwordx4 v[176:177], off
	s_waitcnt vmcnt(8)
	s_waitcnt lgkmcnt(0)
	s_barrier
	s_waitcnt lgkmcnt(0)
	v_mfma_f32_16x16x128_f8f6f4 v[94:97], v[26:33], v[184:191], v[94:97]
	v_mfma_f32_16x16x128_f8f6f4 v[90:93], v[18:25], v[184:191], v[90:93]
	v_mfma_f32_16x16x128_f8f6f4 v[82:85], v[26:33], v[192:199], v[82:85]
	v_mfma_f32_16x16x128_f8f6f4 v[74:77], v[18:25], v[192:199], v[74:77]
	v_mfma_f32_16x16x128_f8f6f4 v[66:69], v[26:33], v[200:207], v[66:69]
	v_mfma_f32_16x16x128_f8f6f4 v[58:61], v[18:25], v[200:207], v[58:61]
	v_mfma_f32_16x16x128_f8f6f4 v[50:53], v[26:33], v[208:215], v[50:53]
	v_mfma_f32_16x16x128_f8f6f4 v[42:45], v[18:25], v[208:215], v[42:45]
	v_mfma_f32_16x16x128_f8f6f4 v[86:89], v[10:17], v[184:191], v[86:89]
	v_mfma_f32_16x16x128_f8f6f4 v[78:81], v[2:9], v[184:191], v[78:81]
	v_mfma_f32_16x16x128_f8f6f4 v[70:73], v[10:17], v[192:199], v[70:73]
	v_mfma_f32_16x16x128_f8f6f4 v[62:65], v[2:9], v[192:199], v[62:65]
	v_mfma_f32_16x16x128_f8f6f4 v[54:57], v[10:17], v[200:207], v[54:57]
	v_mfma_f32_16x16x128_f8f6f4 v[46:49], v[2:9], v[200:207], v[46:49]
	v_mfma_f32_16x16x128_f8f6f4 v[38:41], v[10:17], v[208:215], v[38:41]
	v_mfma_f32_16x16x128_f8f6f4 v[34:37], v[2:9], v[208:215], v[34:37]
	s_barrier
	s_add_i32 s71, 0, 0x18000
	s_add_i32 s72, 0, 0x1c000
	v_add_u32_e32 v14, s71, v180
	v_add_u32_e32 v30, s72, v180
	ds_read_b128 v[2:5], v14
	ds_read_b128 v[6:9], v14 offset:1024
	ds_read_b128 v[10:13], v14 offset:2048
	ds_read_b128 v[14:17], v14 offset:3072
	ds_read_b128 v[18:21], v30
	ds_read_b128 v[22:25], v30 offset:1024
	ds_read_b128 v[26:29], v30 offset:2048
	ds_read_b128 v[30:33], v30 offset:3072
	s_add_u32 s44, s44, 0x158000
	s_addc_u32 s45, s45, 0
	s_mov_b32 m0, s50
	v_lshl_add_u64 v[216:217], s[44:45], 0, v[164:165]
	ds_read_b128 v[184:187], v183 offset:32768
	ds_read_b128 v[188:191], v183 offset:33792
	ds_read_b128 v[192:195], v183 offset:34816
	ds_read_b128 v[196:199], v183 offset:35840
	ds_read_b128 v[200:203], v183 offset:36864
	ds_read_b128 v[204:207], v183 offset:37888
	ds_read_b128 v[208:211], v183 offset:38912
	ds_read_b128 v[212:215], v183 offset:39936
	global_load_lds_dwordx4 v[216:217], off
	v_lshl_add_u64 v[216:217], s[44:45], 0, v[162:163]
	s_mov_b32 m0, s51
	s_nop 0
	global_load_lds_dwordx4 v[216:217], off
	s_waitcnt vmcnt(8)
	s_waitcnt lgkmcnt(0)
	s_barrier
	s_waitcnt lgkmcnt(0)
	v_mfma_f32_16x16x128_f8f6f4 v[158:161], v[2:9], v[184:191], v[158:161]
	v_mfma_f32_16x16x128_f8f6f4 v[154:157], v[10:17], v[184:191], v[154:157]
	v_mfma_f32_16x16x128_f8f6f4 v[150:153], v[2:9], v[192:199], v[150:153]
	v_mfma_f32_16x16x128_f8f6f4 v[138:141], v[10:17], v[192:199], v[138:141]
	v_mfma_f32_16x16x128_f8f6f4 v[130:133], v[2:9], v[200:207], v[130:133]
	v_mfma_f32_16x16x128_f8f6f4 v[122:125], v[10:17], v[200:207], v[122:125]
	v_mfma_f32_16x16x128_f8f6f4 v[114:117], v[2:9], v[208:215], v[114:117]
	v_mfma_f32_16x16x128_f8f6f4 v[106:109], v[10:17], v[208:215], v[106:109]
	v_mfma_f32_16x16x128_f8f6f4 v[146:149], v[18:25], v[184:191], v[146:149]
	v_mfma_f32_16x16x128_f8f6f4 v[142:145], v[26:33], v[184:191], v[142:145]
	v_mfma_f32_16x16x128_f8f6f4 v[134:137], v[18:25], v[192:199], v[134:137]
	v_mfma_f32_16x16x128_f8f6f4 v[126:129], v[26:33], v[192:199], v[126:129]
	v_mfma_f32_16x16x128_f8f6f4 v[118:121], v[18:25], v[200:207], v[118:121]
	v_mfma_f32_16x16x128_f8f6f4 v[110:113], v[26:33], v[200:207], v[110:113]
	v_mfma_f32_16x16x128_f8f6f4 v[102:105], v[18:25], v[208:215], v[102:105]
	v_mfma_f32_16x16x128_f8f6f4 v[98:101], v[26:33], v[208:215], v[98:101]
	s_barrier
	s_add_i32 s44, s71, s47
	v_lshl_add_u64 v[170:171], v[170:171], 0, s[14:15]
	s_mov_b32 m0, s44
	ds_read_b128 v[184:187], v183 offset:49152
	ds_read_b128 v[188:191], v183 offset:50176
	ds_read_b128 v[192:195], v183 offset:51200
	ds_read_b128 v[196:199], v183 offset:52224
	ds_read_b128 v[200:203], v183 offset:53248
	ds_read_b128 v[204:207], v183 offset:54272
	ds_read_b128 v[208:211], v183 offset:55296
	ds_read_b128 v[212:215], v183 offset:56320
	global_load_lds_dwordx4 v[170:171], off
	s_add_i32 m0, s44, 0x2000
	s_add_u32 s42, s42, 0x158080
	v_lshl_add_u64 v[170:171], v[172:173], 0, s[14:15]
	s_addc_u32 s43, s43, 0
	s_add_i32 s44, s72, s47
	global_load_lds_dwordx4 v[170:171], off
	v_lshl_add_u64 v[170:171], s[42:43], 0, v[164:165]
	s_mov_b32 m0, s44
	s_nop 0
	global_load_lds_dwordx4 v[170:171], off
	v_lshl_add_u64 v[170:171], s[42:43], 0, v[162:163]
	s_add_i32 m0, s44, 0x2000
	s_nop 0
	global_load_lds_dwordx4 v[170:171], off
	v_lshl_add_u64 v[170:171], v[174:175], 0, s[14:15]
	s_mov_b32 m0, s57
	s_nop 0
	global_load_lds_dwordx4 v[170:171], off
	v_lshl_add_u64 v[170:171], v[176:177], 0, s[14:15]
	s_mov_b32 m0, s58
	s_nop 0
	global_load_lds_dwordx4 v[170:171], off
	s_waitcnt vmcnt(8)
	s_waitcnt lgkmcnt(0)
	s_barrier
	s_waitcnt lgkmcnt(0)
	v_mfma_f32_16x16x128_f8f6f4 v[94:97], v[2:9], v[184:191], v[94:97]
	v_mfma_f32_16x16x128_f8f6f4 v[90:93], v[10:17], v[184:191], v[90:93]
	v_mfma_f32_16x16x128_f8f6f4 v[82:85], v[2:9], v[192:199], v[82:85]
	v_mfma_f32_16x16x128_f8f6f4 v[74:77], v[10:17], v[192:199], v[74:77]
	v_mfma_f32_16x16x128_f8f6f4 v[66:69], v[2:9], v[200:207], v[66:69]
	v_mfma_f32_16x16x128_f8f6f4 v[58:61], v[10:17], v[200:207], v[58:61]
	v_mfma_f32_16x16x128_f8f6f4 v[50:53], v[2:9], v[208:215], v[50:53]
	v_mfma_f32_16x16x128_f8f6f4 v[42:45], v[10:17], v[208:215], v[42:45]
	v_mfma_f32_16x16x128_f8f6f4 v[86:89], v[18:25], v[184:191], v[86:89]
	v_mfma_f32_16x16x128_f8f6f4 v[78:81], v[26:33], v[184:191], v[78:81]
	v_mfma_f32_16x16x128_f8f6f4 v[70:73], v[18:25], v[192:199], v[70:73]
	v_mfma_f32_16x16x128_f8f6f4 v[62:65], v[26:33], v[192:199], v[62:65]
	v_mfma_f32_16x16x128_f8f6f4 v[54:57], v[18:25], v[200:207], v[54:57]
	v_mfma_f32_16x16x128_f8f6f4 v[46:49], v[26:33], v[200:207], v[46:49]
	v_mfma_f32_16x16x128_f8f6f4 v[38:41], v[18:25], v[208:215], v[38:41]
	v_mfma_f32_16x16x128_f8f6f4 v[34:37], v[26:33], v[208:215], v[34:37]
	s_barrier
	s_add_u32 s40, s40, 0x100
	s_addc_u32 s41, s41, 0
	s_add_u32 s68, s68, 0x100
	s_addc_u32 s69, s69, 0
	s_cmp_ge_i32 s70, s39
	s_mov_b32 s42, s70
	s_cbranch_scc0 .LBB0_1690
	s_and_b64 vcc, exec, s[16:17]
	s_cbranch_vccz .LBB0_1693
	s_barrier

.LBB0_1764:
	s_add_u32 s34, s76, 0x39400000
	s_addc_u32 s35, s77, 0
	s_add_u32 s36, s76, 0x12200000
	s_addc_u32 s37, s77, 0
	s_add_i32 s0, s4, s0
	s_ashr_i32 s4, s0, 31
	s_lshr_b32 s4, s4, 25
	s_add_i32 s4, s0, s4
	s_ashr_i32 s5, s4, 7
	s_and_b32 s4, s4, 0xff80
	s_sub_i32 s4, s0, s4
	s_bfe_i32 s0, s4, 0x80000
	s_bfe_u32 s0, s0, 0x3000c
	s_add_i32 s6, s4, s0
	s_bfe_i32 s0, s6, 0x80000
	s_and_b32 s6, s6, 0xf8
	v_bfe_u32 v3, v0, 2, 4
	v_lshrrev_b32_e32 v4, 3, v0
	s_sub_i32 s4, s4, s6
	v_and_or_b32 v5, v4, 48, v3
	v_or_b32_e32 v4, 64, v4
	s_movk_i32 s3, 0x70
	s_lshl_b32 s5, s5, 3
	s_sext_i32_i16 s7, s0
	s_sext_i32_i8 s4, s4
	v_and_or_b32 v3, v4, s3, v3
	s_lshr_b32 s3, s2, 6
	s_add_i32 s24, s5, s4
	s_ashr_i32 s4, s7, 3
	s_lshr_b32 s1, s2, 8
	v_lshlrev_b32_e32 v1, 4, v0
	v_and_b32_e32 v2, 32, v0
	s_lshl_b32 s38, s3, 10
	s_lshr_b32 s0, s7, 3
	s_mul_hi_i32 s5, s4, 0x2b0000
	s_mul_i32 s4, s4, 0x2b0000
	v_bitop3_b32 v1, v1, v2, 48 bitop3:0x6c
	v_and_b32_e32 v10, 64, v0
	s_add_u32 s28, s36, s4
	v_or_b32_e32 v2, v1, v10
	v_mul_u32_u24_e32 v11, 0x2b00, v5
	s_addc_u32 s29, s37, s5
	s_add_i32 s39, s38, 0
	v_or_b32_e32 v160, v11, v2
	s_add_i32 m0, s39, 0x10000
	v_mul_u32_u24_e32 v12, 0x2b00, v3
	global_load_lds_dwordx4 v160, s[28:29]
	s_add_i32 m0, s39, 0x12000
	v_or_b32_e32 v162, v12, v2
	s_add_u32 s4, s28, 0x158000
	global_load_lds_dwordx4 v162, s[28:29]
	s_addc_u32 s5, s29, 0
	s_add_i32 m0, s39, 0x14000
	s_mul_i32 s8, s24, 0x2b0000
	global_load_lds_dwordx4 v160, s[4:5]
	s_add_i32 m0, s39, 0x16000
	s_mul_hi_i32 s6, s24, 0x2b0000
	s_add_u32 s26, s34, s8
	s_addc_u32 s27, s35, s6
	s_add_i32 s40, s39, 0x2000
	global_load_lds_dwordx4 v162, s[4:5]
	s_mov_b32 m0, s39
	s_add_u32 s4, s26, 0x158000
	global_load_lds_dwordx4 v160, s[26:27]
	s_mov_b32 m0, s40
	s_addc_u32 s5, s27, 0
	s_add_i32 s41, s39, 0x4000
	global_load_lds_dwordx4 v162, s[26:27]
	s_mov_b32 m0, s41
	s_add_i32 s42, s39, 0x6000
	global_load_lds_dwordx4 v160, s[4:5]
	s_mov_b32 m0, s42
	v_mov_b32_e32 v161, 0
	global_load_lds_dwordx4 v162, s[4:5]
	v_mov_b32_e32 v163, v161
	s_cmp_eq_u32 s1, 1
	s_mov_b32 s43, 0
	v_lshl_add_u64 v[8:9], s[28:29], 0, v[160:161]
	v_lshl_add_u64 v[6:7], s[28:29], 0, v[162:163]
	v_lshl_add_u64 v[2:3], s[26:27], 0, v[160:161]
	s_cselect_b64 s[4:5], -1, 0
	s_cmp_lg_u32 s1, 1
	v_lshl_add_u64 v[4:5], s[26:27], 0, v[162:163]
	s_cbranch_scc1 .LBB0_1766
	s_setprio 1
	s_barrier

.LBB0_1780:
	ds_read_b128 v[24:27], v183
	ds_read_b128 v[28:31], v183 offset:1024
	ds_read_b128 v[16:19], v183 offset:2048
	ds_read_b128 v[20:23], v183 offset:3072
	ds_read_b128 v[8:11], v184
	ds_read_b128 v[12:15], v184 offset:1024
	ds_read_b128 v[0:3], v184 offset:2048
	ds_read_b128 v[4:7], v184 offset:3072
	s_add_u32 s28, s26, 0xffea8080
	s_addc_u32 s29, s27, -1
	s_cmpk_eq_i32 s56, 0x52
	s_cselect_b32 s31, s3, s29
	s_cselect_b32 s30, s2, s28
	s_cselect_b32 s29, s23, s55
	s_cselect_b32 s28, s22, s33
	v_lshl_add_u64 v[210:211], s[26:27], 0, v[164:165]
	s_add_i32 m0, s39, 0xc000
	ds_read_b128 v[172:175], v185
	ds_read_b128 v[176:179], v185 offset:1024
	ds_read_b128 v[186:189], v185 offset:2048
	ds_read_b128 v[190:193], v185 offset:3072
	ds_read_b128 v[194:197], v185 offset:4096
	ds_read_b128 v[198:201], v185 offset:5120
	ds_read_b128 v[202:205], v185 offset:6144
	ds_read_b128 v[206:209], v185 offset:7168
	global_load_lds_dwordx4 v[210:211], off
	v_lshl_add_u64 v[210:211], s[26:27], 0, v[166:167]
	s_add_i32 m0, s39, 0xe000
	s_nop 0
	global_load_lds_dwordx4 v[210:211], off
	s_waitcnt vmcnt(8)
	s_waitcnt lgkmcnt(0)
	s_barrier
	s_waitcnt lgkmcnt(0)
	v_mfma_f32_16x16x128_f8f6f4 v[156:159], v[24:31], v[172:179], v[156:159]
	v_mfma_f32_16x16x128_f8f6f4 v[152:155], v[16:23], v[172:179], v[152:155]
	v_mfma_f32_16x16x128_f8f6f4 v[148:151], v[24:31], v[186:193], v[148:151]
	v_mfma_f32_16x16x128_f8f6f4 v[136:139], v[16:23], v[186:193], v[136:139]
	v_mfma_f32_16x16x128_f8f6f4 v[128:131], v[24:31], v[194:201], v[128:131]
	v_mfma_f32_16x16x128_f8f6f4 v[120:123], v[16:23], v[194:201], v[120:123]
	v_mfma_f32_16x16x128_f8f6f4 v[112:115], v[24:31], v[202:209], v[112:115]
	v_mfma_f32_16x16x128_f8f6f4 v[104:107], v[16:23], v[202:209], v[104:107]
	v_mfma_f32_16x16x128_f8f6f4 v[144:147], v[8:15], v[172:179], v[144:147]
	v_mfma_f32_16x16x128_f8f6f4 v[140:143], v[0:7], v[172:179], v[140:143]
	v_mfma_f32_16x16x128_f8f6f4 v[132:135], v[8:15], v[186:193], v[132:135]
	v_mfma_f32_16x16x128_f8f6f4 v[124:127], v[0:7], v[186:193], v[124:127]
	v_mfma_f32_16x16x128_f8f6f4 v[116:119], v[8:15], v[194:201], v[116:119]
	v_mfma_f32_16x16x128_f8f6f4 v[108:111], v[0:7], v[194:201], v[108:111]
	v_mfma_f32_16x16x128_f8f6f4 v[100:103], v[8:15], v[202:209], v[100:103]
	v_mfma_f32_16x16x128_f8f6f4 v[96:99], v[0:7], v[202:209], v[96:99]
	s_barrier
	s_add_i32 s57, s51, s38
	v_lshl_add_u64 v[172:173], s[28:29], 0, v[160:161]
	s_mov_b32 m0, s57
	ds_read_b128 v[186:189], v185 offset:16384
	ds_read_b128 v[190:193], v185 offset:17408
	ds_read_b128 v[194:197], v185 offset:18432
	ds_read_b128 v[198:201], v185 offset:19456
	ds_read_b128 v[202:205], v185 offset:20480
	ds_read_b128 v[206:209], v185 offset:21504
	ds_read_b128 v[210:213], v185 offset:22528
	ds_read_b128 v[214:217], v185 offset:23552
	global_load_lds_dwordx4 v[172:173], off
	s_add_i32 m0, s57, 0x2000
	s_add_u32 s58, s28, 0x158000
	v_lshl_add_u64 v[174:175], s[28:29], 0, v[162:163]
	s_addc_u32 s59, s29, 0
	s_add_i32 s57, s52, s38
	global_load_lds_dwordx4 v[174:175], off
	v_lshl_add_u64 v[176:177], s[58:59], 0, v[160:161]
	s_mov_b32 m0, s57
	v_lshl_add_u64 v[178:179], s[30:31], 0, v[162:163]
	global_load_lds_dwordx4 v[176:177], off
	v_lshl_add_u64 v[176:177], s[58:59], 0, v[162:163]
	s_add_i32 m0, s57, 0x2000
	s_nop 0
	global_load_lds_dwordx4 v[176:177], off
	v_lshl_add_u64 v[176:177], s[30:31], 0, v[160:161]
	s_mov_b32 m0, s39
	s_nop 0
	global_load_lds_dwordx4 v[176:177], off
	s_mov_b32 m0, s40
	s_nop 0
	global_load_lds_dwordx4 v[178:179], off
	s_waitcnt vmcnt(8)
	s_waitcnt lgkmcnt(0)
	s_barrier
	s_waitcnt lgkmcnt(0)
	v_mfma_f32_16x16x128_f8f6f4 v[92:95], v[24:31], v[186:193], v[92:95]
	v_mfma_f32_16x16x128_f8f6f4 v[88:91], v[16:23], v[186:193], v[88:91]
	v_mfma_f32_16x16x128_f8f6f4 v[80:83], v[24:31], v[194:201], v[80:83]
	v_mfma_f32_16x16x128_f8f6f4 v[72:75], v[16:23], v[194:201], v[72:75]
	v_mfma_f32_16x16x128_f8f6f4 v[64:67], v[24:31], v[202:209], v[64:67]
	v_mfma_f32_16x16x128_f8f6f4 v[56:59], v[16:23], v[202:209], v[56:59]
	v_mfma_f32_16x16x128_f8f6f4 v[48:51], v[24:31], v[210:217], v[48:51]
	v_mfma_f32_16x16x128_f8f6f4 v[40:43], v[16:23], v[210:217], v[40:43]
	v_mfma_f32_16x16x128_f8f6f4 v[84:87], v[8:15], v[186:193], v[84:87]
	v_mfma_f32_16x16x128_f8f6f4 v[76:79], v[0:7], v[186:193], v[76:79]
	v_mfma_f32_16x16x128_f8f6f4 v[68:71], v[8:15], v[194:201], v[68:71]
	v_mfma_f32_16x16x128_f8f6f4 v[60:63], v[0:7], v[194:201], v[60:63]
	v_mfma_f32_16x16x128_f8f6f4 v[52:55], v[8:15], v[202:209], v[52:55]
	v_mfma_f32_16x16x128_f8f6f4 v[44:47], v[0:7], v[202:209], v[44:47]
	v_mfma_f32_16x16x128_f8f6f4 v[36:39], v[8:15], v[210:217], v[36:39]
	v_mfma_f32_16x16x128_f8f6f4 v[32:35], v[0:7], v[210:217], v[32:35]
	s_barrier
	s_add_i32 s57, 0, 0x18000
	s_add_i32 s58, 0, 0x1c000
	v_add_u32_e32 v12, s57, v182
	v_add_u32_e32 v28, s58, v182
	ds_read_b128 v[0:3], v12
	ds_read_b128 v[4:7], v12 offset:1024
	ds_read_b128 v[8:11], v12 offset:2048
	ds_read_b128 v[12:15], v12 offset:3072
	ds_read_b128 v[16:19], v28
	ds_read_b128 v[20:23], v28 offset:1024
	ds_read_b128 v[24:27], v28 offset:2048
	ds_read_b128 v[28:31], v28 offset:3072
	s_add_u32 s30, s30, 0x158000
	s_addc_u32 s31, s31, 0
	s_mov_b32 m0, s41
	v_lshl_add_u64 v[218:219], s[30:31], 0, v[160:161]
	ds_read_b128 v[186:189], v185 offset:32768
	ds_read_b128 v[190:193], v185 offset:33792
	ds_read_b128 v[194:197], v185 offset:34816
	ds_read_b128 v[198:201], v185 offset:35840
	ds_read_b128 v[202:205], v185 offset:36864
	ds_read_b128 v[206:209], v185 offset:37888
	ds_read_b128 v[210:213], v185 offset:38912
	ds_read_b128 v[214:217], v185 offset:39936
	global_load_lds_dwordx4 v[218:219], off
	v_lshl_add_u64 v[218:219], s[30:31], 0, v[162:163]
	s_mov_b32 m0, s42
	s_nop 0
	global_load_lds_dwordx4 v[218:219], off
	s_waitcnt vmcnt(8)
	s_waitcnt lgkmcnt(0)
	s_barrier
	s_waitcnt lgkmcnt(0)
	v_mfma_f32_16x16x128_f8f6f4 v[156:159], v[0:7], v[186:193], v[156:159]
	v_mfma_f32_16x16x128_f8f6f4 v[152:155], v[8:15], v[186:193], v[152:155]
	v_mfma_f32_16x16x128_f8f6f4 v[148:151], v[0:7], v[194:201], v[148:151]
	v_mfma_f32_16x16x128_f8f6f4 v[136:139], v[8:15], v[194:201], v[136:139]
	v_mfma_f32_16x16x128_f8f6f4 v[128:131], v[0:7], v[202:209], v[128:131]
	v_mfma_f32_16x16x128_f8f6f4 v[120:123], v[8:15], v[202:209], v[120:123]
	v_mfma_f32_16x16x128_f8f6f4 v[112:115], v[0:7], v[210:217], v[112:115]
	v_mfma_f32_16x16x128_f8f6f4 v[104:107], v[8:15], v[210:217], v[104:107]
	v_mfma_f32_16x16x128_f8f6f4 v[144:147], v[16:23], v[186:193], v[144:147]
	v_mfma_f32_16x16x128_f8f6f4 v[140:143], v[24:31], v[186:193], v[140:143]
	v_mfma_f32_16x16x128_f8f6f4 v[132:135], v[16:23], v[194:201], v[132:135]
	v_mfma_f32_16x16x128_f8f6f4 v[124:127], v[24:31], v[194:201], v[124:127]
	v_mfma_f32_16x16x128_f8f6f4 v[116:119], v[16:23], v[202:209], v[116:119]
	v_mfma_f32_16x16x128_f8f6f4 v[108:111], v[24:31], v[202:209], v[108:111]
	v_mfma_f32_16x16x128_f8f6f4 v[100:103], v[16:23], v[210:217], v[100:103]
	v_mfma_f32_16x16x128_f8f6f4 v[96:99], v[24:31], v[210:217], v[96:99]
	s_barrier
	s_add_i32 s30, s57, s38
	v_lshl_add_u64 v[172:173], v[172:173], 0, s[8:9]
	s_mov_b32 m0, s30
	ds_read_b128 v[186:189], v185 offset:49152
	ds_read_b128 v[190:193], v185 offset:50176
	ds_read_b128 v[194:197], v185 offset:51200
	ds_read_b128 v[198:201], v185 offset:52224
	ds_read_b128 v[202:205], v185 offset:53248
	ds_read_b128 v[206:209], v185 offset:54272
	ds_read_b128 v[210:213], v185 offset:55296
	ds_read_b128 v[214:217], v185 offset:56320
	global_load_lds_dwordx4 v[172:173], off
	s_add_i32 m0, s30, 0x2000
	s_add_u32 s28, s28, 0x158080
	v_lshl_add_u64 v[172:173], v[174:175], 0, s[8:9]
	s_addc_u32 s29, s29, 0
	s_add_i32 s30, s58, s38
	global_load_lds_dwordx4 v[172:173], off
	v_lshl_add_u64 v[172:173], s[28:29], 0, v[160:161]
	s_mov_b32 m0, s30
	s_nop 0
	global_load_lds_dwordx4 v[172:173], off
	v_lshl_add_u64 v[172:173], s[28:29], 0, v[162:163]
	s_add_i32 m0, s30, 0x2000
	s_nop 0
	global_load_lds_dwordx4 v[172:173], off
	v_lshl_add_u64 v[172:173], v[176:177], 0, s[8:9]
	s_mov_b32 m0, s48
	s_nop 0
	global_load_lds_dwordx4 v[172:173], off
	v_lshl_add_u64 v[172:173], v[178:179], 0, s[8:9]
	s_mov_b32 m0, s49
	s_nop 0
	global_load_lds_dwordx4 v[172:173], off
	s_waitcnt vmcnt(8)
	s_waitcnt lgkmcnt(0)
	s_barrier
	s_waitcnt lgkmcnt(0)
	v_mfma_f32_16x16x128_f8f6f4 v[92:95], v[0:7], v[186:193], v[92:95]
	v_mfma_f32_16x16x128_f8f6f4 v[88:91], v[8:15], v[186:193], v[88:91]
	v_mfma_f32_16x16x128_f8f6f4 v[80:83], v[0:7], v[194:201], v[80:83]
	v_mfma_f32_16x16x128_f8f6f4 v[72:75], v[8:15], v[194:201], v[72:75]
	v_mfma_f32_16x16x128_f8f6f4 v[64:67], v[0:7], v[202:209], v[64:67]
	v_mfma_f32_16x16x128_f8f6f4 v[56:59], v[8:15], v[202:209], v[56:59]
	v_mfma_f32_16x16x128_f8f6f4 v[48:51], v[0:7], v[210:217], v[48:51]
	v_mfma_f32_16x16x128_f8f6f4 v[40:43], v[8:15], v[210:217], v[40:43]
	v_mfma_f32_16x16x128_f8f6f4 v[84:87], v[16:23], v[186:193], v[84:87]
	v_mfma_f32_16x16x128_f8f6f4 v[76:79], v[24:31], v[186:193], v[76:79]
	v_mfma_f32_16x16x128_f8f6f4 v[68:71], v[16:23], v[194:201], v[68:71]
	v_mfma_f32_16x16x128_f8f6f4 v[60:63], v[24:31], v[194:201], v[60:63]
	v_mfma_f32_16x16x128_f8f6f4 v[52:55], v[16:23], v[202:209], v[52:55]
	v_mfma_f32_16x16x128_f8f6f4 v[44:47], v[24:31], v[202:209], v[44:47]
	v_mfma_f32_16x16x128_f8f6f4 v[36:39], v[16:23], v[210:217], v[36:39]
	v_mfma_f32_16x16x128_f8f6f4 v[32:35], v[24:31], v[210:217], v[32:35]
	s_barrier
	s_add_i32 s56, s56, 2
	s_add_u32 s26, s26, 0x100
	s_addc_u32 s27, s27, 0
	s_add_u32 s33, s33, 0x100
	s_addc_u32 s55, s55, 0
	s_cmpk_gt_u32 s56, 0x53
	s_cbranch_scc0 .LBB0_1780
	s_and_b64 vcc, exec, s[10:11]
	s_cbranch_vccz .LBB0_1783
	s_barrier
